# wave reductions via DPP/permlane-swap VALU ops instead of ds_bpermute in conv LayerNorm, gMLP LayerNorm and residual-epilogue ssq (256 sites) on top of v021
# speedup vs baseline: 1.0018x; 1.0018x over previous
; DI u32x4 pack8(f32x4 a, f32x4 b) { u32x4 w; w.x = pk2(a[0], a[1]); w.y = pk2(a[2], a[3]); w.z = pk2(b[0], b[1]); w.w = pk2(b[2], b[3]); return w; }
;     DI void operator()(const pg8::Acc& acc, const pg8::Unit& u, int wr, int wc, int fr, int fq) const {
;         const int row0 = u.pm * 256 + wr * 64 + fr, col0 = u.pn * 256 + wc * 32 + 8 * fq;
;         if (u.kind == 0) {
;             float* X = (float*)(ws + WS_X); float* SSP = (float*)(ws + WS_SSP) + (size_t)site * MT * 16;
; #pragma unroll
;             for (int ai = 0; ai < 2; ++ai) {
;                 bf16* XH = (bf16*)X;
;                 u32x4 xv[4][2];
; #pragma unroll
;                 for (int m = 0; m < 4; ++m)
; #pragma unroll
;                     for (int bj = 0; bj < 2; ++bj) xv[m][bj] = *(const u32x4*)(XH + (size_t)(row0 + ai * 128 + m * 16) * DM + col0 + bj * 128);
; #pragma unroll
;                 for (int m = 0; m < 4; ++m) { const int row = row0 + ai * 128 + m * 16; float ssq = 0.f;
; #pragma unroll
;                     for (int bj = 0; bj < 2; ++bj) { const u32x4 x = xv[m][bj];
;                         const f32x4 xa = (f32x4){bflo(x.x), bfhi(x.x), bflo(x.y), bfhi(x.y)} + acc[ai][bj][m][0] * scale, xb = (f32x4){bflo(x.z), bfhi(x.z), bflo(x.w), bfhi(x.w)} + acc[ai][bj][m][1] * scale;
;                         *(u32x4*)(XH + (size_t)row * DM + col0 + bj * 128) = pack8(xa, xb);
;                         ssq += ((xa[0] * xa[0] + xa[1] * xa[1]) + (xa[2] * xa[2] + xa[3] * xa[3])) + ((xb[0] * xb[0] + xb[1] * xb[1]) + (xb[2] * xb[2] + xb[3] * xb[3])); }
;                     ssq += __shfl_xor(ssq, 16); ssq += __shfl_xor(ssq, 32);
;                     if (fq == 0) SSP[(size_t)row * 16 + u.pn * 4 + wc] = ssq; }
;             }
.LBB0_417:
	v_lshl_add_u64 v[176:177], v[132:133], 1, s[8:9]
	v_and_b32_e32 v133, 64, v198
	v_xor_b32_e32 v132, 16, v198
	v_add_u32_e32 v133, 64, v133
	v_cmp_lt_i32_e32 vcc, v132, v133
	v_or_b32_e32 v186, 16, v174
	v_ashrrev_i32_e32 v187, 31, v186
	v_cndmask_b32_e32 v132, v198, v132, vcc
	v_lshlrev_b32_e32 v195, 2, v132
	v_xor_b32_e32 v132, 32, v198
	v_cmp_lt_i32_e32 vcc, v132, v133
	v_or_b32_e32 v182, 32, v174
	v_ashrrev_i32_e32 v183, 31, v182
	v_cndmask_b32_e32 v132, v198, v132, vcc
	v_lshlrev_b32_e32 v194, 2, v132
	v_lshlrev_b64 v[132:133], 11, v[174:175]
	v_lshl_add_u64 v[190:191], v[176:177], 0, v[132:133]
	global_load_dwordx4 v[202:205], v[190:191], off
	global_load_dwordx4 v[156:159], v[190:191], off offset:256
	v_lshlrev_b64 v[132:133], 11, v[186:187]
	v_or_b32_e32 v178, 48, v174
	v_lshl_add_u64 v[188:189], v[176:177], 0, v[132:133]
	v_lshlrev_b64 v[132:133], 11, v[182:183]
	v_ashrrev_i32_e32 v179, 31, v178
	v_lshl_add_u64 v[184:185], v[176:177], 0, v[132:133]
	v_lshlrev_b64 v[132:133], 11, v[178:179]
	v_lshl_add_u64 v[180:181], v[176:177], 0, v[132:133]
	global_load_dwordx4 v[152:155], v[188:189], off
	global_load_dwordx4 v[148:151], v[188:189], off offset:256
	global_load_dwordx4 v[144:147], v[184:185], off
	global_load_dwordx4 v[140:143], v[184:185], off offset:256
	global_load_dwordx4 v[136:139], v[180:181], off
	global_load_dwordx4 v[132:135], v[180:181], off offset:256
	v_lshl_add_u64 v[240:241], s[88:89], 1, v[190:191]
	v_lshl_add_u64 v[242:243], s[88:89], 1, v[188:189]
	v_lshl_add_u64 v[244:245], s[88:89], 1, v[184:185]
	v_lshl_add_u64 v[246:247], s[88:89], 1, v[180:181]
	global_load_dwordx4 v[208:211], v[240:241], off
	global_load_dwordx4 v[212:215], v[240:241], off offset:256
	global_load_dwordx4 v[216:219], v[242:243], off
	global_load_dwordx4 v[220:223], v[242:243], off offset:256
	global_load_dwordx4 v[224:227], v[244:245], off
	global_load_dwordx4 v[228:231], v[244:245], off offset:256
	global_load_dwordx4 v[232:235], v[246:247], off
	global_load_dwordx4 v[236:239], v[246:247], off offset:256
	s_waitcnt vmcnt(0)
	v_lshlrev_b32_e32 v206, 16, v202
	v_and_b32_e32 v207, 0xffff0000, v202
	v_lshlrev_b32_e32 v202, 16, v203
	v_and_b32_e32 v203, 0xffff0000, v203
	v_pk_fma_f32 v[130:131], v[130:131], 0.5, v[202:203] op_sel_hi:[1,0,1]
	v_lshlrev_b32_e32 v202, 16, v204
	v_and_b32_e32 v203, 0xffff0000, v204
	v_lshlrev_b32_e32 v204, 16, v205
	v_and_b32_e32 v205, 0xffff0000, v205
	v_pk_fma_f32 v[128:129], v[128:129], 0.5, v[206:207] op_sel_hi:[1,0,1]
	v_pk_fma_f32 v[204:205], v[126:127], 0.5, v[204:205] op_sel_hi:[1,0,1]
	v_pk_fma_f32 v[202:203], v[124:125], 0.5, v[202:203] op_sel_hi:[1,0,1]
	v_cvt_pk_bf16_f32 v124, v128, v129
	v_cvt_pk_bf16_f32 v125, v130, v131
	v_cvt_pk_bf16_f32 v126, v202, v203
	v_cvt_pk_bf16_f32 v127, v204, v205
	global_store_dwordx4 v[190:191], v[124:127], off
	s_nop 1
	v_mul_f32_e32 v124, v129, v129
	v_mul_f32_e32 v125, v131, v131
	v_fmac_f32_e32 v124, v128, v128
	v_fmac_f32_e32 v125, v130, v130
	v_add_f32_e32 v124, v124, v125
	v_mul_f32_e32 v125, v203, v203
	v_mul_f32_e32 v126, v205, v205
	v_fmac_f32_e32 v125, v202, v202
	v_fmac_f32_e32 v126, v204, v204
	v_add_f32_e32 v125, v125, v126
	v_add_f32_e32 v128, v124, v125
	v_lshlrev_b32_e32 v124, 16, v156
	v_and_b32_e32 v125, 0xffff0000, v156
	v_lshlrev_b32_e32 v126, 16, v157
	v_and_b32_e32 v127, 0xffff0000, v157
	v_pk_fma_f32 v[122:123], v[122:123], 0.5, v[126:127] op_sel_hi:[1,0,1]
	v_pk_fma_f32 v[120:121], v[120:121], 0.5, v[124:125] op_sel_hi:[1,0,1]
	v_lshlrev_b32_e32 v124, 16, v158
	v_and_b32_e32 v125, 0xffff0000, v158
	v_lshlrev_b32_e32 v126, 16, v159
	v_and_b32_e32 v127, 0xffff0000, v159
	v_pk_fma_f32 v[126:127], v[118:119], 0.5, v[126:127] op_sel_hi:[1,0,1]
	v_pk_fma_f32 v[124:125], v[116:117], 0.5, v[124:125] op_sel_hi:[1,0,1]
	v_cvt_pk_bf16_f32 v116, v120, v121
	v_cvt_pk_bf16_f32 v117, v122, v123
	v_cvt_pk_bf16_f32 v118, v124, v125
	v_cvt_pk_bf16_f32 v119, v126, v127
	global_store_dwordx4 v[190:191], v[116:119], off offset:256
	s_nop 1
	v_mul_f32_e32 v116, v121, v121
	v_mul_f32_e32 v117, v123, v123
	v_fmac_f32_e32 v116, v120, v120
	v_fmac_f32_e32 v117, v122, v122
	v_add_f32_e32 v116, v116, v117
	v_mul_f32_e32 v117, v125, v125
	v_mul_f32_e32 v118, v127, v127
	v_fmac_f32_e32 v117, v124, v124
	v_fmac_f32_e32 v118, v126, v126
	v_add_f32_e32 v117, v117, v118
	v_add_f32_e32 v116, v116, v117
	v_add_f32_e32 v116, v128, v116
	v_mov_b32_e32 v117, v116
	v_mov_b32_e32 v254, v116
	s_nop 1
	v_permlane16_swap_b32_e32 v117, v254
	s_nop 1
	v_mov_b32_dpp v117, v254 quad_perm:[0,1,2,3] row_mask:0x5 bank_mask:0xf
	s_waitcnt lgkmcnt(0)
	v_add_f32_e32 v116, v116, v117
	v_mov_b32_e32 v117, v116
	v_mov_b32_e32 v255, v116
	s_nop 1
	v_permlane32_swap_b32_e32 v117, v255
	s_nop 1
	v_mov_b32_dpp v117, v255 quad_perm:[0,1,2,3] row_mask:0x3 bank_mask:0xf
	s_and_saveexec_b64 s[18:19], s[2:3]
	s_cbranch_execz .LBB0_419
	s_waitcnt lgkmcnt(0)
	v_add_f32_e32 v118, v116, v117
	s_lshl_b32 s20, s37, 2
	v_lshlrev_b64 v[116:117], 6, v[174:175]
	s_ashr_i32 s21, s20, 31
	v_lshl_add_u64 v[116:117], s[10:11], 0, v[116:117]
	v_lshl_add_u64 v[116:117], s[20:21], 2, v[116:117]
	s_lshl_b32 s62, s43, 2
	v_lshl_add_u64 v[116:117], v[116:117], 0, s[62:63]
	global_store_dword v[116:117], v118, off
; DI u32x4 pack8(f32x4 a, f32x4 b) { u32x4 w; w.x = pk2(a[0], a[1]); w.y = pk2(a[2], a[3]); w.z = pk2(b[0], b[1]); w.w = pk2(b[2], b[3]); return w; }
;     DI void operator()(const pg8::Acc& acc, const pg8::Unit& u, int wr, int wc, int fr, int fq) const {
;     ...
;                 for (int m = 0; m < 4; ++m)
; #pragma unroll
;                     for (int bj = 0; bj < 2; ++bj) xv[m][bj] = *(const u32x4*)(XH + (size_t)(row0 + ai * 128 + m * 16) * DM + col0 + bj * 128);
; #pragma unroll
;                 for (int m = 0; m < 4; ++m) { const int row = row0 + ai * 128 + m * 16; float ssq = 0.f;
; #pragma unroll
;                     for (int bj = 0; bj < 2; ++bj) { const u32x4 x = xv[m][bj];
;                         const f32x4 xa = (f32x4){bflo(x.x), bfhi(x.x), bflo(x.y), bfhi(x.y)} + acc[ai][bj][m][0] * scale, xb = (f32x4){bflo(x.z), bfhi(x.z), bflo(x.w), bfhi(x.w)} + acc[ai][bj][m][1] * scale;
;                         *(u32x4*)(XH + (size_t)row * DM + col0 + bj * 128) = pack8(xa, xb);
;                         ssq += ((xa[0] * xa[0] + xa[1] * xa[1]) + (xa[2] * xa[2] + xa[3] * xa[3])) + ((xb[0] * xb[0] + xb[1] * xb[1]) + (xb[2] * xb[2] + xb[3] * xb[3])); }
;                     ssq += __shfl_xor(ssq, 16); ssq += __shfl_xor(ssq, 32);
;                     if (fq == 0) SSP[(size_t)row * 16 + u.pn * 4 + wc] = ssq; }
.LBB0_419:
	s_or_b64 exec, exec, s[18:19]
	v_lshlrev_b32_e32 v116, 16, v152
	s_waitcnt lgkmcnt(0)
	v_and_b32_e32 v117, 0xffff0000, v152
	v_lshlrev_b32_e32 v118, 16, v153
	v_and_b32_e32 v119, 0xffff0000, v153
	v_pk_fma_f32 v[114:115], v[114:115], 0.5, v[118:119] op_sel_hi:[1,0,1]
	v_pk_fma_f32 v[112:113], v[112:113], 0.5, v[116:117] op_sel_hi:[1,0,1]
	v_lshlrev_b32_e32 v116, 16, v154
	v_and_b32_e32 v117, 0xffff0000, v154
	v_lshlrev_b32_e32 v118, 16, v155
	v_and_b32_e32 v119, 0xffff0000, v155
	v_pk_fma_f32 v[118:119], v[110:111], 0.5, v[118:119] op_sel_hi:[1,0,1]
	v_pk_fma_f32 v[110:111], v[108:109], 0.5, v[116:117] op_sel_hi:[1,0,1]
	v_cvt_pk_bf16_f32 v108, v112, v113
	v_mul_f32_e32 v113, v113, v113
	v_fmac_f32_e32 v113, v112, v112
	v_mul_f32_e32 v112, v115, v115
	v_fmac_f32_e32 v112, v114, v114
	v_cvt_pk_bf16_f32 v109, v114, v115
	v_add_f32_e32 v112, v113, v112
	v_mul_f32_e32 v113, v111, v111
	v_mul_f32_e32 v114, v119, v119
	v_fmac_f32_e32 v113, v110, v110
	v_fmac_f32_e32 v114, v118, v118
	v_add_f32_e32 v113, v113, v114
	v_add_f32_e32 v116, v112, v113
	v_lshlrev_b32_e32 v112, 16, v148
	v_and_b32_e32 v113, 0xffff0000, v148
	v_lshlrev_b32_e32 v114, 16, v149
	v_and_b32_e32 v115, 0xffff0000, v149
	v_pk_fma_f32 v[106:107], v[106:107], 0.5, v[114:115] op_sel_hi:[1,0,1]
	v_pk_fma_f32 v[104:105], v[104:105], 0.5, v[112:113] op_sel_hi:[1,0,1]
	v_lshlrev_b32_e32 v112, 16, v150
	v_and_b32_e32 v113, 0xffff0000, v150
	v_lshlrev_b32_e32 v114, 16, v151
	v_and_b32_e32 v115, 0xffff0000, v151
	v_pk_fma_f32 v[112:113], v[100:101], 0.5, v[112:113] op_sel_hi:[1,0,1]
	v_mul_f32_e32 v100, v105, v105
	v_mul_f32_e32 v101, v107, v107
	v_pk_fma_f32 v[114:115], v[102:103], 0.5, v[114:115] op_sel_hi:[1,0,1]
	v_fmac_f32_e32 v100, v104, v104
	v_fmac_f32_e32 v101, v106, v106
	v_add_f32_e32 v100, v100, v101
	v_mul_f32_e32 v101, v113, v113
	v_mul_f32_e32 v102, v115, v115
	v_fmac_f32_e32 v101, v112, v112
	v_fmac_f32_e32 v102, v114, v114
	v_add_f32_e32 v101, v101, v102
	v_add_f32_e32 v100, v100, v101
	v_add_f32_e32 v100, v116, v100
	v_mov_b32_e32 v101, v100
	v_mov_b32_e32 v254, v100
	s_nop 1
	v_permlane16_swap_b32_e32 v101, v254
	s_nop 1
	v_mov_b32_dpp v101, v254 quad_perm:[0,1,2,3] row_mask:0x5 bank_mask:0xf
	v_cvt_pk_bf16_f32 v110, v110, v111
	v_cvt_pk_bf16_f32 v111, v118, v119
	v_cvt_pk_bf16_f32 v102, v104, v105
	v_cvt_pk_bf16_f32 v103, v106, v107
	s_waitcnt lgkmcnt(0)
	v_add_f32_e32 v100, v100, v101
	v_mov_b32_e32 v101, v100
	v_mov_b32_e32 v255, v100
	s_nop 1
	v_permlane32_swap_b32_e32 v101, v255
	s_nop 1
	v_mov_b32_dpp v101, v255 quad_perm:[0,1,2,3] row_mask:0x3 bank_mask:0xf
	v_cvt_pk_bf16_f32 v104, v112, v113
	v_cvt_pk_bf16_f32 v105, v114, v115
	global_store_dwordx4 v[188:189], v[108:111], off
	global_store_dwordx4 v[188:189], v[102:105], off offset:256
	s_and_saveexec_b64 s[18:19], s[2:3]
	s_cbranch_execz .LBB0_421
	s_waitcnt lgkmcnt(0)
	v_add_f32_e32 v102, v100, v101
	s_lshl_b32 s20, s37, 2
	v_lshlrev_b64 v[100:101], 6, v[186:187]
	s_ashr_i32 s21, s20, 31
	v_lshl_add_u64 v[100:101], s[10:11], 0, v[100:101]
	v_lshl_add_u64 v[100:101], s[20:21], 2, v[100:101]
	s_lshl_b32 s62, s43, 2
	v_lshl_add_u64 v[100:101], v[100:101], 0, s[62:63]
	global_store_dword v[100:101], v102, off
.LBB0_421:
	s_or_b64 exec, exec, s[18:19]
	v_lshlrev_b32_e32 v100, 16, v144
	s_waitcnt lgkmcnt(0)
	v_and_b32_e32 v101, 0xffff0000, v144
	v_lshlrev_b32_e32 v102, 16, v145
	v_and_b32_e32 v103, 0xffff0000, v145
	v_pk_fma_f32 v[98:99], v[98:99], 0.5, v[102:103] op_sel_hi:[1,0,1]
	v_pk_fma_f32 v[96:97], v[96:97], 0.5, v[100:101] op_sel_hi:[1,0,1]
	v_lshlrev_b32_e32 v100, 16, v146
	v_and_b32_e32 v101, 0xffff0000, v146
	v_lshlrev_b32_e32 v102, 16, v147
	v_and_b32_e32 v103, 0xffff0000, v147
	v_pk_fma_f32 v[102:103], v[94:95], 0.5, v[102:103] op_sel_hi:[1,0,1]
	v_pk_fma_f32 v[94:95], v[92:93], 0.5, v[100:101] op_sel_hi:[1,0,1]
	v_cvt_pk_bf16_f32 v92, v96, v97
	v_mul_f32_e32 v97, v97, v97
	v_fmac_f32_e32 v97, v96, v96
	v_mul_f32_e32 v96, v99, v99
	v_fmac_f32_e32 v96, v98, v98
	v_cvt_pk_bf16_f32 v93, v98, v99
	v_add_f32_e32 v96, v97, v96
	v_mul_f32_e32 v97, v95, v95
	v_mul_f32_e32 v98, v103, v103
	v_fmac_f32_e32 v97, v94, v94
	v_fmac_f32_e32 v98, v102, v102
	v_add_f32_e32 v97, v97, v98
	v_add_f32_e32 v100, v96, v97
	v_lshlrev_b32_e32 v96, 16, v140
	v_and_b32_e32 v97, 0xffff0000, v140
	v_lshlrev_b32_e32 v98, 16, v141
	v_and_b32_e32 v99, 0xffff0000, v141
	v_pk_fma_f32 v[90:91], v[90:91], 0.5, v[98:99] op_sel_hi:[1,0,1]
	v_pk_fma_f32 v[88:89], v[88:89], 0.5, v[96:97] op_sel_hi:[1,0,1]
	v_lshlrev_b32_e32 v96, 16, v142
	v_and_b32_e32 v97, 0xffff0000, v142
	v_lshlrev_b32_e32 v98, 16, v143
	v_and_b32_e32 v99, 0xffff0000, v143
	v_pk_fma_f32 v[96:97], v[84:85], 0.5, v[96:97] op_sel_hi:[1,0,1]
	v_mul_f32_e32 v84, v89, v89
	v_mul_f32_e32 v85, v91, v91
	v_pk_fma_f32 v[98:99], v[86:87], 0.5, v[98:99] op_sel_hi:[1,0,1]
	v_fmac_f32_e32 v84, v88, v88
	v_fmac_f32_e32 v85, v90, v90
	v_add_f32_e32 v84, v84, v85
	v_mul_f32_e32 v85, v97, v97
	v_mul_f32_e32 v86, v99, v99
	v_fmac_f32_e32 v85, v96, v96
	v_fmac_f32_e32 v86, v98, v98
	v_add_f32_e32 v85, v85, v86
	v_add_f32_e32 v84, v84, v85
	v_add_f32_e32 v84, v100, v84
	v_mov_b32_e32 v85, v84
	v_mov_b32_e32 v254, v84
	s_nop 1
	v_permlane16_swap_b32_e32 v85, v254
	s_nop 1
	v_mov_b32_dpp v85, v254 quad_perm:[0,1,2,3] row_mask:0x5 bank_mask:0xf
	v_cvt_pk_bf16_f32 v94, v94, v95
	v_cvt_pk_bf16_f32 v95, v102, v103
	v_cvt_pk_bf16_f32 v86, v88, v89
	v_cvt_pk_bf16_f32 v87, v90, v91
	s_waitcnt lgkmcnt(0)
	v_add_f32_e32 v84, v84, v85
	v_mov_b32_e32 v85, v84
	v_mov_b32_e32 v255, v84
	s_nop 1
	v_permlane32_swap_b32_e32 v85, v255
	s_nop 1
	v_mov_b32_dpp v85, v255 quad_perm:[0,1,2,3] row_mask:0x3 bank_mask:0xf
	v_cvt_pk_bf16_f32 v88, v96, v97
	v_cvt_pk_bf16_f32 v89, v98, v99
	global_store_dwordx4 v[184:185], v[92:95], off
	global_store_dwordx4 v[184:185], v[86:89], off offset:256
	s_and_saveexec_b64 s[18:19], s[2:3]
	s_cbranch_execz .LBB0_423
	s_waitcnt lgkmcnt(0)
	v_add_f32_e32 v86, v84, v85
	s_lshl_b32 s20, s37, 2
	v_lshlrev_b64 v[84:85], 6, v[182:183]
	s_ashr_i32 s21, s20, 31
	v_lshl_add_u64 v[84:85], s[10:11], 0, v[84:85]
	v_lshl_add_u64 v[84:85], s[20:21], 2, v[84:85]
	s_lshl_b32 s62, s43, 2
	v_lshl_add_u64 v[84:85], v[84:85], 0, s[62:63]
	global_store_dword v[84:85], v86, off
; DI u32x4 pack8(f32x4 a, f32x4 b) { u32x4 w; w.x = pk2(a[0], a[1]); w.y = pk2(a[2], a[3]); w.z = pk2(b[0], b[1]); w.w = pk2(b[2], b[3]); return w; }
;     DI void operator()(const pg8::Acc& acc, const pg8::Unit& u, int wr, int wc, int fr, int fq) const {
;     ...
;                 for (int m = 0; m < 4; ++m)
; #pragma unroll
;                     for (int bj = 0; bj < 2; ++bj) xv[m][bj] = *(const u32x4*)(XH + (size_t)(row0 + ai * 128 + m * 16) * DM + col0 + bj * 128);
; #pragma unroll
;                 for (int m = 0; m < 4; ++m) { const int row = row0 + ai * 128 + m * 16; float ssq = 0.f;
; #pragma unroll
;                     for (int bj = 0; bj < 2; ++bj) { const u32x4 x = xv[m][bj];
;                         const f32x4 xa = (f32x4){bflo(x.x), bfhi(x.x), bflo(x.y), bfhi(x.y)} + acc[ai][bj][m][0] * scale, xb = (f32x4){bflo(x.z), bfhi(x.z), bflo(x.w), bfhi(x.w)} + acc[ai][bj][m][1] * scale;
;                         *(u32x4*)(XH + (size_t)row * DM + col0 + bj * 128) = pack8(xa, xb);
;                         ssq += ((xa[0] * xa[0] + xa[1] * xa[1]) + (xa[2] * xa[2] + xa[3] * xa[3])) + ((xb[0] * xb[0] + xb[1] * xb[1]) + (xb[2] * xb[2] + xb[3] * xb[3])); }
;                     ssq += __shfl_xor(ssq, 16); ssq += __shfl_xor(ssq, 32);
;                     if (fq == 0) SSP[(size_t)row * 16 + u.pn * 4 + wc] = ssq; }
.LBB0_423:
	s_or_b64 exec, exec, s[18:19]
	v_lshlrev_b32_e32 v84, 16, v136
	s_waitcnt lgkmcnt(0)
	v_and_b32_e32 v85, 0xffff0000, v136
	v_lshlrev_b32_e32 v86, 16, v137
	v_and_b32_e32 v87, 0xffff0000, v137
	v_pk_fma_f32 v[82:83], v[82:83], 0.5, v[86:87] op_sel_hi:[1,0,1]
	v_pk_fma_f32 v[80:81], v[80:81], 0.5, v[84:85] op_sel_hi:[1,0,1]
	v_lshlrev_b32_e32 v84, 16, v138
	v_and_b32_e32 v85, 0xffff0000, v138
	v_lshlrev_b32_e32 v86, 16, v139
	v_and_b32_e32 v87, 0xffff0000, v139
	v_pk_fma_f32 v[86:87], v[78:79], 0.5, v[86:87] op_sel_hi:[1,0,1]
	v_pk_fma_f32 v[78:79], v[76:77], 0.5, v[84:85] op_sel_hi:[1,0,1]
	v_cvt_pk_bf16_f32 v76, v80, v81
	v_mul_f32_e32 v81, v81, v81
	v_fmac_f32_e32 v81, v80, v80
	v_mul_f32_e32 v80, v83, v83
	v_fmac_f32_e32 v80, v82, v82
	v_cvt_pk_bf16_f32 v77, v82, v83
	v_add_f32_e32 v80, v81, v80
	v_mul_f32_e32 v81, v79, v79
	v_mul_f32_e32 v82, v87, v87
	v_fmac_f32_e32 v81, v78, v78
	v_fmac_f32_e32 v82, v86, v86
	v_add_f32_e32 v81, v81, v82
	v_add_f32_e32 v84, v80, v81
	v_lshlrev_b32_e32 v80, 16, v132
	v_and_b32_e32 v81, 0xffff0000, v132
	v_lshlrev_b32_e32 v82, 16, v133
	v_and_b32_e32 v83, 0xffff0000, v133
	v_pk_fma_f32 v[74:75], v[74:75], 0.5, v[82:83] op_sel_hi:[1,0,1]
	v_pk_fma_f32 v[72:73], v[72:73], 0.5, v[80:81] op_sel_hi:[1,0,1]
	v_lshlrev_b32_e32 v80, 16, v134
	v_and_b32_e32 v81, 0xffff0000, v134
	v_lshlrev_b32_e32 v82, 16, v135
	v_and_b32_e32 v83, 0xffff0000, v135
	v_pk_fma_f32 v[80:81], v[68:69], 0.5, v[80:81] op_sel_hi:[1,0,1]
	v_mul_f32_e32 v68, v73, v73
	v_mul_f32_e32 v69, v75, v75
	v_pk_fma_f32 v[82:83], v[70:71], 0.5, v[82:83] op_sel_hi:[1,0,1]
	v_fmac_f32_e32 v68, v72, v72
	v_fmac_f32_e32 v69, v74, v74
	v_add_f32_e32 v68, v68, v69
	v_mul_f32_e32 v69, v81, v81
	v_mul_f32_e32 v70, v83, v83
	v_fmac_f32_e32 v69, v80, v80
	v_fmac_f32_e32 v70, v82, v82
	v_add_f32_e32 v69, v69, v70
	v_add_f32_e32 v68, v68, v69
	v_add_f32_e32 v68, v84, v68
	v_mov_b32_e32 v69, v68
	v_mov_b32_e32 v254, v68
	s_nop 1
	v_permlane16_swap_b32_e32 v69, v254
	s_nop 1
	v_mov_b32_dpp v69, v254 quad_perm:[0,1,2,3] row_mask:0x5 bank_mask:0xf
	v_cvt_pk_bf16_f32 v78, v78, v79
	v_cvt_pk_bf16_f32 v79, v86, v87
	v_cvt_pk_bf16_f32 v70, v72, v73
	v_cvt_pk_bf16_f32 v71, v74, v75
	s_waitcnt lgkmcnt(0)
	v_add_f32_e32 v68, v68, v69
	v_mov_b32_e32 v69, v68
	v_mov_b32_e32 v255, v68
	s_nop 1
	v_permlane32_swap_b32_e32 v69, v255
	s_nop 1
	v_mov_b32_dpp v69, v255 quad_perm:[0,1,2,3] row_mask:0x3 bank_mask:0xf
	v_cvt_pk_bf16_f32 v72, v80, v81
	v_cvt_pk_bf16_f32 v73, v82, v83
	global_store_dwordx4 v[180:181], v[76:79], off
	global_store_dwordx4 v[180:181], v[70:73], off offset:256
	s_and_saveexec_b64 s[18:19], s[2:3]
	s_cbranch_execz .LBB0_425
	s_waitcnt lgkmcnt(0)
	v_add_f32_e32 v70, v68, v69
	s_lshl_b32 s20, s37, 2
	v_lshlrev_b64 v[68:69], 6, v[178:179]
	s_ashr_i32 s21, s20, 31
	v_lshl_add_u64 v[68:69], s[10:11], 0, v[68:69]
	v_lshl_add_u64 v[68:69], s[20:21], 2, v[68:69]
	s_lshl_b32 s62, s43, 2
	v_lshl_add_u64 v[68:69], v[68:69], 0, s[62:63]
	global_store_dword v[68:69], v70, off
.LBB0_425:
	s_or_b64 exec, exec, s[18:19]
	v_add_u32_e32 v108, 0x80, v174
	v_ashrrev_i32_e32 v109, 31, v108
	s_waitcnt lgkmcnt(0)
	v_lshlrev_b64 v[68:69], 11, v[108:109]
	v_lshl_add_u64 v[110:111], v[176:177], 0, v[68:69]
	s_nop 1
	v_mov_b64_e32 v[112:113], v[208:209]
	v_mov_b64_e32 v[114:115], v[210:211]
	v_mov_b64_e32 v[92:93], v[212:213]
	v_mov_b64_e32 v[94:95], v[214:215]
	v_add_u32_e32 v104, 0x90, v174
	v_ashrrev_i32_e32 v105, 31, v104
	v_add_u32_e32 v100, 0xa0, v174
	v_lshlrev_b64 v[68:69], 11, v[104:105]
	v_ashrrev_i32_e32 v101, 31, v100
	v_add_u32_e32 v96, 0xb0, v174
	v_lshl_add_u64 v[106:107], v[176:177], 0, v[68:69]
	v_lshlrev_b64 v[68:69], 11, v[100:101]
	v_ashrrev_i32_e32 v97, 31, v96
	v_lshl_add_u64 v[102:103], v[176:177], 0, v[68:69]
	v_lshlrev_b64 v[68:69], 11, v[96:97]
	v_lshl_add_u64 v[98:99], v[176:177], 0, v[68:69]
	v_mov_b64_e32 v[88:89], v[216:217]
	v_mov_b64_e32 v[90:91], v[218:219]
	v_mov_b64_e32 v[84:85], v[220:221]
	v_mov_b64_e32 v[86:87], v[222:223]
	v_mov_b64_e32 v[80:81], v[224:225]
	v_mov_b64_e32 v[82:83], v[226:227]
	v_mov_b64_e32 v[76:77], v[228:229]
	v_mov_b64_e32 v[78:79], v[230:231]
	v_mov_b64_e32 v[72:73], v[232:233]
	v_mov_b64_e32 v[74:75], v[234:235]
	v_mov_b64_e32 v[68:69], v[236:237]
	v_mov_b64_e32 v[70:71], v[238:239]
	v_lshlrev_b32_e32 v116, 16, v112
	v_and_b32_e32 v117, 0xffff0000, v112
	v_lshlrev_b32_e32 v112, 16, v113
	v_and_b32_e32 v113, 0xffff0000, v113
	v_pk_fma_f32 v[66:67], v[66:67], 0.5, v[112:113] op_sel_hi:[1,0,1]
	v_lshlrev_b32_e32 v112, 16, v114
	v_and_b32_e32 v113, 0xffff0000, v114
	v_lshlrev_b32_e32 v114, 16, v115
	v_and_b32_e32 v115, 0xffff0000, v115
	v_pk_fma_f32 v[64:65], v[64:65], 0.5, v[116:117] op_sel_hi:[1,0,1]
	v_pk_fma_f32 v[114:115], v[62:63], 0.5, v[114:115] op_sel_hi:[1,0,1]
	v_pk_fma_f32 v[112:113], v[60:61], 0.5, v[112:113] op_sel_hi:[1,0,1]
	v_cvt_pk_bf16_f32 v60, v64, v65
	v_cvt_pk_bf16_f32 v61, v66, v67
	v_cvt_pk_bf16_f32 v62, v112, v113
	v_cvt_pk_bf16_f32 v63, v114, v115
	global_store_dwordx4 v[110:111], v[60:63], off
	s_nop 1
	v_mul_f32_e32 v60, v65, v65
	v_mul_f32_e32 v61, v67, v67
	v_fmac_f32_e32 v60, v64, v64
	v_fmac_f32_e32 v61, v66, v66
	v_add_f32_e32 v60, v60, v61
	v_mul_f32_e32 v61, v113, v113
	v_mul_f32_e32 v62, v115, v115
	v_fmac_f32_e32 v61, v112, v112
	v_fmac_f32_e32 v62, v114, v114
	v_add_f32_e32 v61, v61, v62
	v_add_f32_e32 v64, v60, v61
	v_lshlrev_b32_e32 v60, 16, v92
	v_and_b32_e32 v61, 0xffff0000, v92
	v_lshlrev_b32_e32 v62, 16, v93
	v_and_b32_e32 v63, 0xffff0000, v93
	v_pk_fma_f32 v[58:59], v[58:59], 0.5, v[62:63] op_sel_hi:[1,0,1]
	v_pk_fma_f32 v[56:57], v[56:57], 0.5, v[60:61] op_sel_hi:[1,0,1]
	v_lshlrev_b32_e32 v60, 16, v94
	v_and_b32_e32 v61, 0xffff0000, v94
	v_lshlrev_b32_e32 v62, 16, v95
	v_and_b32_e32 v63, 0xffff0000, v95
	v_pk_fma_f32 v[62:63], v[54:55], 0.5, v[62:63] op_sel_hi:[1,0,1]
	v_pk_fma_f32 v[60:61], v[52:53], 0.5, v[60:61] op_sel_hi:[1,0,1]
	v_cvt_pk_bf16_f32 v52, v56, v57
	v_cvt_pk_bf16_f32 v53, v58, v59
	v_cvt_pk_bf16_f32 v54, v60, v61
	v_cvt_pk_bf16_f32 v55, v62, v63
	global_store_dwordx4 v[110:111], v[52:55], off offset:256
	s_nop 1
	v_mul_f32_e32 v52, v57, v57
	v_mul_f32_e32 v53, v59, v59
	v_fmac_f32_e32 v52, v56, v56
	v_fmac_f32_e32 v53, v58, v58
	v_add_f32_e32 v52, v52, v53
	v_mul_f32_e32 v53, v61, v61
	v_mul_f32_e32 v54, v63, v63
	v_fmac_f32_e32 v53, v60, v60
	v_fmac_f32_e32 v54, v62, v62
	v_add_f32_e32 v53, v53, v54
	v_add_f32_e32 v52, v52, v53
	v_add_f32_e32 v52, v64, v52
	v_mov_b32_e32 v53, v52
	v_mov_b32_e32 v254, v52
	s_nop 1
	v_permlane16_swap_b32_e32 v53, v254
	s_nop 1
	v_mov_b32_dpp v53, v254 quad_perm:[0,1,2,3] row_mask:0x5 bank_mask:0xf
	s_waitcnt lgkmcnt(0)
	v_add_f32_e32 v52, v52, v53
	v_mov_b32_e32 v53, v52
	v_mov_b32_e32 v255, v52
	s_nop 1
	v_permlane32_swap_b32_e32 v53, v255
	s_nop 1
	v_mov_b32_dpp v53, v255 quad_perm:[0,1,2,3] row_mask:0x3 bank_mask:0xf
	s_and_saveexec_b64 s[18:19], s[2:3]
	s_cbranch_execz .LBB0_427
; DI u32x4 pack8(f32x4 a, f32x4 b) { u32x4 w; w.x = pk2(a[0], a[1]); w.y = pk2(a[2], a[3]); w.z = pk2(b[0], b[1]); w.w = pk2(b[2], b[3]); return w; }
;     DI void operator()(const pg8::Acc& acc, const pg8::Unit& u, int wr, int wc, int fr, int fq) const {
;     ...
;                 for (int m = 0; m < 4; ++m)
; #pragma unroll
;                     for (int bj = 0; bj < 2; ++bj) xv[m][bj] = *(const u32x4*)(XH + (size_t)(row0 + ai * 128 + m * 16) * DM + col0 + bj * 128);
; #pragma unroll
;                 for (int m = 0; m < 4; ++m) { const int row = row0 + ai * 128 + m * 16; float ssq = 0.f;
; #pragma unroll
;                     for (int bj = 0; bj < 2; ++bj) { const u32x4 x = xv[m][bj];
;                         const f32x4 xa = (f32x4){bflo(x.x), bfhi(x.x), bflo(x.y), bfhi(x.y)} + acc[ai][bj][m][0] * scale, xb = (f32x4){bflo(x.z), bfhi(x.z), bflo(x.w), bfhi(x.w)} + acc[ai][bj][m][1] * scale;
;                         *(u32x4*)(XH + (size_t)row * DM + col0 + bj * 128) = pack8(xa, xb);
;                         ssq += ((xa[0] * xa[0] + xa[1] * xa[1]) + (xa[2] * xa[2] + xa[3] * xa[3])) + ((xb[0] * xb[0] + xb[1] * xb[1]) + (xb[2] * xb[2] + xb[3] * xb[3])); }
;                     ssq += __shfl_xor(ssq, 16); ssq += __shfl_xor(ssq, 32);
;                     if (fq == 0) SSP[(size_t)row * 16 + u.pn * 4 + wc] = ssq; }
	s_waitcnt lgkmcnt(0)
	v_add_f32_e32 v54, v52, v53
	s_lshl_b32 s20, s37, 2
	v_lshlrev_b64 v[52:53], 6, v[108:109]
	s_ashr_i32 s21, s20, 31
	v_lshl_add_u64 v[52:53], s[10:11], 0, v[52:53]
	v_lshl_add_u64 v[52:53], s[20:21], 2, v[52:53]
	s_lshl_b32 s62, s43, 2
	v_lshl_add_u64 v[52:53], v[52:53], 0, s[62:63]
	global_store_dword v[52:53], v54, off
.LBB0_427:
	s_or_b64 exec, exec, s[18:19]
	v_lshlrev_b32_e32 v52, 16, v88
	s_waitcnt lgkmcnt(0)
	v_and_b32_e32 v53, 0xffff0000, v88
	v_lshlrev_b32_e32 v54, 16, v89
	v_and_b32_e32 v55, 0xffff0000, v89
	v_pk_fma_f32 v[50:51], v[50:51], 0.5, v[54:55] op_sel_hi:[1,0,1]
	v_pk_fma_f32 v[48:49], v[48:49], 0.5, v[52:53] op_sel_hi:[1,0,1]
	v_lshlrev_b32_e32 v52, 16, v90
	v_and_b32_e32 v53, 0xffff0000, v90
	v_lshlrev_b32_e32 v54, 16, v91
	v_and_b32_e32 v55, 0xffff0000, v91
	v_pk_fma_f32 v[54:55], v[46:47], 0.5, v[54:55] op_sel_hi:[1,0,1]
	v_pk_fma_f32 v[46:47], v[44:45], 0.5, v[52:53] op_sel_hi:[1,0,1]
	v_cvt_pk_bf16_f32 v44, v48, v49
	v_mul_f32_e32 v49, v49, v49
	v_fmac_f32_e32 v49, v48, v48
	v_mul_f32_e32 v48, v51, v51
	v_fmac_f32_e32 v48, v50, v50
	v_cvt_pk_bf16_f32 v45, v50, v51
	v_add_f32_e32 v48, v49, v48
	v_mul_f32_e32 v49, v47, v47
	v_mul_f32_e32 v50, v55, v55
	v_fmac_f32_e32 v49, v46, v46
	v_fmac_f32_e32 v50, v54, v54
	v_add_f32_e32 v49, v49, v50
	v_add_f32_e32 v52, v48, v49
	v_lshlrev_b32_e32 v48, 16, v84
	v_and_b32_e32 v49, 0xffff0000, v84
	v_lshlrev_b32_e32 v50, 16, v85
	v_and_b32_e32 v51, 0xffff0000, v85
	v_pk_fma_f32 v[42:43], v[42:43], 0.5, v[50:51] op_sel_hi:[1,0,1]
	v_pk_fma_f32 v[40:41], v[40:41], 0.5, v[48:49] op_sel_hi:[1,0,1]
	v_lshlrev_b32_e32 v48, 16, v86
	v_and_b32_e32 v49, 0xffff0000, v86
	v_lshlrev_b32_e32 v50, 16, v87
	v_and_b32_e32 v51, 0xffff0000, v87
	v_pk_fma_f32 v[48:49], v[36:37], 0.5, v[48:49] op_sel_hi:[1,0,1]
	v_mul_f32_e32 v36, v41, v41
	v_mul_f32_e32 v37, v43, v43
	v_pk_fma_f32 v[50:51], v[38:39], 0.5, v[50:51] op_sel_hi:[1,0,1]
	v_fmac_f32_e32 v36, v40, v40
	v_fmac_f32_e32 v37, v42, v42
	v_add_f32_e32 v36, v36, v37
	v_mul_f32_e32 v37, v49, v49
	v_mul_f32_e32 v38, v51, v51
	v_fmac_f32_e32 v37, v48, v48
	v_fmac_f32_e32 v38, v50, v50
	v_add_f32_e32 v37, v37, v38
	v_add_f32_e32 v36, v36, v37
	v_add_f32_e32 v36, v52, v36
	v_mov_b32_e32 v37, v36
	v_mov_b32_e32 v254, v36
	s_nop 1
	v_permlane16_swap_b32_e32 v37, v254
	s_nop 1
	v_mov_b32_dpp v37, v254 quad_perm:[0,1,2,3] row_mask:0x5 bank_mask:0xf
	v_cvt_pk_bf16_f32 v46, v46, v47
	v_cvt_pk_bf16_f32 v47, v54, v55
	v_cvt_pk_bf16_f32 v38, v40, v41
	v_cvt_pk_bf16_f32 v39, v42, v43
	s_waitcnt lgkmcnt(0)
	v_add_f32_e32 v36, v36, v37
	v_mov_b32_e32 v37, v36
	v_mov_b32_e32 v255, v36
	s_nop 1
	v_permlane32_swap_b32_e32 v37, v255
	s_nop 1
	v_mov_b32_dpp v37, v255 quad_perm:[0,1,2,3] row_mask:0x3 bank_mask:0xf
	v_cvt_pk_bf16_f32 v40, v48, v49
	v_cvt_pk_bf16_f32 v41, v50, v51
	global_store_dwordx4 v[106:107], v[44:47], off
	global_store_dwordx4 v[106:107], v[38:41], off offset:256
	s_and_saveexec_b64 s[18:19], s[2:3]
	s_cbranch_execz .LBB0_429
	s_waitcnt lgkmcnt(0)
	v_add_f32_e32 v38, v36, v37
	s_lshl_b32 s20, s37, 2
	v_lshlrev_b64 v[36:37], 6, v[104:105]
	s_ashr_i32 s21, s20, 31
	v_lshl_add_u64 v[36:37], s[10:11], 0, v[36:37]
	v_lshl_add_u64 v[36:37], s[20:21], 2, v[36:37]
	s_lshl_b32 s62, s43, 2
	v_lshl_add_u64 v[36:37], v[36:37], 0, s[62:63]
	global_store_dword v[36:37], v38, off
; DI u32x4 pack8(f32x4 a, f32x4 b) { u32x4 w; w.x = pk2(a[0], a[1]); w.y = pk2(a[2], a[3]); w.z = pk2(b[0], b[1]); w.w = pk2(b[2], b[3]); return w; }
;     DI void operator()(const pg8::Acc& acc, const pg8::Unit& u, int wr, int wc, int fr, int fq) const {
;     ...
;                 for (int m = 0; m < 4; ++m)
; #pragma unroll
;                     for (int bj = 0; bj < 2; ++bj) xv[m][bj] = *(const u32x4*)(XH + (size_t)(row0 + ai * 128 + m * 16) * DM + col0 + bj * 128);
; #pragma unroll
;                 for (int m = 0; m < 4; ++m) { const int row = row0 + ai * 128 + m * 16; float ssq = 0.f;
; #pragma unroll
;                     for (int bj = 0; bj < 2; ++bj) { const u32x4 x = xv[m][bj];
;                         const f32x4 xa = (f32x4){bflo(x.x), bfhi(x.x), bflo(x.y), bfhi(x.y)} + acc[ai][bj][m][0] * scale, xb = (f32x4){bflo(x.z), bfhi(x.z), bflo(x.w), bfhi(x.w)} + acc[ai][bj][m][1] * scale;
;                         *(u32x4*)(XH + (size_t)row * DM + col0 + bj * 128) = pack8(xa, xb);
;                         ssq += ((xa[0] * xa[0] + xa[1] * xa[1]) + (xa[2] * xa[2] + xa[3] * xa[3])) + ((xb[0] * xb[0] + xb[1] * xb[1]) + (xb[2] * xb[2] + xb[3] * xb[3])); }
;                     ssq += __shfl_xor(ssq, 16); ssq += __shfl_xor(ssq, 32);
;                     if (fq == 0) SSP[(size_t)row * 16 + u.pn * 4 + wc] = ssq; }
.LBB0_429:
	s_or_b64 exec, exec, s[18:19]
	v_lshlrev_b32_e32 v36, 16, v80
	s_waitcnt lgkmcnt(0)
	v_and_b32_e32 v37, 0xffff0000, v80
	v_lshlrev_b32_e32 v38, 16, v81
	v_and_b32_e32 v39, 0xffff0000, v81
	v_pk_fma_f32 v[34:35], v[34:35], 0.5, v[38:39] op_sel_hi:[1,0,1]
	v_pk_fma_f32 v[32:33], v[32:33], 0.5, v[36:37] op_sel_hi:[1,0,1]
	v_lshlrev_b32_e32 v36, 16, v82
	v_and_b32_e32 v37, 0xffff0000, v82
	v_lshlrev_b32_e32 v38, 16, v83
	v_and_b32_e32 v39, 0xffff0000, v83
	v_pk_fma_f32 v[38:39], v[30:31], 0.5, v[38:39] op_sel_hi:[1,0,1]
	v_pk_fma_f32 v[30:31], v[28:29], 0.5, v[36:37] op_sel_hi:[1,0,1]
	v_cvt_pk_bf16_f32 v28, v32, v33
	v_mul_f32_e32 v33, v33, v33
	v_fmac_f32_e32 v33, v32, v32
	v_mul_f32_e32 v32, v35, v35
	v_fmac_f32_e32 v32, v34, v34
	v_cvt_pk_bf16_f32 v29, v34, v35
	v_add_f32_e32 v32, v33, v32
	v_mul_f32_e32 v33, v31, v31
	v_mul_f32_e32 v34, v39, v39
	v_fmac_f32_e32 v33, v30, v30
	v_fmac_f32_e32 v34, v38, v38
	v_add_f32_e32 v33, v33, v34
	v_add_f32_e32 v36, v32, v33
	v_lshlrev_b32_e32 v32, 16, v76
	v_and_b32_e32 v33, 0xffff0000, v76
	v_lshlrev_b32_e32 v34, 16, v77
	v_and_b32_e32 v35, 0xffff0000, v77
	v_pk_fma_f32 v[26:27], v[26:27], 0.5, v[34:35] op_sel_hi:[1,0,1]
	v_pk_fma_f32 v[24:25], v[24:25], 0.5, v[32:33] op_sel_hi:[1,0,1]
	v_lshlrev_b32_e32 v32, 16, v78
	v_and_b32_e32 v33, 0xffff0000, v78
	v_lshlrev_b32_e32 v34, 16, v79
	v_and_b32_e32 v35, 0xffff0000, v79
	v_pk_fma_f32 v[32:33], v[20:21], 0.5, v[32:33] op_sel_hi:[1,0,1]
	v_mul_f32_e32 v20, v25, v25
	v_mul_f32_e32 v21, v27, v27
	v_pk_fma_f32 v[34:35], v[22:23], 0.5, v[34:35] op_sel_hi:[1,0,1]
	v_fmac_f32_e32 v20, v24, v24
	v_fmac_f32_e32 v21, v26, v26
	v_add_f32_e32 v20, v20, v21
	v_mul_f32_e32 v21, v33, v33
	v_mul_f32_e32 v22, v35, v35
	v_fmac_f32_e32 v21, v32, v32
	v_fmac_f32_e32 v22, v34, v34
	v_add_f32_e32 v21, v21, v22
	v_add_f32_e32 v20, v20, v21
	v_add_f32_e32 v20, v36, v20
	v_mov_b32_e32 v21, v20
	v_mov_b32_e32 v254, v20
	s_nop 1
	v_permlane16_swap_b32_e32 v21, v254
	s_nop 1
	v_mov_b32_dpp v21, v254 quad_perm:[0,1,2,3] row_mask:0x5 bank_mask:0xf
	v_cvt_pk_bf16_f32 v30, v30, v31
	v_cvt_pk_bf16_f32 v31, v38, v39
	v_cvt_pk_bf16_f32 v22, v24, v25
	v_cvt_pk_bf16_f32 v23, v26, v27
	s_waitcnt lgkmcnt(0)
	v_add_f32_e32 v20, v20, v21
	v_mov_b32_e32 v21, v20
	v_mov_b32_e32 v255, v20
	s_nop 1
	v_permlane32_swap_b32_e32 v21, v255
	s_nop 1
	v_mov_b32_dpp v21, v255 quad_perm:[0,1,2,3] row_mask:0x3 bank_mask:0xf
	v_cvt_pk_bf16_f32 v24, v32, v33
	v_cvt_pk_bf16_f32 v25, v34, v35
	global_store_dwordx4 v[102:103], v[28:31], off
	global_store_dwordx4 v[102:103], v[22:25], off offset:256
	s_and_saveexec_b64 s[18:19], s[2:3]
	s_cbranch_execz .LBB0_431
	s_waitcnt lgkmcnt(0)
	v_add_f32_e32 v22, v20, v21
	s_lshl_b32 s20, s37, 2
	v_lshlrev_b64 v[20:21], 6, v[100:101]
	s_ashr_i32 s21, s20, 31
	v_lshl_add_u64 v[20:21], s[10:11], 0, v[20:21]
	v_lshl_add_u64 v[20:21], s[20:21], 2, v[20:21]
	s_lshl_b32 s62, s43, 2
	v_lshl_add_u64 v[20:21], v[20:21], 0, s[62:63]
	global_store_dword v[20:21], v22, off
.LBB0_431:
	s_or_b64 exec, exec, s[18:19]
	v_lshlrev_b32_e32 v20, 16, v72
	s_waitcnt lgkmcnt(0)
	v_and_b32_e32 v21, 0xffff0000, v72
	v_lshlrev_b32_e32 v22, 16, v73
	v_and_b32_e32 v23, 0xffff0000, v73
	v_pk_fma_f32 v[18:19], v[18:19], 0.5, v[22:23] op_sel_hi:[1,0,1]
	v_pk_fma_f32 v[16:17], v[16:17], 0.5, v[20:21] op_sel_hi:[1,0,1]
	v_lshlrev_b32_e32 v20, 16, v74
	v_and_b32_e32 v21, 0xffff0000, v74
	v_lshlrev_b32_e32 v22, 16, v75
	v_and_b32_e32 v23, 0xffff0000, v75
	v_pk_fma_f32 v[22:23], v[14:15], 0.5, v[22:23] op_sel_hi:[1,0,1]
	v_pk_fma_f32 v[14:15], v[12:13], 0.5, v[20:21] op_sel_hi:[1,0,1]
	v_cvt_pk_bf16_f32 v12, v16, v17
	v_mul_f32_e32 v17, v17, v17
	v_fmac_f32_e32 v17, v16, v16
	v_mul_f32_e32 v16, v19, v19
	v_fmac_f32_e32 v16, v18, v18
	v_cvt_pk_bf16_f32 v13, v18, v19
	v_add_f32_e32 v16, v17, v16
	v_mul_f32_e32 v17, v15, v15
	v_mul_f32_e32 v18, v23, v23
	v_fmac_f32_e32 v17, v14, v14
	v_fmac_f32_e32 v18, v22, v22
	v_add_f32_e32 v17, v17, v18
	v_add_f32_e32 v20, v16, v17
	v_lshlrev_b32_e32 v16, 16, v68
	v_and_b32_e32 v17, 0xffff0000, v68
	v_lshlrev_b32_e32 v18, 16, v69
	v_and_b32_e32 v19, 0xffff0000, v69
	v_pk_fma_f32 v[10:11], v[10:11], 0.5, v[18:19] op_sel_hi:[1,0,1]
	v_pk_fma_f32 v[8:9], v[8:9], 0.5, v[16:17] op_sel_hi:[1,0,1]
	v_lshlrev_b32_e32 v16, 16, v70
	v_and_b32_e32 v17, 0xffff0000, v70
	v_lshlrev_b32_e32 v18, 16, v71
	v_and_b32_e32 v19, 0xffff0000, v71
	v_pk_fma_f32 v[16:17], v[4:5], 0.5, v[16:17] op_sel_hi:[1,0,1]
	v_mul_f32_e32 v4, v9, v9
	v_mul_f32_e32 v5, v11, v11
	v_pk_fma_f32 v[18:19], v[6:7], 0.5, v[18:19] op_sel_hi:[1,0,1]
	v_fmac_f32_e32 v4, v8, v8
	v_fmac_f32_e32 v5, v10, v10
	v_add_f32_e32 v4, v4, v5
	v_mul_f32_e32 v5, v17, v17
	v_mul_f32_e32 v6, v19, v19
	v_fmac_f32_e32 v5, v16, v16
	v_fmac_f32_e32 v6, v18, v18
	v_add_f32_e32 v5, v5, v6
	v_add_f32_e32 v4, v4, v5
	v_add_f32_e32 v4, v20, v4
	v_mov_b32_e32 v5, v4
	v_mov_b32_e32 v254, v4
	s_nop 1
	v_permlane16_swap_b32_e32 v5, v254
	s_nop 1
	v_mov_b32_dpp v5, v254 quad_perm:[0,1,2,3] row_mask:0x5 bank_mask:0xf
	v_cvt_pk_bf16_f32 v14, v14, v15
	v_cvt_pk_bf16_f32 v15, v22, v23
	v_cvt_pk_bf16_f32 v6, v8, v9
	v_cvt_pk_bf16_f32 v7, v10, v11
	s_waitcnt lgkmcnt(0)
	v_add_f32_e32 v4, v4, v5
	v_mov_b32_e32 v5, v4
	v_mov_b32_e32 v255, v4
	s_nop 1
	v_permlane32_swap_b32_e32 v5, v255
	s_nop 1
	v_mov_b32_dpp v5, v255 quad_perm:[0,1,2,3] row_mask:0x3 bank_mask:0xf
	v_cvt_pk_bf16_f32 v8, v16, v17
	v_cvt_pk_bf16_f32 v9, v18, v19
	global_store_dwordx4 v[98:99], v[12:15], off
	global_store_dwordx4 v[98:99], v[6:9], off offset:256
	s_and_saveexec_b64 s[18:19], s[2:3]
	s_cbranch_execz .LBB0_433
	s_waitcnt lgkmcnt(0)
	v_add_f32_e32 v6, v4, v5
	s_lshl_b32 s20, s37, 2
	v_lshlrev_b64 v[4:5], 6, v[96:97]
	s_ashr_i32 s21, s20, 31
	v_lshl_add_u64 v[4:5], s[10:11], 0, v[4:5]
	v_lshl_add_u64 v[4:5], s[20:21], 2, v[4:5]
	s_lshl_b32 s62, s43, 2
	v_lshl_add_u64 v[4:5], v[4:5], 0, s[62:63]
	global_store_dword v[4:5], v6, off

; #define LAS __attribute__((address_space(3)))
; DI void conv_unit(const Args& a, const Frame& F, int l, int unit) {
;     ...
;     {
;         const int c2 = tid & 127, th = tid >> 7;
; #pragma unroll 1
;         for (int tg = 0; tg < 4; ++tg) { const int t = th * 16 + tg * 4;
;             f32x2 zz[34];
; #pragma unroll
;             for (int k = 0; k < 34; ++k) { const unsigned z2 = *(const LAS unsigned*)(Z + (t + k) * 256 + 2 * c2); zz[k] = (f32x2){bflo(z2), bfhi(z2)}; }
; #pragma unroll
;             for (int q = 0; q < 4; ++q) { f32x2 s = cb;
; #pragma unroll
;                 for (int k = 0; k < 31; ++k) s = s + w[k] * zz[k + q];
;                 *(LAS f32x2*)(Y + (t + q) * 260 + 2 * c2) = s; } }
;     }
.LBB0_1522:
	v_add_u32_e32 v109, s0, v73
	ds_read2st64_b32 v[68:69], v109 offset1:2
	ds_read2st64_b32 v[74:75], v109 offset0:4 offset1:6
	ds_read2st64_b32 v[78:79], v109 offset0:8 offset1:10
	ds_read2st64_b32 v[82:83], v109 offset0:12 offset1:14
	ds_read2st64_b32 v[86:87], v109 offset0:16 offset1:18
	s_waitcnt lgkmcnt(4)
	v_lshlrev_b32_e32 v70, 16, v68
	v_and_b32_e32 v71, 0xffff0000, v68
	v_lshlrev_b32_e32 v68, 16, v69
	v_and_b32_e32 v69, 0xffff0000, v69
	v_pk_fma_f32 v[70:71], v[92:93], v[70:71], v[158:159]
	s_waitcnt lgkmcnt(3)
	v_lshlrev_b32_e32 v76, 16, v74
	v_and_b32_e32 v77, 0xffff0000, v74
	v_pk_fma_f32 v[70:71], v[94:95], v[68:69], v[70:71]
	v_pk_fma_f32 v[68:69], v[92:93], v[68:69], v[158:159]
	v_lshlrev_b32_e32 v74, 16, v75
	v_and_b32_e32 v75, 0xffff0000, v75
	v_pk_fma_f32 v[68:69], v[94:95], v[76:77], v[68:69]
	s_waitcnt lgkmcnt(2)
	v_lshlrev_b32_e32 v80, 16, v78
	v_and_b32_e32 v81, 0xffff0000, v78
	v_pk_fma_f32 v[70:71], v[96:97], v[76:77], v[70:71]
	v_pk_fma_f32 v[68:69], v[96:97], v[74:75], v[68:69]
	v_lshlrev_b32_e32 v78, 16, v79
	v_and_b32_e32 v79, 0xffff0000, v79
	ds_read2st64_b32 v[90:91], v109 offset0:20 offset1:22
	v_pk_fma_f32 v[70:71], v[98:99], v[74:75], v[70:71]
	v_pk_fma_f32 v[68:69], v[98:99], v[80:81], v[68:69]
	s_waitcnt lgkmcnt(2)
	v_lshlrev_b32_e32 v84, 16, v82
	v_and_b32_e32 v85, 0xffff0000, v82
	v_pk_fma_f32 v[70:71], v[100:101], v[80:81], v[70:71]
	v_pk_fma_f32 v[68:69], v[100:101], v[78:79], v[68:69]
	v_lshlrev_b32_e32 v82, 16, v83
	v_and_b32_e32 v83, 0xffff0000, v83
	ds_read2st64_b32 v[164:165], v109 offset0:24 offset1:26
	v_pk_fma_f32 v[70:71], v[102:103], v[78:79], v[70:71]
	v_pk_fma_f32 v[68:69], v[102:103], v[84:85], v[68:69]
	s_waitcnt lgkmcnt(2)
	v_lshlrev_b32_e32 v88, 16, v86
	v_and_b32_e32 v89, 0xffff0000, v86
	v_pk_fma_f32 v[70:71], v[104:105], v[84:85], v[70:71]
	v_pk_fma_f32 v[68:69], v[104:105], v[82:83], v[68:69]
	v_lshlrev_b32_e32 v86, 16, v87
	v_and_b32_e32 v87, 0xffff0000, v87
	ds_read2st64_b32 v[168:169], v109 offset0:28 offset1:30
	v_pk_fma_f32 v[70:71], v[106:107], v[82:83], v[70:71]
	v_pk_fma_f32 v[68:69], v[106:107], v[88:89], v[68:69]
	s_waitcnt lgkmcnt(2)
	v_lshlrev_b32_e32 v162, 16, v90
	v_and_b32_e32 v163, 0xffff0000, v90
	v_pk_fma_f32 v[70:71], v[112:113], v[88:89], v[70:71]
	v_pk_fma_f32 v[68:69], v[112:113], v[86:87], v[68:69]
	v_lshlrev_b32_e32 v90, 16, v91
	v_and_b32_e32 v91, 0xffff0000, v91
	ds_read2st64_b32 v[172:173], v109 offset0:32 offset1:34
	v_pk_fma_f32 v[70:71], v[120:121], v[86:87], v[70:71]
	v_pk_fma_f32 v[68:69], v[120:121], v[162:163], v[68:69]
	s_waitcnt lgkmcnt(2)
	v_lshlrev_b32_e32 v166, 16, v164
	v_and_b32_e32 v167, 0xffff0000, v164
	v_pk_fma_f32 v[70:71], v[122:123], v[162:163], v[70:71]
	v_pk_fma_f32 v[68:69], v[122:123], v[90:91], v[68:69]
	v_lshlrev_b32_e32 v164, 16, v165
	v_and_b32_e32 v165, 0xffff0000, v165
	ds_read2st64_b32 v[176:177], v109 offset0:36 offset1:38
	v_pk_fma_f32 v[70:71], v[124:125], v[90:91], v[70:71]
	v_pk_fma_f32 v[68:69], v[124:125], v[166:167], v[68:69]
	s_waitcnt lgkmcnt(2)
	v_lshlrev_b32_e32 v170, 16, v168
	v_and_b32_e32 v171, 0xffff0000, v168
	v_pk_fma_f32 v[70:71], v[114:115], v[166:167], v[70:71]
	v_pk_fma_f32 v[68:69], v[114:115], v[164:165], v[68:69]
	v_lshlrev_b32_e32 v168, 16, v169
	v_and_b32_e32 v169, 0xffff0000, v169
	ds_read2st64_b32 v[180:181], v109 offset0:40 offset1:42
	v_pk_fma_f32 v[70:71], v[116:117], v[164:165], v[70:71]
	v_pk_fma_f32 v[68:69], v[116:117], v[170:171], v[68:69]
	s_waitcnt lgkmcnt(2)
	v_lshlrev_b32_e32 v174, 16, v172
	v_and_b32_e32 v175, 0xffff0000, v172
	v_pk_fma_f32 v[70:71], v[118:119], v[170:171], v[70:71]
	v_pk_fma_f32 v[68:69], v[118:119], v[168:169], v[68:69]
	v_lshlrev_b32_e32 v172, 16, v173
	v_and_b32_e32 v173, 0xffff0000, v173
	ds_read2st64_b32 v[184:185], v109 offset0:44 offset1:46
	v_pk_fma_f32 v[70:71], v[128:129], v[168:169], v[70:71]
	v_pk_fma_f32 v[68:69], v[128:129], v[174:175], v[68:69]
	s_waitcnt lgkmcnt(2)
	v_lshlrev_b32_e32 v178, 16, v176
	v_and_b32_e32 v179, 0xffff0000, v176
	v_pk_fma_f32 v[70:71], v[130:131], v[174:175], v[70:71]
	v_pk_fma_f32 v[68:69], v[130:131], v[172:173], v[68:69]
	v_lshlrev_b32_e32 v176, 16, v177
	v_and_b32_e32 v177, 0xffff0000, v177
	ds_read2st64_b32 v[188:189], v109 offset0:48 offset1:50
	v_pk_fma_f32 v[70:71], v[126:127], v[172:173], v[70:71]
	v_pk_fma_f32 v[68:69], v[126:127], v[178:179], v[68:69]
	s_waitcnt lgkmcnt(2)
	v_lshlrev_b32_e32 v182, 16, v180
	v_and_b32_e32 v183, 0xffff0000, v180
	v_pk_fma_f32 v[70:71], v[136:137], v[178:179], v[70:71]
	v_pk_fma_f32 v[68:69], v[136:137], v[176:177], v[68:69]
	v_lshlrev_b32_e32 v180, 16, v181
	v_and_b32_e32 v181, 0xffff0000, v181
	ds_read2st64_b32 v[192:193], v109 offset0:52 offset1:54
	v_pk_fma_f32 v[70:71], v[138:139], v[176:177], v[70:71]
	v_pk_fma_f32 v[68:69], v[138:139], v[182:183], v[68:69]
	s_waitcnt lgkmcnt(2)
	v_lshlrev_b32_e32 v186, 16, v184
	v_and_b32_e32 v187, 0xffff0000, v184
	v_pk_fma_f32 v[70:71], v[132:133], v[182:183], v[70:71]
	v_pk_fma_f32 v[68:69], v[132:133], v[180:181], v[68:69]
	v_lshlrev_b32_e32 v184, 16, v185
	v_and_b32_e32 v185, 0xffff0000, v185
	ds_read2st64_b32 v[202:203], v109 offset0:56 offset1:58
	v_pk_fma_f32 v[70:71], v[134:135], v[180:181], v[70:71]
	v_pk_fma_f32 v[68:69], v[134:135], v[186:187], v[68:69]
	s_waitcnt lgkmcnt(2)
	v_lshlrev_b32_e32 v190, 16, v188
	v_and_b32_e32 v191, 0xffff0000, v188
	v_pk_fma_f32 v[70:71], v[146:147], v[186:187], v[70:71]
	v_pk_fma_f32 v[68:69], v[146:147], v[184:185], v[68:69]
	v_lshlrev_b32_e32 v188, 16, v189
	v_and_b32_e32 v189, 0xffff0000, v189
	ds_read2st64_b32 v[206:207], v109 offset0:60 offset1:62
	v_pk_fma_f32 v[70:71], v[148:149], v[184:185], v[70:71]
	v_pk_fma_f32 v[68:69], v[148:149], v[190:191], v[68:69]
	s_waitcnt lgkmcnt(2)
; #define LAS __attribute__((address_space(3)))
; DI void conv_unit(const Args& a, const Frame& F, int l, int unit) {
;     ...
;         for (int tg = 0; tg < 4; ++tg) { const int t = th * 16 + tg * 4;
;             f32x2 zz[34];
; #pragma unroll
;             for (int k = 0; k < 34; ++k) { const unsigned z2 = *(const LAS unsigned*)(Z + (t + k) * 256 + 2 * c2); zz[k] = (f32x2){bflo(z2), bfhi(z2)}; }
; #pragma unroll
;             for (int q = 0; q < 4; ++q) { f32x2 s = cb;
; #pragma unroll
;                 for (int k = 0; k < 31; ++k) s = s + w[k] * zz[k + q];
;                 *(LAS f32x2*)(Y + (t + q) * 260 + 2 * c2) = s; } }
;     }
;     __syncthreads();
;     {
;         const f32x4 lg = ((const f32x4*)(a.in[I_CLG] + l * 256))[lane], lb = ((const f32x4*)(a.in[I_CLB] + l * 256))[lane];
	v_lshlrev_b32_e32 v194, 16, v192
	v_and_b32_e32 v195, 0xffff0000, v192
	v_pk_fma_f32 v[70:71], v[150:151], v[190:191], v[70:71]
	v_pk_fma_f32 v[68:69], v[150:151], v[188:189], v[68:69]
	v_lshlrev_b32_e32 v192, 16, v193
	v_and_b32_e32 v193, 0xffff0000, v193
	v_pk_fma_f32 v[70:71], v[140:141], v[188:189], v[70:71]
	v_pk_fma_f32 v[68:69], v[140:141], v[194:195], v[68:69]
	s_waitcnt lgkmcnt(1)
	v_lshlrev_b32_e32 v204, 16, v202
	v_and_b32_e32 v205, 0xffff0000, v202
	v_pk_fma_f32 v[70:71], v[142:143], v[194:195], v[70:71]
	v_pk_fma_f32 v[68:69], v[142:143], v[192:193], v[68:69]
	v_lshlrev_b32_e32 v202, 16, v203
	v_and_b32_e32 v203, 0xffff0000, v203
	v_pk_fma_f32 v[70:71], v[144:145], v[192:193], v[70:71]
	v_pk_fma_f32 v[68:69], v[144:145], v[204:205], v[68:69]
	s_waitcnt lgkmcnt(0)
	v_lshlrev_b32_e32 v208, 16, v206
	v_and_b32_e32 v209, 0xffff0000, v206
	v_pk_fma_f32 v[70:71], v[152:153], v[204:205], v[70:71]
	v_pk_fma_f32 v[68:69], v[152:153], v[202:203], v[68:69]
	v_lshlrev_b32_e32 v206, 16, v207
	v_and_b32_e32 v207, 0xffff0000, v207
	v_pk_fma_f32 v[70:71], v[154:155], v[202:203], v[70:71]
	v_pk_fma_f32 v[68:69], v[154:155], v[208:209], v[68:69]
	v_pk_fma_f32 v[70:71], v[156:157], v[208:209], v[70:71]
	v_pk_fma_f32 v[68:69], v[156:157], v[206:207], v[68:69]
	ds_read2st64_b32 v[210:211], v109 offset0:64 offset1:66
	ds_write2_b64 v72, v[70:71], v[68:69] offset1:130
	v_pk_fma_f32 v[68:69], v[92:93], v[76:77], v[158:159]
	v_pk_fma_f32 v[70:71], v[92:93], v[74:75], v[158:159]
	v_pk_fma_f32 v[68:69], v[94:95], v[74:75], v[68:69]
	v_pk_fma_f32 v[70:71], v[94:95], v[80:81], v[70:71]
	v_pk_fma_f32 v[68:69], v[96:97], v[80:81], v[68:69]
	v_pk_fma_f32 v[70:71], v[96:97], v[78:79], v[70:71]
	v_pk_fma_f32 v[68:69], v[98:99], v[78:79], v[68:69]
	v_pk_fma_f32 v[70:71], v[98:99], v[84:85], v[70:71]
	v_pk_fma_f32 v[68:69], v[100:101], v[84:85], v[68:69]
	v_pk_fma_f32 v[70:71], v[100:101], v[82:83], v[70:71]
	v_pk_fma_f32 v[68:69], v[102:103], v[82:83], v[68:69]
	v_pk_fma_f32 v[70:71], v[102:103], v[88:89], v[70:71]
	v_pk_fma_f32 v[68:69], v[104:105], v[88:89], v[68:69]
	v_pk_fma_f32 v[70:71], v[104:105], v[86:87], v[70:71]
	v_pk_fma_f32 v[68:69], v[106:107], v[86:87], v[68:69]
	v_pk_fma_f32 v[70:71], v[106:107], v[162:163], v[70:71]
	v_pk_fma_f32 v[68:69], v[112:113], v[162:163], v[68:69]
	v_pk_fma_f32 v[70:71], v[112:113], v[90:91], v[70:71]
	v_pk_fma_f32 v[68:69], v[120:121], v[90:91], v[68:69]
	v_pk_fma_f32 v[70:71], v[120:121], v[166:167], v[70:71]
	v_pk_fma_f32 v[68:69], v[122:123], v[166:167], v[68:69]
	v_pk_fma_f32 v[70:71], v[122:123], v[164:165], v[70:71]
	v_pk_fma_f32 v[68:69], v[124:125], v[164:165], v[68:69]
	v_pk_fma_f32 v[70:71], v[124:125], v[170:171], v[70:71]
	v_pk_fma_f32 v[68:69], v[114:115], v[170:171], v[68:69]
	v_pk_fma_f32 v[70:71], v[114:115], v[168:169], v[70:71]
	v_pk_fma_f32 v[68:69], v[116:117], v[168:169], v[68:69]
	v_pk_fma_f32 v[70:71], v[116:117], v[174:175], v[70:71]
	v_pk_fma_f32 v[68:69], v[118:119], v[174:175], v[68:69]
	v_pk_fma_f32 v[70:71], v[118:119], v[172:173], v[70:71]
	v_pk_fma_f32 v[68:69], v[128:129], v[172:173], v[68:69]
	v_pk_fma_f32 v[70:71], v[128:129], v[178:179], v[70:71]
	v_pk_fma_f32 v[68:69], v[130:131], v[178:179], v[68:69]
	v_pk_fma_f32 v[70:71], v[130:131], v[176:177], v[70:71]
	v_pk_fma_f32 v[68:69], v[126:127], v[176:177], v[68:69]
	v_pk_fma_f32 v[70:71], v[126:127], v[182:183], v[70:71]
	v_pk_fma_f32 v[68:69], v[136:137], v[182:183], v[68:69]
	v_pk_fma_f32 v[70:71], v[136:137], v[180:181], v[70:71]
	v_pk_fma_f32 v[68:69], v[138:139], v[180:181], v[68:69]
	v_pk_fma_f32 v[70:71], v[138:139], v[186:187], v[70:71]
	v_pk_fma_f32 v[68:69], v[132:133], v[186:187], v[68:69]
	v_pk_fma_f32 v[70:71], v[132:133], v[184:185], v[70:71]
	v_pk_fma_f32 v[68:69], v[134:135], v[184:185], v[68:69]
	v_pk_fma_f32 v[70:71], v[134:135], v[190:191], v[70:71]
	v_pk_fma_f32 v[68:69], v[146:147], v[190:191], v[68:69]
	v_pk_fma_f32 v[70:71], v[146:147], v[188:189], v[70:71]
	v_pk_fma_f32 v[68:69], v[148:149], v[188:189], v[68:69]
	v_pk_fma_f32 v[70:71], v[148:149], v[194:195], v[70:71]
	v_pk_fma_f32 v[68:69], v[150:151], v[194:195], v[68:69]
	v_pk_fma_f32 v[70:71], v[150:151], v[192:193], v[70:71]
	v_pk_fma_f32 v[68:69], v[140:141], v[192:193], v[68:69]
	v_pk_fma_f32 v[70:71], v[140:141], v[204:205], v[70:71]
	v_pk_fma_f32 v[68:69], v[142:143], v[204:205], v[68:69]
	v_pk_fma_f32 v[70:71], v[142:143], v[202:203], v[70:71]
	v_pk_fma_f32 v[68:69], v[144:145], v[202:203], v[68:69]
	v_pk_fma_f32 v[70:71], v[144:145], v[208:209], v[70:71]
	s_waitcnt lgkmcnt(1)
	v_lshlrev_b32_e32 v212, 16, v210
	v_and_b32_e32 v213, 0xffff0000, v210
	v_pk_fma_f32 v[68:69], v[152:153], v[208:209], v[68:69]
	v_pk_fma_f32 v[70:71], v[152:153], v[206:207], v[70:71]
	v_lshlrev_b32_e32 v210, 16, v211
	v_and_b32_e32 v211, 0xffff0000, v211
	v_pk_fma_f32 v[68:69], v[154:155], v[206:207], v[68:69]
	v_pk_fma_f32 v[70:71], v[154:155], v[212:213], v[70:71]
	s_addk_i32 s0, 0x800
	v_pk_fma_f32 v[68:69], v[156:157], v[212:213], v[68:69]
	v_pk_fma_f32 v[70:71], v[156:157], v[210:211], v[70:71]
	v_add_u32_e32 v74, 0x800, v72
	v_add_u32_e32 v72, 0x1040, v72
	s_cmpk_lg_i32 s0, 0x2000
	ds_write2_b64 v74, v[68:69], v[70:71] offset0:4 offset1:134
	s_cbranch_scc1 .LBB0_1522
	v_ashrrev_i32_e32 v109, 31, v108
	v_lshlrev_b64 v[72:73], 4, v[108:109]
	v_lshl_add_u64 v[68:69], s[12:13], 0, v[72:73]
	v_lshl_add_u64 v[72:73], s[14:15], 0, v[72:73]
	s_waitcnt lgkmcnt(0)
	s_barrier
; #define LAS __attribute__((address_space(3)))
; template <int N> DI void wave_sum_n(float (&v)[N]) {
; #pragma unroll
;     for (int o = 1; o < 64; o <<= 1) {
;         float t[N];
; #pragma unroll
;         for (int i = 0; i < N; ++i) t[i] = __shfl_xor(v[i], o);
; #pragma unroll
;         for (int i = 0; i < N; ++i) v[i] += t[i]; }
; }
; DI void conv_unit(const Args& a, const Frame& F, int l, int unit) {
;     ...
;     {
;         const f32x4 lg = ((const f32x4*)(a.in[I_CLG] + l * 256))[lane], lb = ((const f32x4*)(a.in[I_CLB] + l * 256))[lane];
;         LAS unsigned char* A = F.lds + CV_A;
;         f32x4 v[8]; float st[16];
; #pragma unroll
;         for (int r = 0; r < 8; ++r) { v[r] = *(const LAS f32x4*)(Y + (8 * F.wave + r) * 260 + 4 * lane);
;             st[r] = (v[r][0] + v[r][1]) + (v[r][2] + v[r][3]); st[8 + r] = (v[r][0] * v[r][0] + v[r][1] * v[r][1]) + (v[r][2] * v[r][2] + v[r][3] * v[r][3]); }
;         wave_sum_n<16>(st);
; #pragma unroll
;         for (int r = 0; r < 8; ++r) { const int t = 8 * F.wave + r; const float mu = st[r] * (1.f / 256.f); const float var = fmaxf(st[8 + r] * (1.f / 256.f) - mu * mu, 0.f); const float rstd = 1.f / sqrtf(var + EPS);
	global_load_dwordx4 v[68:71], v[68:69], off
	v_lshl_add_u32 v116, v108, 4, s21
	global_load_dwordx4 v[72:75], v[72:73], off
	ds_read_b128 v[104:107], v116 offset:49152
	ds_read_b128 v[100:103], v116 offset:50192
	v_and_b32_e32 v81, 64, v198
	v_add_u32_e32 v117, 64, v81
	v_xor_b32_e32 v81, 1, v198
	v_cmp_lt_i32_e32 vcc, v81, v117
	s_waitcnt lgkmcnt(1)
	v_mul_f32_e32 v80, v104, v104
	v_mul_f32_e32 v82, v105, v105
	v_cndmask_b32_e32 v81, v198, v81, vcc
	v_mul_f32_e32 v112, v106, v106
	v_mul_f32_e32 v114, v107, v107
	v_lshlrev_b32_e32 v109, 2, v81
	v_mov_b32_e32 v81, v104
	v_mov_b32_e32 v83, v105
	v_mov_b32_e32 v113, v106
	v_mov_b32_e32 v115, v107
	v_pk_add_f32 v[80:81], v[80:81], v[82:83]
	v_pk_add_f32 v[82:83], v[112:113], v[114:115]
	v_xor_b32_e32 v112, 2, v198
	v_pk_add_f32 v[80:81], v[80:81], v[82:83]
	s_nop 1
	v_mov_b32_dpp v83, v81 quad_perm:[1,0,3,2] row_mask:0xf bank_mask:0xf
	v_mov_b32_dpp v82, v80 quad_perm:[1,0,3,2] row_mask:0xf bank_mask:0xf
	v_cmp_lt_i32_e32 vcc, v112, v117
	s_waitcnt lgkmcnt(0)
	v_mul_f32_e32 v166, v100, v100
	v_mul_f32_e32 v168, v101, v101
	v_cndmask_b32_e32 v112, v198, v112, vcc
	v_lshlrev_b32_e32 v158, 2, v112
	s_waitcnt lgkmcnt(0)
	v_pk_add_f32 v[80:81], v[80:81], v[82:83]
	s_nop 1
	v_mov_b32_dpp v83, v81 quad_perm:[2,3,0,1] row_mask:0xf bank_mask:0xf
	v_mov_b32_dpp v82, v80 quad_perm:[2,3,0,1] row_mask:0xf bank_mask:0xf
	v_xor_b32_e32 v112, 4, v198
	v_cmp_lt_i32_e32 vcc, v112, v117
	v_mul_f32_e32 v170, v102, v102
	v_mul_f32_e32 v172, v103, v103
	v_cndmask_b32_e32 v112, v198, v112, vcc
	v_lshlrev_b32_e32 v159, 2, v112
	s_waitcnt lgkmcnt(0)
	v_pk_add_f32 v[80:81], v[80:81], v[82:83]
	s_nop 1
	v_mov_b32_dpp v83, v81 row_half_mirror row_mask:0xf bank_mask:0xf
	v_mov_b32_dpp v82, v80 row_half_mirror row_mask:0xf bank_mask:0xf
	v_xor_b32_e32 v112, 8, v198
	v_cmp_lt_i32_e32 vcc, v112, v117
	v_mov_b32_e32 v167, v100
	v_mov_b32_e32 v169, v101
	v_cndmask_b32_e32 v112, v198, v112, vcc
	v_lshlrev_b32_e32 v162, 2, v112
	s_waitcnt lgkmcnt(0)
	v_pk_add_f32 v[80:81], v[80:81], v[82:83]
	s_nop 1
	v_mov_b32_dpp v83, v81 row_ror:8 row_mask:0xf bank_mask:0xf
	v_mov_b32_dpp v82, v80 row_ror:8 row_mask:0xf bank_mask:0xf
	v_xor_b32_e32 v112, 16, v198
	v_cmp_lt_i32_e32 vcc, v112, v117
	v_mov_b32_e32 v171, v102
	v_mov_b32_e32 v173, v103
	v_cndmask_b32_e32 v112, v198, v112, vcc
	v_lshlrev_b32_e32 v163, 2, v112
	s_waitcnt lgkmcnt(0)
	v_pk_add_f32 v[80:81], v[80:81], v[82:83]
	v_mov_b32_e32 v83, v81
	v_mov_b32_e32 v254, v81
	s_nop 1
	v_permlane16_swap_b32_e32 v83, v254
	s_nop 1
	v_mov_b32_dpp v83, v254 quad_perm:[0,1,2,3] row_mask:0x5 bank_mask:0xf
	v_mov_b32_e32 v82, v80
	v_mov_b32_e32 v255, v80
	s_nop 1
	v_permlane16_swap_b32_e32 v82, v255
	s_nop 1
	v_mov_b32_dpp v82, v255 quad_perm:[0,1,2,3] row_mask:0x5 bank_mask:0xf
	v_xor_b32_e32 v112, 32, v198
	v_cmp_lt_i32_e32 vcc, v112, v117
	v_pk_add_f32 v[166:167], v[166:167], v[168:169]
	v_pk_add_f32 v[168:169], v[170:171], v[172:173]
	v_cndmask_b32_e32 v112, v198, v112, vcc
	v_lshlrev_b32_e32 v164, 2, v112
	s_waitcnt lgkmcnt(0)
	v_pk_add_f32 v[112:113], v[80:81], v[82:83]
	v_mov_b32_e32 v115, v113
	v_mov_b32_e32 v254, v113
	s_nop 1
	v_permlane32_swap_b32_e32 v115, v254
	s_nop 1
	v_mov_b32_dpp v115, v254 quad_perm:[0,1,2,3] row_mask:0x3 bank_mask:0xf
	v_mov_b32_e32 v114, v112
	v_mov_b32_e32 v255, v112
	s_nop 1
	v_permlane32_swap_b32_e32 v114, v255
	s_nop 1
	v_mov_b32_dpp v114, v255 quad_perm:[0,1,2,3] row_mask:0x3 bank_mask:0xf
	v_pk_add_f32 v[166:167], v[166:167], v[168:169]
	s_nop 1
	v_mov_b32_dpp v169, v167 quad_perm:[1,0,3,2] row_mask:0xf bank_mask:0xf
	v_mov_b32_dpp v168, v166 quad_perm:[1,0,3,2] row_mask:0xf bank_mask:0xf
	ds_read_b128 v[96:99], v116 offset:51232
	ds_read_b128 v[92:95], v116 offset:52272
	s_waitcnt lgkmcnt(2)
	v_pk_add_f32 v[112:113], v[112:113], v[114:115]
	ds_read_b128 v[88:91], v116 offset:53312
	ds_read_b128 v[84:87], v116 offset:54352
	v_pk_mul_f32 v[174:175], v[112:113], s[80:81] op_sel_hi:[1,0]
	s_waitcnt lgkmcnt(4)
	v_pk_add_f32 v[166:167], v[166:167], v[168:169]
	v_fma_f32 v112, -v175, v175, v174
	v_max_f32_e32 v112, 0, v112
	v_add_f32_e32 v112, 0x358637bd, v112
	v_mul_f32_e32 v113, 0x4f800000, v112
	v_cmp_gt_f32_e32 vcc, s67, v112
	v_mov_b32_dpp v169, v167 quad_perm:[2,3,0,1] row_mask:0xf bank_mask:0xf
	v_mov_b32_dpp v168, v166 quad_perm:[2,3,0,1] row_mask:0xf bank_mask:0xf
	v_cndmask_b32_e32 v112, v112, v113, vcc
	v_sqrt_f32_e32 v113, v112
	v_pk_add_f32 v[104:105], v[104:105], v[174:175] op_sel:[0,1] neg_lo:[0,1] neg_hi:[0,1]
	s_waitcnt lgkmcnt(3)
	v_mul_f32_e32 v154, v96, v96
	s_waitcnt lgkmcnt(0)
	v_pk_add_f32 v[166:167], v[166:167], v[168:169]
	v_add_u32_e32 v114, -1, v113
	v_fma_f32 v115, -v114, v113, v112
	v_cmp_ge_f32_e64 s[2:3], 0, v115
	v_add_u32_e32 v115, 1, v113
	v_mov_b32_dpp v169, v167 row_half_mirror row_mask:0xf bank_mask:0xf
	v_cndmask_b32_e64 v114, v113, v114, s[2:3]
	v_fma_f32 v113, -v115, v113, v112
	v_cmp_lt_f32_e64 s[2:3], 0, v113
	v_mov_b32_dpp v168, v166 row_half_mirror row_mask:0xf bank_mask:0xf
	v_mul_f32_e32 v156, v97, v97
	v_cndmask_b32_e64 v113, v114, v115, s[2:3]
	v_mul_f32_e32 v114, 0x37800000, v113
	v_cndmask_b32_e32 v113, v113, v114, vcc
	v_cmp_class_f32_e32 vcc, v112, v196
	s_waitcnt lgkmcnt(0)
	v_pk_add_f32 v[166:167], v[166:167], v[168:169]
	s_nop 1
	v_mov_b32_dpp v169, v167 row_ror:8 row_mask:0xf bank_mask:0xf
	v_cndmask_b32_e32 v113, v113, v112, vcc
	v_div_scale_f32 v115, s[0:1], v113, v113, 1.0
	v_rcp_f32_e32 v117, v115
	v_mov_b32_dpp v168, v166 row_ror:8 row_mask:0xf bank_mask:0xf
	v_mul_f32_e32 v150, v98, v98
	v_mul_f32_e32 v152, v99, v99
	v_fma_f32 v119, -v115, v117, 1.0
	v_fmac_f32_e32 v117, v119, v117
	v_div_scale_f32 v119, vcc, 1.0, v113, 1.0
	s_waitcnt lgkmcnt(0)
; #define LAS __attribute__((address_space(3)))
; DI unsigned pk2(float lo, float hi) { const f32x2 v = {lo, hi}; return __builtin_bit_cast(unsigned, __builtin_convertvector(v, hwbf16x2)); }
; DI float siluf_(float x) { return x * sigmoidf_(x); }
; template <int N> DI void wave_sum_n(float (&v)[N]) {
; #pragma unroll
;     for (int o = 1; o < 64; o <<= 1) {
;         float t[N];
; #pragma unroll
;         for (int i = 0; i < N; ++i) t[i] = __shfl_xor(v[i], o);
; #pragma unroll
;         for (int i = 0; i < N; ++i) v[i] += t[i]; }
; }
; DI void conv_unit(const Args& a, const Frame& F, int l, int unit) {
;     ...
;         for (int r = 0; r < 8; ++r) { v[r] = *(const LAS f32x4*)(Y + (8 * F.wave + r) * 260 + 4 * lane);
;             st[r] = (v[r][0] + v[r][1]) + (v[r][2] + v[r][3]); st[8 + r] = (v[r][0] * v[r][0] + v[r][1] * v[r][1]) + (v[r][2] * v[r][2] + v[r][3] * v[r][3]); }
;         wave_sum_n<16>(st);
; #pragma unroll
;         for (int r = 0; r < 8; ++r) { const int t = 8 * F.wave + r; const float mu = st[r] * (1.f / 256.f); const float var = fmaxf(st[8 + r] * (1.f / 256.f) - mu * mu, 0.f); const float rstd = 1.f / sqrtf(var + EPS);
;             f32x4 o;
; #pragma unroll
;             for (int q = 0; q < 4; ++q) o[q] = siluf_((v[r][q] - mu) * rstd * lg[q] + lb[q]);
;             u32x2 wv; wv.x = pk2(o[0], o[1]); wv.y = pk2(o[2], o[3]); *(LAS u32x2*)(A + t * 528 + lane * 8) = wv; }
	v_pk_add_f32 v[166:167], v[166:167], v[168:169]
	v_mul_f32_e32 v121, v119, v117
	v_mov_b32_e32 v169, v167
	v_mov_b32_e32 v254, v167
	s_nop 1
	v_permlane16_swap_b32_e32 v169, v254
	s_nop 1
	v_mov_b32_dpp v169, v254 quad_perm:[0,1,2,3] row_mask:0x5 bank_mask:0xf
	v_mov_b32_e32 v168, v166
	v_mov_b32_e32 v255, v166
	s_nop 1
	v_permlane16_swap_b32_e32 v168, v255
	s_nop 1
	v_mov_b32_dpp v168, v255 quad_perm:[0,1,2,3] row_mask:0x5 bank_mask:0xf
	v_fma_f32 v123, -v115, v121, v119
	v_fmac_f32_e32 v121, v123, v117
	v_fma_f32 v115, -v115, v121, v119
	v_div_fmas_f32 v115, v115, v117, v121
	v_div_fixup_f32 v170, v115, v113, 1.0
	s_waitcnt lgkmcnt(0)
	v_pk_add_f32 v[166:167], v[166:167], v[168:169]
	v_pk_mul_f32 v[104:105], v[104:105], v[170:171] op_sel_hi:[1,0]
	v_mov_b32_e32 v169, v167
	v_mov_b32_e32 v254, v167
	s_nop 1
	v_permlane32_swap_b32_e32 v169, v254
	s_nop 1
	v_mov_b32_dpp v169, v254 quad_perm:[0,1,2,3] row_mask:0x3 bank_mask:0xf
	v_mov_b32_e32 v168, v166
	v_mov_b32_e32 v255, v166
	s_nop 1
	v_permlane32_swap_b32_e32 v168, v255
	s_nop 1
	v_mov_b32_dpp v168, v255 quad_perm:[0,1,2,3] row_mask:0x3 bank_mask:0xf
	s_waitcnt vmcnt(0)
	v_pk_fma_f32 v[172:173], v[68:69], v[104:105], v[72:73]
	v_mov_b32_e32 v155, v96
	v_mul_f32_e32 v104, 0xbfb8aa3b, v172
	v_exp_f32_e32 v105, v104
	v_mul_f32_e32 v113, 0xbfb8aa3b, v173
	v_exp_f32_e32 v113, v113
	s_waitcnt lgkmcnt(0)
	v_pk_add_f32 v[166:167], v[166:167], v[168:169]
	v_mov_b32_e32 v157, v97
	v_mov_b32_e32 v151, v98
	v_mov_b32_e32 v153, v99
	v_pk_add_f32 v[106:107], v[106:107], v[174:175] op_sel:[0,1] neg_lo:[0,1] neg_hi:[0,1]
	v_pk_mul_f32 v[166:167], v[166:167], s[80:81] op_sel_hi:[1,0]
	v_pk_add_f32 v[154:155], v[154:155], v[156:157]
	v_pk_add_f32 v[150:151], v[150:151], v[152:153]
	v_add_f32_e32 v105, 1.0, v105
	v_pk_mul_f32 v[106:107], v[106:107], v[170:171] op_sel_hi:[1,0]
	v_fma_f32 v115, -v167, v167, v166
	v_pk_add_f32 v[150:151], v[154:155], v[150:151]
	v_rcp_f32_e32 v176, v105
	v_add_f32_e32 v105, 1.0, v113
	v_pk_fma_f32 v[106:107], v[70:71], v[106:107], v[74:75]
	v_max_f32_e32 v115, 0, v115
	v_mov_b32_dpp v153, v151 quad_perm:[1,0,3,2] row_mask:0xf bank_mask:0xf
	v_mov_b32_dpp v152, v150 quad_perm:[1,0,3,2] row_mask:0xf bank_mask:0xf
	v_rcp_f32_e32 v177, v105
	v_mul_f32_e32 v105, 0xbfb8aa3b, v106
	v_add_f32_e32 v115, 0x358637bd, v115
	v_exp_f32_e32 v105, v105
	v_mul_f32_e32 v113, 0xbfb8aa3b, v107
	v_mul_f32_e32 v117, 0x4f800000, v115
	v_cmp_gt_f32_e32 vcc, s67, v115
	v_exp_f32_e32 v113, v113
	s_waitcnt lgkmcnt(0)
	v_pk_add_f32 v[150:151], v[150:151], v[152:153]
	v_cndmask_b32_e32 v115, v115, v117, vcc
	v_sqrt_f32_e32 v117, v115
	v_add_f32_e32 v105, 1.0, v105
	v_mov_b32_dpp v153, v151 quad_perm:[2,3,0,1] row_mask:0xf bank_mask:0xf
	v_mov_b32_dpp v152, v150 quad_perm:[2,3,0,1] row_mask:0xf bank_mask:0xf
	v_rcp_f32_e32 v168, v105
	v_add_f32_e32 v105, 1.0, v113
	v_rcp_f32_e32 v169, v105
	v_add_u32_e32 v105, -1, v117
	v_fma_f32 v113, -v105, v117, v115
	v_cmp_ge_f32_e64 s[2:3], 0, v113
	v_add_u32_e32 v113, 1, v117
	s_waitcnt lgkmcnt(0)
	v_pk_add_f32 v[150:151], v[150:151], v[152:153]
	v_cndmask_b32_e64 v105, v117, v105, s[2:3]
	v_fma_f32 v117, -v113, v117, v115
	v_cmp_lt_f32_e64 s[2:3], 0, v117
	v_mov_b32_dpp v153, v151 row_half_mirror row_mask:0xf bank_mask:0xf
	v_mov_b32_dpp v152, v150 row_half_mirror row_mask:0xf bank_mask:0xf
	v_cndmask_b32_e64 v105, v105, v113, s[2:3]
	v_mul_f32_e32 v113, 0x37800000, v105
	v_cndmask_b32_e32 v105, v105, v113, vcc
	v_cmp_class_f32_e32 vcc, v115, v196
	s_waitcnt lgkmcnt(0)
	v_pk_add_f32 v[150:151], v[150:151], v[152:153]
	s_nop 1
	v_mov_b32_dpp v153, v151 row_ror:8 row_mask:0xf bank_mask:0xf
	v_cndmask_b32_e32 v105, v105, v115, vcc
	v_div_scale_f32 v113, s[0:1], v105, v105, 1.0
	v_rcp_f32_e32 v115, v113
	v_mov_b32_dpp v152, v150 row_ror:8 row_mask:0xf bank_mask:0xf
	v_pk_add_f32 v[100:101], v[100:101], v[166:167] op_sel:[0,1] neg_lo:[0,1] neg_hi:[0,1]
	v_pk_add_f32 v[102:103], v[102:103], v[166:167] op_sel:[0,1] neg_lo:[0,1] neg_hi:[0,1]
	v_fma_f32 v117, -v113, v115, 1.0
	v_fmac_f32_e32 v115, v117, v115
	v_div_scale_f32 v117, vcc, 1.0, v105, 1.0
	s_waitcnt lgkmcnt(0)
	v_pk_add_f32 v[150:151], v[150:151], v[152:153]
	v_mul_f32_e32 v119, v117, v115
	v_mov_b32_e32 v153, v151
	v_mov_b32_e32 v254, v151
	s_nop 1
	v_permlane16_swap_b32_e32 v153, v254
	s_nop 1
	v_mov_b32_dpp v153, v254 quad_perm:[0,1,2,3] row_mask:0x5 bank_mask:0xf
	v_mov_b32_e32 v152, v150
	v_mov_b32_e32 v255, v150
	s_nop 1
	v_permlane16_swap_b32_e32 v152, v255
	s_nop 1
	v_mov_b32_dpp v152, v255 quad_perm:[0,1,2,3] row_mask:0x5 bank_mask:0xf
	v_fma_f32 v121, -v113, v119, v117
	v_fmac_f32_e32 v119, v121, v115
	v_fma_f32 v113, -v113, v119, v117
	v_div_fmas_f32 v113, v113, v115, v119
	v_div_fixup_f32 v154, v113, v105, 1.0
	s_waitcnt lgkmcnt(0)
	v_pk_add_f32 v[150:151], v[150:151], v[152:153]
	v_pk_mul_f32 v[100:101], v[100:101], v[154:155] op_sel_hi:[1,0]
	v_mov_b32_e32 v153, v151
	v_mov_b32_e32 v254, v151
	s_nop 1
	v_permlane32_swap_b32_e32 v153, v254
	s_nop 1
	v_mov_b32_dpp v153, v254 quad_perm:[0,1,2,3] row_mask:0x3 bank_mask:0xf
	v_mov_b32_e32 v152, v150
	v_mov_b32_e32 v255, v150
	s_nop 1
	v_permlane32_swap_b32_e32 v152, v255
	s_nop 1
	v_mov_b32_dpp v152, v255 quad_perm:[0,1,2,3] row_mask:0x3 bank_mask:0xf
	v_pk_fma_f32 v[156:157], v[68:69], v[100:101], v[72:73]
	v_pk_mul_f32 v[168:169], v[106:107], v[168:169]
	v_mul_f32_e32 v100, 0xbfb8aa3b, v156
	v_exp_f32_e32 v101, v100
	v_mul_f32_e32 v105, 0xbfb8aa3b, v157
	v_exp_f32_e32 v105, v105
	s_waitcnt lgkmcnt(0)
; #define LAS __attribute__((address_space(3)))
; DI unsigned pk2(float lo, float hi) { const f32x2 v = {lo, hi}; return __builtin_bit_cast(unsigned, __builtin_convertvector(v, hwbf16x2)); }
; DI float siluf_(float x) { return x * sigmoidf_(x); }
; template <int N> DI void wave_sum_n(float (&v)[N]) {
; #pragma unroll
;     for (int o = 1; o < 64; o <<= 1) {
;         float t[N];
; #pragma unroll
;         for (int i = 0; i < N; ++i) t[i] = __shfl_xor(v[i], o);
; #pragma unroll
;         for (int i = 0; i < N; ++i) v[i] += t[i]; }
; DI void conv_unit(const Args& a, const Frame& F, int l, int unit) {
;     ...
; #pragma unroll
;         for (int r = 0; r < 8; ++r) { v[r] = *(const LAS f32x4*)(Y + (8 * F.wave + r) * 260 + 4 * lane);
;             st[r] = (v[r][0] + v[r][1]) + (v[r][2] + v[r][3]); st[8 + r] = (v[r][0] * v[r][0] + v[r][1] * v[r][1]) + (v[r][2] * v[r][2] + v[r][3] * v[r][3]); }
;         wave_sum_n<16>(st);
; #pragma unroll
;         for (int r = 0; r < 8; ++r) { const int t = 8 * F.wave + r; const float mu = st[r] * (1.f / 256.f); const float var = fmaxf(st[8 + r] * (1.f / 256.f) - mu * mu, 0.f); const float rstd = 1.f / sqrtf(var + EPS);
;             f32x4 o;
; #pragma unroll
;             for (int q = 0; q < 4; ++q) o[q] = siluf_((v[r][q] - mu) * rstd * lg[q] + lb[q]);
;             u32x2 wv; wv.x = pk2(o[0], o[1]); wv.y = pk2(o[2], o[3]); *(LAS u32x2*)(A + t * 528 + lane * 8) = wv; }
	v_pk_add_f32 v[150:151], v[150:151], v[152:153]
	v_add_f32_e32 v101, 1.0, v101
	v_pk_mul_f32 v[150:151], v[150:151], s[80:81] op_sel_hi:[1,0]
	v_pk_mul_f32 v[102:103], v[102:103], v[154:155] op_sel_hi:[1,0]
	v_fma_f32 v113, -v151, v151, v150
	v_cvt_pk_bf16_f32 v107, v168, v169
	v_rcp_f32_e32 v168, v101
	v_add_f32_e32 v101, 1.0, v105
	v_pk_fma_f32 v[102:103], v[70:71], v[102:103], v[74:75]
	v_max_f32_e32 v113, 0, v113
	v_rcp_f32_e32 v169, v101
	v_mul_f32_e32 v101, 0xbfb8aa3b, v102
	v_add_f32_e32 v113, 0x358637bd, v113
	v_exp_f32_e32 v101, v101
	v_mul_f32_e32 v105, 0xbfb8aa3b, v103
	v_mul_f32_e32 v115, 0x4f800000, v113
	v_cmp_gt_f32_e32 vcc, s67, v113
	v_exp_f32_e32 v105, v105
	v_add_f32_e32 v101, 1.0, v101
	v_cndmask_b32_e32 v113, v113, v115, vcc
	v_sqrt_f32_e32 v115, v113
	v_rcp_f32_e32 v152, v101
	v_add_f32_e32 v101, 1.0, v105
	v_rcp_f32_e32 v153, v101
	v_add_u32_e32 v101, -1, v115
	v_fma_f32 v105, -v101, v115, v113
	v_cmp_ge_f32_e64 s[2:3], 0, v105
	v_add_u32_e32 v105, 1, v115
	v_pk_mul_f32 v[102:103], v[102:103], v[152:153]
	v_cndmask_b32_e64 v101, v115, v101, s[2:3]
	v_fma_f32 v115, -v105, v115, v113
	v_cmp_lt_f32_e64 s[2:3], 0, v115
	v_mul_f32_e32 v146, v92, v92
	v_mul_f32_e32 v148, v93, v93
	v_cndmask_b32_e64 v101, v101, v105, s[2:3]
	v_mul_f32_e32 v105, 0x37800000, v101
	v_cndmask_b32_e32 v101, v101, v105, vcc
	v_cmp_class_f32_e32 vcc, v113, v196
	v_mul_f32_e32 v142, v94, v94
	v_mul_f32_e32 v144, v95, v95
	v_cndmask_b32_e32 v101, v101, v113, vcc
	v_div_scale_f32 v105, s[0:1], v101, v101, 1.0
	v_rcp_f32_e32 v113, v105
	v_cvt_pk_bf16_f32 v153, v102, v103
	v_mov_b32_e32 v147, v92
	v_mov_b32_e32 v149, v93
	v_fma_f32 v102, -v105, v113, 1.0
	v_mov_b32_e32 v143, v94
	v_mov_b32_e32 v145, v95
	v_fmac_f32_e32 v113, v102, v113
	v_pk_add_f32 v[102:103], v[146:147], v[148:149]
	v_pk_add_f32 v[142:143], v[142:143], v[144:145]
	v_div_scale_f32 v115, vcc, 1.0, v101, 1.0
	v_pk_add_f32 v[102:103], v[102:103], v[142:143]
	s_nop 1
	v_mov_b32_dpp v143, v103 quad_perm:[1,0,3,2] row_mask:0xf bank_mask:0xf
	v_mov_b32_dpp v142, v102 quad_perm:[1,0,3,2] row_mask:0xf bank_mask:0xf
	v_mul_f32_e32 v117, v115, v113
	v_fma_f32 v119, -v105, v117, v115
	v_fmac_f32_e32 v117, v119, v113
	v_fma_f32 v105, -v105, v117, v115
	s_waitcnt lgkmcnt(0)
	v_pk_add_f32 v[102:103], v[102:103], v[142:143]
	s_nop 1
	v_mov_b32_dpp v143, v103 quad_perm:[2,3,0,1] row_mask:0xf bank_mask:0xf
	v_mov_b32_dpp v142, v102 quad_perm:[2,3,0,1] row_mask:0xf bank_mask:0xf
	v_div_fmas_f32 v105, v105, v113, v117
	v_div_fixup_f32 v144, v105, v101, 1.0
	v_pk_add_f32 v[96:97], v[96:97], v[150:151] op_sel:[0,1] neg_lo:[0,1] neg_hi:[0,1]
	v_pk_add_f32 v[98:99], v[98:99], v[150:151] op_sel:[0,1] neg_lo:[0,1] neg_hi:[0,1]
	s_waitcnt lgkmcnt(0)
	v_pk_add_f32 v[102:103], v[102:103], v[142:143]
	s_nop 1
	v_mov_b32_dpp v143, v103 row_half_mirror row_mask:0xf bank_mask:0xf
	v_mov_b32_dpp v142, v102 row_half_mirror row_mask:0xf bank_mask:0xf
	v_pk_mul_f32 v[96:97], v[96:97], v[144:145] op_sel_hi:[1,0]
	v_pk_mul_f32 v[98:99], v[98:99], v[144:145] op_sel_hi:[1,0]
	v_pk_fma_f32 v[96:97], v[68:69], v[96:97], v[72:73]
	v_pk_fma_f32 v[98:99], v[70:71], v[98:99], v[74:75]
	s_waitcnt lgkmcnt(0)
	v_pk_add_f32 v[102:103], v[102:103], v[142:143]
	s_nop 1
	v_mov_b32_dpp v143, v103 row_ror:8 row_mask:0xf bank_mask:0xf
	v_mov_b32_dpp v142, v102 row_ror:8 row_mask:0xf bank_mask:0xf
	v_mul_f32_e32 v101, 0xbfb8aa3b, v96
	v_exp_f32_e32 v101, v101
	v_mul_f32_e32 v105, 0xbfb8aa3b, v97
	v_exp_f32_e32 v105, v105
	s_waitcnt lgkmcnt(0)
	v_pk_add_f32 v[102:103], v[102:103], v[142:143]
	v_mov_b32_e32 v143, v103
	v_mov_b32_e32 v254, v103
	s_nop 1
	v_permlane16_swap_b32_e32 v143, v254
	s_nop 1
	v_mov_b32_dpp v143, v254 quad_perm:[0,1,2,3] row_mask:0x5 bank_mask:0xf
	v_mov_b32_e32 v142, v102
	v_mov_b32_e32 v255, v102
	s_nop 1
	v_permlane16_swap_b32_e32 v142, v255
	s_nop 1
	v_mov_b32_dpp v142, v255 quad_perm:[0,1,2,3] row_mask:0x5 bank_mask:0xf
	v_add_f32_e32 v101, 1.0, v101
	v_rcp_f32_e32 v146, v101
	v_add_f32_e32 v101, 1.0, v105
	v_mul_f32_e32 v105, 0xbfb8aa3b, v98
	s_waitcnt lgkmcnt(0)
	v_pk_add_f32 v[102:103], v[102:103], v[142:143]
	v_mov_b32_e32 v143, v103
	v_mov_b32_e32 v254, v103
	s_nop 1
	v_permlane32_swap_b32_e32 v143, v254
	s_nop 1
	v_mov_b32_dpp v143, v254 quad_perm:[0,1,2,3] row_mask:0x3 bank_mask:0xf
	v_mov_b32_e32 v142, v102
	v_mov_b32_e32 v255, v102
	s_nop 1
	v_permlane32_swap_b32_e32 v142, v255
	s_nop 1
	v_mov_b32_dpp v142, v255 quad_perm:[0,1,2,3] row_mask:0x3 bank_mask:0xf
	v_exp_f32_e32 v105, v105
	v_rcp_f32_e32 v147, v101
	v_pk_mul_f32 v[170:171], v[172:173], v[176:177]
	v_pk_mul_f32 v[154:155], v[156:157], v[168:169]
	s_waitcnt lgkmcnt(0)
; #define LAS __attribute__((address_space(3)))
; DI unsigned pk2(float lo, float hi) { const f32x2 v = {lo, hi}; return __builtin_bit_cast(unsigned, __builtin_convertvector(v, hwbf16x2)); }
; DI float siluf_(float x) { return x * sigmoidf_(x); }
; template <int N> DI void wave_sum_n(float (&v)[N]) {
; #pragma unroll
;     for (int o = 1; o < 64; o <<= 1) {
;         float t[N];
; #pragma unroll
;         for (int i = 0; i < N; ++i) t[i] = __shfl_xor(v[i], o);
; #pragma unroll
;         for (int i = 0; i < N; ++i) v[i] += t[i]; }
; DI void conv_unit(const Args& a, const Frame& F, int l, int unit) {
;     ...
; #pragma unroll
;         for (int r = 0; r < 8; ++r) { v[r] = *(const LAS f32x4*)(Y + (8 * F.wave + r) * 260 + 4 * lane);
;             st[r] = (v[r][0] + v[r][1]) + (v[r][2] + v[r][3]); st[8 + r] = (v[r][0] * v[r][0] + v[r][1] * v[r][1]) + (v[r][2] * v[r][2] + v[r][3] * v[r][3]); }
;         wave_sum_n<16>(st);
; #pragma unroll
;         for (int r = 0; r < 8; ++r) { const int t = 8 * F.wave + r; const float mu = st[r] * (1.f / 256.f); const float var = fmaxf(st[8 + r] * (1.f / 256.f) - mu * mu, 0.f); const float rstd = 1.f / sqrtf(var + EPS);
;             f32x4 o;
; #pragma unroll
;             for (int q = 0; q < 4; ++q) o[q] = siluf_((v[r][q] - mu) * rstd * lg[q] + lb[q]);
;             u32x2 wv; wv.x = pk2(o[0], o[1]); wv.y = pk2(o[2], o[3]); *(LAS u32x2*)(A + t * 528 + lane * 8) = wv; }
	v_pk_add_f32 v[102:103], v[102:103], v[142:143]
	v_add_f32_e32 v101, 1.0, v105
	v_pk_mul_f32 v[102:103], v[102:103], s[80:81] op_sel_hi:[1,0]
	v_mul_f32_e32 v105, 0xbfb8aa3b, v99
	v_fma_f32 v113, -v103, v103, v102
	v_max_f32_e32 v113, 0, v113
	v_add_f32_e32 v113, 0x358637bd, v113
	v_mul_f32_e32 v115, 0x4f800000, v113
	v_cmp_gt_f32_e32 vcc, s67, v113
	v_exp_f32_e32 v105, v105
	v_rcp_f32_e32 v142, v101
	v_cndmask_b32_e32 v113, v113, v115, vcc
	v_sqrt_f32_e32 v115, v113
	v_add_f32_e32 v101, 1.0, v105
	v_rcp_f32_e32 v143, v101
	v_cvt_pk_bf16_f32 v106, v170, v171
	v_add_u32_e32 v101, -1, v115
	v_fma_f32 v105, -v101, v115, v113
	v_cmp_ge_f32_e64 s[2:3], 0, v105
	v_add_u32_e32 v105, 1, v115
	v_lshl_add_u32 v100, v108, 3, s22
	v_cndmask_b32_e64 v101, v115, v101, s[2:3]
	v_fma_f32 v115, -v105, v115, v113
	v_cmp_lt_f32_e64 s[2:3], 0, v115
	v_cvt_pk_bf16_f32 v152, v154, v155
	ds_read_b128 v[76:79], v116 offset:55392
	ds_read_b128 v[80:83], v116 offset:56432
	v_cndmask_b32_e64 v101, v101, v105, s[2:3]
	v_mul_f32_e32 v105, 0x37800000, v101
	v_cndmask_b32_e32 v101, v101, v105, vcc
	v_cmp_class_f32_e32 vcc, v113, v196
	ds_write2_b64 v100, v[106:107], v[152:153] offset1:66
	v_mul_f32_e32 v138, v88, v88
	v_cndmask_b32_e32 v101, v101, v113, vcc
	v_div_scale_f32 v105, s[0:1], v101, v101, 1.0
	v_rcp_f32_e32 v113, v105
	v_mul_f32_e32 v140, v89, v89
	v_mul_f32_e32 v134, v90, v90
	v_mul_f32_e32 v136, v91, v91
	v_fma_f32 v106, -v105, v113, 1.0
	v_fmac_f32_e32 v113, v106, v113
	v_div_scale_f32 v106, vcc, 1.0, v101, 1.0
	v_mul_f32_e32 v107, v106, v113
	v_fma_f32 v115, -v105, v107, v106
	v_fmac_f32_e32 v107, v115, v113
	v_fma_f32 v105, -v105, v107, v106
	v_mov_b32_e32 v139, v88
	v_mov_b32_e32 v141, v89
	v_mov_b32_e32 v135, v90
	v_mov_b32_e32 v137, v91
	v_div_fmas_f32 v105, v105, v113, v107
	v_pk_add_f32 v[106:107], v[138:139], v[140:141]
	v_pk_add_f32 v[134:135], v[134:135], v[136:137]
	v_div_fixup_f32 v136, v105, v101, 1.0
	v_pk_add_f32 v[106:107], v[106:107], v[134:135]
	s_nop 1
	v_mov_b32_dpp v135, v107 quad_perm:[1,0,3,2] row_mask:0xf bank_mask:0xf
	v_mov_b32_dpp v134, v106 quad_perm:[1,0,3,2] row_mask:0xf bank_mask:0xf
	v_pk_add_f32 v[92:93], v[92:93], v[102:103] op_sel:[0,1] neg_lo:[0,1] neg_hi:[0,1]
	v_pk_add_f32 v[94:95], v[94:95], v[102:103] op_sel:[0,1] neg_lo:[0,1] neg_hi:[0,1]
	v_pk_mul_f32 v[92:93], v[92:93], v[136:137] op_sel_hi:[1,0]
	v_pk_mul_f32 v[96:97], v[96:97], v[146:147]
	s_waitcnt lgkmcnt(0)
	v_pk_add_f32 v[106:107], v[106:107], v[134:135]
	s_nop 1
	v_mov_b32_dpp v135, v107 quad_perm:[2,3,0,1] row_mask:0xf bank_mask:0xf
	v_mov_b32_dpp v134, v106 quad_perm:[2,3,0,1] row_mask:0xf bank_mask:0xf
	v_pk_fma_f32 v[92:93], v[68:69], v[92:93], v[72:73]
	v_cvt_pk_bf16_f32 v96, v96, v97
	v_mul_f32_e32 v101, 0xbfb8aa3b, v92
	v_exp_f32_e32 v101, v101
	s_waitcnt lgkmcnt(0)
	v_pk_add_f32 v[106:107], v[106:107], v[134:135]
	s_nop 1
	v_mov_b32_dpp v135, v107 row_half_mirror row_mask:0xf bank_mask:0xf
	v_mov_b32_dpp v134, v106 row_half_mirror row_mask:0xf bank_mask:0xf
	v_mul_f32_e32 v105, 0xbfb8aa3b, v93
	v_exp_f32_e32 v105, v105
	v_add_f32_e32 v97, 1.0, v101
	v_pk_mul_f32 v[94:95], v[94:95], v[136:137] op_sel_hi:[1,0]
	s_waitcnt lgkmcnt(0)
	v_pk_add_f32 v[106:107], v[106:107], v[134:135]
	s_nop 1
	v_mov_b32_dpp v135, v107 row_ror:8 row_mask:0xf bank_mask:0xf
	v_mov_b32_dpp v134, v106 row_ror:8 row_mask:0xf bank_mask:0xf
	v_rcp_f32_e32 v138, v97
	v_add_f32_e32 v97, 1.0, v105
	v_pk_fma_f32 v[94:95], v[70:71], v[94:95], v[74:75]
	v_rcp_f32_e32 v139, v97
	s_waitcnt lgkmcnt(0)
	v_pk_add_f32 v[102:103], v[106:107], v[134:135]
	v_mov_b32_e32 v107, v103
	v_mov_b32_e32 v254, v103
	s_nop 1
	v_permlane16_swap_b32_e32 v107, v254
	s_nop 1
	v_mov_b32_dpp v107, v254 quad_perm:[0,1,2,3] row_mask:0x5 bank_mask:0xf
	v_mov_b32_e32 v106, v102
	v_mov_b32_e32 v255, v102
	s_nop 1
	v_permlane16_swap_b32_e32 v106, v255
	s_nop 1
	v_mov_b32_dpp v106, v255 quad_perm:[0,1,2,3] row_mask:0x5 bank_mask:0xf
	v_mul_f32_e32 v97, 0xbfb8aa3b, v94
	v_exp_f32_e32 v97, v97
	v_mul_f32_e32 v101, 0xbfb8aa3b, v95
	v_exp_f32_e32 v101, v101
	s_waitcnt lgkmcnt(0)
	v_pk_add_f32 v[102:103], v[102:103], v[106:107]
	v_mov_b32_e32 v107, v103
	v_mov_b32_e32 v254, v103
	s_nop 1
	v_permlane32_swap_b32_e32 v107, v254
	s_nop 1
	v_mov_b32_dpp v107, v254 quad_perm:[0,1,2,3] row_mask:0x3 bank_mask:0xf
	v_mov_b32_e32 v106, v102
	v_mov_b32_e32 v255, v102
	s_nop 1
	v_permlane32_swap_b32_e32 v106, v255
	s_nop 1
	v_mov_b32_dpp v106, v255 quad_perm:[0,1,2,3] row_mask:0x3 bank_mask:0xf
	v_add_f32_e32 v97, 1.0, v97
	v_rcp_f32_e32 v134, v97
	v_add_f32_e32 v97, 1.0, v101
	v_rcp_f32_e32 v135, v97
	s_waitcnt lgkmcnt(0)
	v_pk_add_f32 v[102:103], v[102:103], v[106:107]
	v_pk_mul_f32 v[98:99], v[98:99], v[142:143]
	v_pk_mul_f32 v[102:103], v[102:103], s[80:81] op_sel_hi:[1,0]
	v_pk_mul_f32 v[92:93], v[92:93], v[138:139]
	v_fma_f32 v97, -v103, v103, v102
	v_max_f32_e32 v97, 0, v97
	v_add_f32_e32 v97, 0x358637bd, v97
	v_mul_f32_e32 v101, 0x4f800000, v97
	v_cmp_gt_f32_e32 vcc, s67, v97
	v_pk_mul_f32 v[94:95], v[94:95], v[134:135]
	v_cvt_pk_bf16_f32 v92, v92, v93
	v_cndmask_b32_e32 v101, v97, v101, vcc
	v_sqrt_f32_e32 v105, v101
	v_cvt_pk_bf16_f32 v97, v98, v99
	v_cvt_pk_bf16_f32 v93, v94, v95
	v_mul_f32_e32 v126, v84, v84
	v_add_u32_e32 v98, -1, v105
	v_fma_f32 v99, -v98, v105, v101
	v_cmp_ge_f32_e64 s[2:3], 0, v99
	v_add_u32_e32 v99, 1, v105
	v_mul_f32_e32 v128, v85, v85
	v_cndmask_b32_e64 v98, v105, v98, s[2:3]
	v_fma_f32 v105, -v99, v105, v101
	v_cmp_lt_f32_e64 s[2:3], 0, v105
	v_mul_f32_e32 v130, v86, v86
	v_mul_f32_e32 v132, v87, v87
	v_cndmask_b32_e64 v98, v98, v99, s[2:3]
	v_mul_f32_e32 v99, 0x37800000, v98
	v_cndmask_b32_e32 v98, v98, v99, vcc
	v_cmp_class_f32_e32 vcc, v101, v196
	ds_write2_b64 v100, v[96:97], v[92:93] offset0:132 offset1:198
	v_mov_b32_e32 v127, v84
	v_cndmask_b32_e32 v98, v98, v101, vcc
	v_div_scale_f32 v99, s[0:1], v98, v98, 1.0
	v_rcp_f32_e32 v101, v99
	v_mov_b32_e32 v129, v85
	v_mov_b32_e32 v131, v86
	v_mov_b32_e32 v133, v87
	v_fma_f32 v92, -v99, v101, 1.0
	v_fmac_f32_e32 v101, v92, v101
	v_pk_add_f32 v[92:93], v[126:127], v[128:129]
	v_pk_add_f32 v[94:95], v[130:131], v[132:133]
	v_div_scale_f32 v96, vcc, 1.0, v98, 1.0
	v_pk_add_f32 v[92:93], v[92:93], v[94:95]
	s_nop 1
	v_mov_b32_dpp v95, v93 quad_perm:[1,0,3,2] row_mask:0xf bank_mask:0xf
	v_mov_b32_dpp v94, v92 quad_perm:[1,0,3,2] row_mask:0xf bank_mask:0xf
	v_mul_f32_e32 v97, v96, v101
	v_fma_f32 v105, -v99, v97, v96
	v_fmac_f32_e32 v97, v105, v101
	v_fma_f32 v96, -v99, v97, v96
	s_waitcnt lgkmcnt(0)
; #define LAS __attribute__((address_space(3)))
; DI unsigned pk2(float lo, float hi) { const f32x2 v = {lo, hi}; return __builtin_bit_cast(unsigned, __builtin_convertvector(v, hwbf16x2)); }
; DI float siluf_(float x) { return x * sigmoidf_(x); }
; template <int N> DI void wave_sum_n(float (&v)[N]) {
; #pragma unroll
;     for (int o = 1; o < 64; o <<= 1) {
;         float t[N];
; #pragma unroll
;         for (int i = 0; i < N; ++i) t[i] = __shfl_xor(v[i], o);
; #pragma unroll
;         for (int i = 0; i < N; ++i) v[i] += t[i]; }
; DI void conv_unit(const Args& a, const Frame& F, int l, int unit) {
;     ...
; #pragma unroll
;         for (int r = 0; r < 8; ++r) { v[r] = *(const LAS f32x4*)(Y + (8 * F.wave + r) * 260 + 4 * lane);
;             st[r] = (v[r][0] + v[r][1]) + (v[r][2] + v[r][3]); st[8 + r] = (v[r][0] * v[r][0] + v[r][1] * v[r][1]) + (v[r][2] * v[r][2] + v[r][3] * v[r][3]); }
;         wave_sum_n<16>(st);
; #pragma unroll
;         for (int r = 0; r < 8; ++r) { const int t = 8 * F.wave + r; const float mu = st[r] * (1.f / 256.f); const float var = fmaxf(st[8 + r] * (1.f / 256.f) - mu * mu, 0.f); const float rstd = 1.f / sqrtf(var + EPS);
;             f32x4 o;
; #pragma unroll
;             for (int q = 0; q < 4; ++q) o[q] = siluf_((v[r][q] - mu) * rstd * lg[q] + lb[q]);
;             u32x2 wv; wv.x = pk2(o[0], o[1]); wv.y = pk2(o[2], o[3]); *(LAS u32x2*)(A + t * 528 + lane * 8) = wv; }
	v_pk_add_f32 v[92:93], v[92:93], v[94:95]
	s_nop 1
	v_mov_b32_dpp v95, v93 quad_perm:[2,3,0,1] row_mask:0xf bank_mask:0xf
	v_mov_b32_dpp v94, v92 quad_perm:[2,3,0,1] row_mask:0xf bank_mask:0xf
	v_div_fmas_f32 v96, v96, v101, v97
	v_div_fixup_f32 v96, v96, v98, 1.0
	v_pk_add_f32 v[88:89], v[88:89], v[102:103] op_sel:[0,1] neg_lo:[0,1] neg_hi:[0,1]
	v_pk_add_f32 v[90:91], v[90:91], v[102:103] op_sel:[0,1] neg_lo:[0,1] neg_hi:[0,1]
	s_waitcnt lgkmcnt(0)
	v_pk_add_f32 v[92:93], v[92:93], v[94:95]
	s_nop 1
	v_mov_b32_dpp v95, v93 row_half_mirror row_mask:0xf bank_mask:0xf
	v_mov_b32_dpp v94, v92 row_half_mirror row_mask:0xf bank_mask:0xf
	v_pk_mul_f32 v[88:89], v[88:89], v[96:97] op_sel_hi:[1,0]
	v_mul_f32_e32 v118, v76, v76
	v_pk_fma_f32 v[88:89], v[68:69], v[88:89], v[72:73]
	v_mul_f32_e32 v124, v77, v77
	s_waitcnt lgkmcnt(0)
	v_pk_add_f32 v[92:93], v[92:93], v[94:95]
	s_nop 1
	v_mov_b32_dpp v95, v93 row_ror:8 row_mask:0xf bank_mask:0xf
	v_mov_b32_dpp v94, v92 row_ror:8 row_mask:0xf bank_mask:0xf
	v_mul_f32_e32 v97, 0xbfb8aa3b, v88
	v_exp_f32_e32 v97, v97
	v_mul_f32_e32 v98, 0xbfb8aa3b, v89
	v_exp_f32_e32 v99, v98
	s_waitcnt lgkmcnt(0)
	v_pk_add_f32 v[92:93], v[92:93], v[94:95]
	v_mov_b32_e32 v95, v93
	v_mov_b32_e32 v254, v93
	s_nop 1
	v_permlane16_swap_b32_e32 v95, v254
	s_nop 1
	v_mov_b32_dpp v95, v254 quad_perm:[0,1,2,3] row_mask:0x5 bank_mask:0xf
	v_mov_b32_e32 v94, v92
	v_mov_b32_e32 v255, v92
	s_nop 1
	v_permlane16_swap_b32_e32 v94, v255
	s_nop 1
	v_mov_b32_dpp v94, v255 quad_perm:[0,1,2,3] row_mask:0x5 bank_mask:0xf
	v_add_f32_e32 v97, 1.0, v97
	v_rcp_f32_e32 v98, v97
	v_add_f32_e32 v97, 1.0, v99
	v_pk_mul_f32 v[90:91], v[90:91], v[96:97] op_sel_hi:[1,0]
	s_waitcnt lgkmcnt(0)
	v_pk_add_f32 v[92:93], v[92:93], v[94:95]
	v_mov_b32_e32 v95, v93
	v_mov_b32_e32 v254, v93
	s_nop 1
	v_permlane32_swap_b32_e32 v95, v254
	s_nop 1
	v_mov_b32_dpp v95, v254 quad_perm:[0,1,2,3] row_mask:0x3 bank_mask:0xf
	v_mov_b32_e32 v94, v92
	v_mov_b32_e32 v255, v92
	s_nop 1
	v_permlane32_swap_b32_e32 v94, v255
	s_nop 1
	v_mov_b32_dpp v94, v255 quad_perm:[0,1,2,3] row_mask:0x3 bank_mask:0xf
	v_pk_fma_f32 v[90:91], v[70:71], v[90:91], v[74:75]
	v_rcp_f32_e32 v99, v97
	v_mul_f32_e32 v96, 0xbfb8aa3b, v90
	v_exp_f32_e32 v96, v96
	s_waitcnt lgkmcnt(0)
	v_pk_add_f32 v[92:93], v[92:93], v[94:95]
	v_mul_f32_e32 v97, 0xbfb8aa3b, v91
	v_pk_mul_f32 v[92:93], v[92:93], s[80:81] op_sel_hi:[1,0]
	v_exp_f32_e32 v97, v97
	v_fma_f32 v94, -v93, v93, v92
	v_max_f32_e32 v94, 0, v94
	v_add_f32_e32 v94, 0x358637bd, v94
	v_mul_f32_e32 v95, 0x4f800000, v94
	v_cmp_gt_f32_e32 vcc, s67, v94
	v_add_f32_e32 v96, 1.0, v96
	v_pk_mul_f32 v[88:89], v[88:89], v[98:99]
	v_cndmask_b32_e32 v101, v94, v95, vcc
	v_sqrt_f32_e32 v102, v101
	v_rcp_f32_e32 v94, v96
	v_add_f32_e32 v95, 1.0, v97
	v_rcp_f32_e32 v95, v95
	v_add_u32_e32 v96, -1, v102
	v_fma_f32 v97, -v96, v102, v101
	v_cmp_ge_f32_e64 s[2:3], 0, v97
	v_add_u32_e32 v97, 1, v102
	v_cvt_pk_bf16_f32 v88, v88, v89
	v_cndmask_b32_e64 v96, v102, v96, s[2:3]
	v_fma_f32 v102, -v97, v102, v101
	v_cmp_lt_f32_e64 s[2:3], 0, v102
	v_pk_mul_f32 v[90:91], v[90:91], v[94:95]
	v_mul_f32_e32 v120, v78, v78
	v_cndmask_b32_e64 v96, v96, v97, s[2:3]
	v_mul_f32_e32 v97, 0x37800000, v96
	v_cndmask_b32_e32 v96, v96, v97, vcc
	v_cmp_class_f32_e32 vcc, v101, v196
	v_mul_f32_e32 v122, v79, v79
	v_mov_b32_e32 v119, v76
	v_cndmask_b32_e32 v101, v96, v101, vcc
	v_div_scale_f32 v96, s[0:1], v101, v101, 1.0
	v_rcp_f32_e32 v102, v96
	v_mov_b32_e32 v125, v77
	v_mov_b32_e32 v121, v78
	v_mov_b32_e32 v123, v79
	v_fma_f32 v89, -v96, v102, 1.0
	v_fmac_f32_e32 v102, v89, v102
	v_div_scale_f32 v89, vcc, 1.0, v101, 1.0
	v_mul_f32_e32 v98, v89, v102
	v_fma_f32 v94, -v96, v98, v89
	v_fmac_f32_e32 v98, v94, v102
	v_fma_f32 v89, -v96, v98, v89
	v_pk_add_f32 v[94:95], v[118:119], v[124:125]
	v_pk_add_f32 v[96:97], v[120:121], v[122:123]
	v_div_fmas_f32 v89, v89, v102, v98
	v_pk_add_f32 v[94:95], v[94:95], v[96:97]
	s_nop 1
	v_mov_b32_dpp v97, v95 quad_perm:[1,0,3,2] row_mask:0xf bank_mask:0xf
	v_mov_b32_dpp v96, v94 quad_perm:[1,0,3,2] row_mask:0xf bank_mask:0xf
	v_div_fixup_f32 v98, v89, v101, 1.0
	v_pk_add_f32 v[84:85], v[84:85], v[92:93] op_sel:[0,1] neg_lo:[0,1] neg_hi:[0,1]
	v_pk_add_f32 v[86:87], v[86:87], v[92:93] op_sel:[0,1] neg_lo:[0,1] neg_hi:[0,1]
	v_pk_mul_f32 v[84:85], v[84:85], v[98:99] op_sel_hi:[1,0]
	s_waitcnt lgkmcnt(0)
	v_pk_add_f32 v[94:95], v[94:95], v[96:97]
	s_nop 1
	v_mov_b32_dpp v97, v95 quad_perm:[2,3,0,1] row_mask:0xf bank_mask:0xf
	v_mov_b32_dpp v96, v94 quad_perm:[2,3,0,1] row_mask:0xf bank_mask:0xf
	v_pk_fma_f32 v[84:85], v[68:69], v[84:85], v[72:73]
	v_mul_f32_e32 v114, v80, v80
	v_mul_f32_e32 v89, 0xbfb8aa3b, v84
	v_exp_f32_e32 v99, v89
	s_waitcnt lgkmcnt(0)
	v_pk_add_f32 v[94:95], v[94:95], v[96:97]
	s_nop 1
	v_mov_b32_dpp v97, v95 row_half_mirror row_mask:0xf bank_mask:0xf
	v_mov_b32_dpp v96, v94 row_half_mirror row_mask:0xf bank_mask:0xf
	v_cvt_pk_bf16_f32 v89, v90, v91
	v_mul_f32_e32 v90, 0xbfb8aa3b, v85
	v_exp_f32_e32 v101, v90
	v_add_f32_e32 v99, 1.0, v99
	s_waitcnt lgkmcnt(0)
	v_pk_add_f32 v[90:91], v[94:95], v[96:97]
	s_nop 1
	v_mov_b32_dpp v95, v91 row_ror:8 row_mask:0xf bank_mask:0xf
	v_mov_b32_dpp v94, v90 row_ror:8 row_mask:0xf bank_mask:0xf
	v_add_f32_e32 v97, 1.0, v101
	v_rcp_f32_e32 v96, v99
	v_rcp_f32_e32 v97, v97
	v_pk_mul_f32 v[86:87], v[86:87], v[98:99] op_sel_hi:[1,0]
	s_waitcnt lgkmcnt(0)
; #define LAS __attribute__((address_space(3)))
; DI unsigned pk2(float lo, float hi) { const f32x2 v = {lo, hi}; return __builtin_bit_cast(unsigned, __builtin_convertvector(v, hwbf16x2)); }
; DI float siluf_(float x) { return x * sigmoidf_(x); }
; template <int N> DI void wave_sum_n(float (&v)[N]) {
; #pragma unroll
;     for (int o = 1; o < 64; o <<= 1) {
;         float t[N];
; #pragma unroll
;         for (int i = 0; i < N; ++i) t[i] = __shfl_xor(v[i], o);
; #pragma unroll
;         for (int i = 0; i < N; ++i) v[i] += t[i]; }
; DI void conv_unit(const Args& a, const Frame& F, int l, int unit) {
;     ...
; #pragma unroll
;         for (int r = 0; r < 8; ++r) { v[r] = *(const LAS f32x4*)(Y + (8 * F.wave + r) * 260 + 4 * lane);
;             st[r] = (v[r][0] + v[r][1]) + (v[r][2] + v[r][3]); st[8 + r] = (v[r][0] * v[r][0] + v[r][1] * v[r][1]) + (v[r][2] * v[r][2] + v[r][3] * v[r][3]); }
;         wave_sum_n<16>(st);
; #pragma unroll
;         for (int r = 0; r < 8; ++r) { const int t = 8 * F.wave + r; const float mu = st[r] * (1.f / 256.f); const float var = fmaxf(st[8 + r] * (1.f / 256.f) - mu * mu, 0.f); const float rstd = 1.f / sqrtf(var + EPS);
;             f32x4 o;
; #pragma unroll
;             for (int q = 0; q < 4; ++q) o[q] = siluf_((v[r][q] - mu) * rstd * lg[q] + lb[q]);
;             u32x2 wv; wv.x = pk2(o[0], o[1]); wv.y = pk2(o[2], o[3]); *(LAS u32x2*)(A + t * 528 + lane * 8) = wv; }
	v_pk_add_f32 v[90:91], v[90:91], v[94:95]
	v_mov_b32_e32 v93, v91
	v_mov_b32_e32 v254, v91
	s_nop 1
	v_permlane16_swap_b32_e32 v93, v254
	s_nop 1
	v_mov_b32_dpp v93, v254 quad_perm:[0,1,2,3] row_mask:0x5 bank_mask:0xf
	v_mov_b32_e32 v92, v90
	v_mov_b32_e32 v255, v90
	s_nop 1
	v_permlane16_swap_b32_e32 v92, v255
	s_nop 1
	v_mov_b32_dpp v92, v255 quad_perm:[0,1,2,3] row_mask:0x5 bank_mask:0xf
	v_pk_fma_f32 v[86:87], v[70:71], v[86:87], v[74:75]
	v_pk_mul_f32 v[84:85], v[84:85], v[96:97]
	v_mul_f32_e32 v94, 0xbfb8aa3b, v86
	v_exp_f32_e32 v94, v94
	s_waitcnt lgkmcnt(0)
	v_pk_add_f32 v[90:91], v[90:91], v[92:93]
	v_mov_b32_e32 v93, v91
	v_mov_b32_e32 v254, v91
	s_nop 1
	v_permlane32_swap_b32_e32 v93, v254
	s_nop 1
	v_mov_b32_dpp v93, v254 quad_perm:[0,1,2,3] row_mask:0x3 bank_mask:0xf
	v_mov_b32_e32 v92, v90
	v_mov_b32_e32 v255, v90
	s_nop 1
	v_permlane32_swap_b32_e32 v92, v255
	s_nop 1
	v_mov_b32_dpp v92, v255 quad_perm:[0,1,2,3] row_mask:0x3 bank_mask:0xf
	v_mul_f32_e32 v95, 0xbfb8aa3b, v87
	v_exp_f32_e32 v95, v95
	v_add_f32_e32 v94, 1.0, v94
	v_mul_f32_e32 v116, v81, v81
	s_waitcnt lgkmcnt(0)
	v_pk_add_f32 v[90:91], v[90:91], v[92:93]
	v_mul_f32_e32 v112, v82, v82
	v_pk_mul_f32 v[90:91], v[90:91], s[80:81] op_sel_hi:[1,0]
	v_mul_f32_e32 v104, v83, v83
	v_fma_f32 v92, -v91, v91, v90
	v_max_f32_e32 v92, 0, v92
	v_add_f32_e32 v92, 0x358637bd, v92
	v_mul_f32_e32 v93, 0x4f800000, v92
	v_cmp_gt_f32_e32 vcc, s67, v92
	v_cvt_pk_bf16_f32 v84, v84, v85
	v_mov_b32_e32 v115, v80
	v_cndmask_b32_e32 v96, v92, v93, vcc
	v_sqrt_f32_e32 v97, v96
	v_rcp_f32_e32 v92, v94
	v_add_f32_e32 v93, 1.0, v95
	v_rcp_f32_e32 v93, v93
	v_add_u32_e32 v94, -1, v97
	v_fma_f32 v95, -v94, v97, v96
	v_cmp_ge_f32_e64 s[2:3], 0, v95
	v_add_u32_e32 v95, 1, v97
	v_pk_mul_f32 v[86:87], v[86:87], v[92:93]
	v_cndmask_b32_e64 v94, v97, v94, s[2:3]
	v_fma_f32 v97, -v95, v97, v96
	v_cmp_lt_f32_e64 s[2:3], 0, v97
	v_cvt_pk_bf16_f32 v85, v86, v87
	v_mov_b32_e32 v117, v81
	v_cndmask_b32_e64 v94, v94, v95, s[2:3]
	v_mul_f32_e32 v95, 0x37800000, v94
	v_cndmask_b32_e32 v94, v94, v95, vcc
	v_cmp_class_f32_e32 vcc, v96, v196
	v_mov_b32_e32 v113, v82
	v_mov_b32_e32 v105, v83
	v_cndmask_b32_e32 v94, v94, v96, vcc
	v_div_scale_f32 v95, s[0:1], v94, v94, 1.0
	v_rcp_f32_e32 v96, v95
	v_pk_add_f32 v[92:93], v[112:113], v[104:105]
	v_div_scale_f32 v97, vcc, 1.0, v94, 1.0
	v_fma_f32 v86, -v95, v96, 1.0
	v_fmac_f32_e32 v96, v86, v96
	v_pk_add_f32 v[86:87], v[114:115], v[116:117]
	v_mul_f32_e32 v98, v97, v96
	v_pk_add_f32 v[86:87], v[86:87], v[92:93]
	s_nop 1
	v_mov_b32_dpp v93, v87 quad_perm:[1,0,3,2] row_mask:0xf bank_mask:0xf
	v_mov_b32_dpp v92, v86 quad_perm:[1,0,3,2] row_mask:0xf bank_mask:0xf
	v_fma_f32 v99, -v95, v98, v97
	v_fmac_f32_e32 v98, v99, v96
	v_fma_f32 v95, -v95, v98, v97
	v_div_fmas_f32 v95, v95, v96, v98
	s_waitcnt lgkmcnt(0)
	v_pk_add_f32 v[86:87], v[86:87], v[92:93]
	s_nop 1
	v_mov_b32_dpp v93, v87 quad_perm:[2,3,0,1] row_mask:0xf bank_mask:0xf
	v_mov_b32_dpp v92, v86 quad_perm:[2,3,0,1] row_mask:0xf bank_mask:0xf
	v_div_fixup_f32 v94, v95, v94, 1.0
	v_pk_add_f32 v[76:77], v[76:77], v[90:91] op_sel:[0,1] neg_lo:[0,1] neg_hi:[0,1]
	v_pk_add_f32 v[78:79], v[78:79], v[90:91] op_sel:[0,1] neg_lo:[0,1] neg_hi:[0,1]
	v_pk_mul_f32 v[76:77], v[76:77], v[94:95] op_sel_hi:[1,0]
	s_waitcnt lgkmcnt(0)
	v_pk_add_f32 v[86:87], v[86:87], v[92:93]
	s_nop 1
	v_mov_b32_dpp v93, v87 row_half_mirror row_mask:0xf bank_mask:0xf
	v_mov_b32_dpp v92, v86 row_half_mirror row_mask:0xf bank_mask:0xf
	v_pk_fma_f32 v[76:77], v[68:69], v[76:77], v[72:73]
	s_waitcnt lgkmcnt(0)
	v_pk_add_f32 v[86:87], v[86:87], v[92:93]
	s_nop 1
	v_mov_b32_dpp v93, v87 row_ror:8 row_mask:0xf bank_mask:0xf
	v_mov_b32_dpp v92, v86 row_ror:8 row_mask:0xf bank_mask:0xf
	v_mul_f32_e32 v95, 0xbfb8aa3b, v76
	v_exp_f32_e32 v95, v95
	v_mul_f32_e32 v96, 0xbfb8aa3b, v77
	v_exp_f32_e32 v97, v96
	s_waitcnt lgkmcnt(0)
	v_pk_add_f32 v[86:87], v[86:87], v[92:93]
	v_mov_b32_e32 v93, v87
	v_mov_b32_e32 v254, v87
	s_nop 1
	v_permlane16_swap_b32_e32 v93, v254
	s_nop 1
	v_mov_b32_dpp v93, v254 quad_perm:[0,1,2,3] row_mask:0x5 bank_mask:0xf
	v_mov_b32_e32 v92, v86
	v_mov_b32_e32 v255, v86
	s_nop 1
	v_permlane16_swap_b32_e32 v92, v255
	s_nop 1
	v_mov_b32_dpp v92, v255 quad_perm:[0,1,2,3] row_mask:0x5 bank_mask:0xf
	v_add_f32_e32 v95, 1.0, v95
	v_rcp_f32_e32 v96, v95
	v_add_f32_e32 v95, 1.0, v97
	v_rcp_f32_e32 v97, v95
	v_add_u32_e32 v95, 0x800, v100
	ds_write2_b64 v95, v[88:89], v[84:85] offset0:8 offset1:74
	s_waitcnt lgkmcnt(1)
	v_pk_add_f32 v[84:85], v[86:87], v[92:93]
	v_mov_b32_e32 v87, v85
	v_mov_b32_e32 v254, v85
	s_nop 1
	v_permlane32_swap_b32_e32 v87, v254
	s_nop 1
	v_mov_b32_dpp v87, v254 quad_perm:[0,1,2,3] row_mask:0x3 bank_mask:0xf
	v_mov_b32_e32 v86, v84
	v_mov_b32_e32 v255, v84
	s_nop 1
	v_permlane32_swap_b32_e32 v86, v255
	s_nop 1
	v_mov_b32_dpp v86, v255 quad_perm:[0,1,2,3] row_mask:0x3 bank_mask:0xf
	v_pk_mul_f32 v[78:79], v[78:79], v[94:95] op_sel_hi:[1,0]
	v_pk_mul_f32 v[76:77], v[76:77], v[96:97]
	v_pk_fma_f32 v[78:79], v[70:71], v[78:79], v[74:75]
	v_cvt_pk_bf16_f32 v76, v76, v77
	s_waitcnt lgkmcnt(0)
; #define LAS __attribute__((address_space(3)))
; DI unsigned pk2(float lo, float hi) { const f32x2 v = {lo, hi}; return __builtin_bit_cast(unsigned, __builtin_convertvector(v, hwbf16x2)); }
; DI float siluf_(float x) { return x * sigmoidf_(x); }
; #define MFMA16(a, b, c) __builtin_amdgcn_mfma_f32_16x16x32_bf16((a), (b), (c), 0, 0, 0)
; DI void mm64_compute(const LAS unsigned char* A, int lda_b, const bf16x8 (&bfr)[2][8], int lane, f32x4 (&acc)[4][2]) {
;     const int fr = lane & 15, fq = lane >> 4;
; #pragma unroll
;     for (int rt = 0; rt < 4; ++rt) { acc[rt][0] = (f32x4){0.f, 0.f, 0.f, 0.f}; acc[rt][1] = (f32x4){0.f, 0.f, 0.f, 0.f}; }
; #pragma unroll
;     for (int rt = 0; rt < 4; ++rt)
;     {
;         bf16x8 af[8];
; #pragma unroll
;         for (int ks = 0; ks < 8; ++ks) af[ks] = ld8l(A + (16 * rt + fr) * lda_b + (32 * ks + 8 * fq) * 2);
; #pragma unroll
;         for (int ks = 0; ks < 8; ++ks) { acc[rt][0] = MFMA16(af[ks], bfr[0][ks], acc[rt][0]); acc[rt][1] = MFMA16(af[ks], bfr[1][ks], acc[rt][1]); }
;         __builtin_amdgcn_sched_barrier(0);
;     }
; }
; DI void conv_unit(const Args& a, const Frame& F, int l, int unit) {
;     ...
;         for (int r = 0; r < 8; ++r) { const int t = 8 * F.wave + r; const float mu = st[r] * (1.f / 256.f); const float var = fmaxf(st[8 + r] * (1.f / 256.f) - mu * mu, 0.f); const float rstd = 1.f / sqrtf(var + EPS);
;             f32x4 o;
; #pragma unroll
;             for (int q = 0; q < 4; ++q) o[q] = siluf_((v[r][q] - mu) * rstd * lg[q] + lb[q]);
;             u32x2 wv; wv.x = pk2(o[0], o[1]); wv.y = pk2(o[2], o[3]); *(LAS u32x2*)(A + t * 528 + lane * 8) = wv; }
;     }
;     __syncthreads();
;     f32x4 acc[4][2];
;     mm64_compute(F.lds + CV_A, 528, bfr, lane, acc);
	v_pk_add_f32 v[84:85], v[84:85], v[86:87]
	v_mul_f32_e32 v88, 0xbfb8aa3b, v78
	v_pk_mul_f32 v[84:85], v[84:85], s[80:81] op_sel_hi:[1,0]
	v_exp_f32_e32 v88, v88
	v_fma_f32 v86, -v85, v85, v84
	v_max_f32_e32 v86, 0, v86
	v_add_f32_e32 v86, 0x358637bd, v86
	v_mul_f32_e32 v87, 0x4f800000, v86
	v_cmp_gt_f32_e32 vcc, s67, v86
	v_mul_f32_e32 v89, 0xbfb8aa3b, v79
	v_exp_f32_e32 v89, v89
	v_cndmask_b32_e32 v86, v86, v87, vcc
	v_sqrt_f32_e32 v87, v86
	v_add_f32_e32 v88, 1.0, v88
	v_pk_add_f32 v[80:81], v[80:81], v[84:85] op_sel:[0,1] neg_lo:[0,1] neg_hi:[0,1]
	v_add_u32_e32 v90, -1, v87
	v_fma_f32 v91, -v90, v87, v86
	v_cmp_ge_f32_e64 s[2:3], 0, v91
	v_add_u32_e32 v91, 1, v87
	s_nop 0
	v_cndmask_b32_e64 v90, v87, v90, s[2:3]
	v_fma_f32 v87, -v91, v87, v86
	v_cmp_lt_f32_e64 s[2:3], 0, v87
	s_nop 1
	v_cndmask_b32_e64 v87, v90, v91, s[2:3]
	v_mul_f32_e32 v90, 0x37800000, v87
	v_cndmask_b32_e32 v87, v87, v90, vcc
	v_cmp_class_f32_e32 vcc, v86, v196
	s_nop 1
	v_cndmask_b32_e32 v90, v87, v86, vcc
	v_div_scale_f32 v91, s[0:1], v90, v90, 1.0
	v_rcp_f32_e32 v92, v91
	v_rcp_f32_e32 v86, v88
	v_add_f32_e32 v87, 1.0, v89
	v_rcp_f32_e32 v87, v87
	v_fma_f32 v88, -v91, v92, 1.0
	v_fmac_f32_e32 v92, v88, v92
	v_div_scale_f32 v88, vcc, 1.0, v90, 1.0
	v_mul_f32_e32 v89, v88, v92
	v_fma_f32 v93, -v91, v89, v88
	v_fmac_f32_e32 v89, v93, v92
	v_fma_f32 v88, -v91, v89, v88
	v_div_fmas_f32 v88, v88, v92, v89
	v_div_fixup_f32 v88, v88, v90, 1.0
	v_pk_mul_f32 v[80:81], v[80:81], v[88:89] op_sel_hi:[1,0]
	s_nop 0
	v_pk_fma_f32 v[68:69], v[68:69], v[80:81], v[72:73]
	s_nop 0
	v_mul_f32_e32 v72, 0xbfb8aa3b, v68
	v_exp_f32_e32 v80, v72
	v_mul_f32_e32 v72, 0xbfb8aa3b, v69
	v_exp_f32_e32 v81, v72
	v_pk_mul_f32 v[72:73], v[78:79], v[86:87]
	v_add_f32_e32 v78, 1.0, v80
	v_rcp_f32_e32 v78, v78
	v_add_f32_e32 v79, 1.0, v81
	v_pk_add_f32 v[80:81], v[82:83], v[84:85] op_sel:[0,1] neg_lo:[0,1] neg_hi:[0,1]
	v_rcp_f32_e32 v79, v79
	v_pk_mul_f32 v[80:81], v[80:81], v[88:89] op_sel_hi:[1,0]
	v_cvt_pk_bf16_f32 v77, v72, v73
	v_pk_fma_f32 v[70:71], v[70:71], v[80:81], v[74:75]
	v_pk_mul_f32 v[68:69], v[68:69], v[78:79]
	v_mul_f32_e32 v74, 0xbfb8aa3b, v70
	v_mul_f32_e32 v75, 0xbfb8aa3b, v71
	v_exp_f32_e32 v74, v74
	v_exp_f32_e32 v75, v75
	v_cvt_pk_bf16_f32 v68, v68, v69
	v_add_f32_e32 v74, 1.0, v74
	v_add_f32_e32 v75, 1.0, v75
	v_rcp_f32_e32 v74, v74
	v_rcp_f32_e32 v75, v75
	s_nop 0
	v_pk_mul_f32 v[70:71], v[70:71], v[74:75]
	s_nop 0
	v_cvt_pk_bf16_f32 v69, v70, v71
	ds_write2_b64 v95, v[76:77], v[68:69] offset0:140 offset1:206
	v_and_b32_e32 v68, -16, v108
	v_mul_u32_u24_e32 v69, 0x210, v161
	v_add3_u32 v96, 0, v68, v69
	s_waitcnt lgkmcnt(0)
	s_barrier
	ds_read_b128 v[68:71], v96
	ds_read_b128 v[72:75], v96 offset:64
	s_waitcnt lgkmcnt(1)
	v_mfma_f32_16x16x32_bf16 v[76:79], v[68:71], v[60:63], 0
	v_mfma_f32_16x16x32_bf16 v[68:71], v[68:71], v[64:67], 0
	s_waitcnt lgkmcnt(0)
	v_mfma_f32_16x16x32_bf16 v[76:79], v[72:75], v[44:47], v[76:79]
	v_mfma_f32_16x16x32_bf16 v[68:71], v[72:75], v[56:59], v[68:71]
	ds_read_b128 v[72:75], v96 offset:128
	ds_read_b128 v[80:83], v96 offset:192
	s_waitcnt lgkmcnt(1)
	v_mfma_f32_16x16x32_bf16 v[76:79], v[72:75], v[36:39], v[76:79]
	v_mfma_f32_16x16x32_bf16 v[68:71], v[72:75], v[52:55], v[68:71]
	s_waitcnt lgkmcnt(0)
	v_mfma_f32_16x16x32_bf16 v[72:75], v[80:83], v[28:31], v[76:79]
	v_mfma_f32_16x16x32_bf16 v[68:71], v[80:83], v[48:51], v[68:71]
	s_nop 3
	ds_read_b128 v[76:79], v96 offset:256
	ds_read_b128 v[80:83], v96 offset:320
	s_waitcnt lgkmcnt(1)
	v_mfma_f32_16x16x32_bf16 v[72:75], v[76:79], v[20:23], v[72:75]
	v_mfma_f32_16x16x32_bf16 v[68:71], v[76:79], v[40:43], v[68:71]
	s_waitcnt lgkmcnt(0)
	v_mfma_f32_16x16x32_bf16 v[72:75], v[80:83], v[12:15], v[72:75]
	v_mfma_f32_16x16x32_bf16 v[68:71], v[80:83], v[32:35], v[68:71]
	ds_read_b128 v[76:79], v96 offset:384
	ds_read_b128 v[80:83], v96 offset:448
	s_waitcnt lgkmcnt(1)
	v_mfma_f32_16x16x32_bf16 v[72:75], v[76:79], v[8:11], v[72:75]
	v_mfma_f32_16x16x32_bf16 v[68:71], v[76:79], v[24:27], v[68:71]
	s_waitcnt lgkmcnt(0)
	v_mfma_f32_16x16x32_bf16 v[72:75], v[80:83], v[4:7], v[72:75]
	v_mfma_f32_16x16x32_bf16 v[68:71], v[80:83], v[16:19], v[68:71]
	ds_read_b128 v[76:79], v96 offset:8448
	ds_read_b128 v[84:87], v96 offset:8512
	s_waitcnt lgkmcnt(1)
	v_mfma_f32_16x16x32_bf16 v[80:83], v[76:79], v[60:63], 0
	v_mfma_f32_16x16x32_bf16 v[76:79], v[76:79], v[64:67], 0
	s_waitcnt lgkmcnt(0)
	v_mfma_f32_16x16x32_bf16 v[80:83], v[84:87], v[44:47], v[80:83]
	v_mfma_f32_16x16x32_bf16 v[76:79], v[84:87], v[56:59], v[76:79]
	ds_read_b128 v[84:87], v96 offset:8576
	s_waitcnt lgkmcnt(0)
	v_mfma_f32_16x16x32_bf16 v[80:83], v[84:87], v[36:39], v[80:83]
	v_mfma_f32_16x16x32_bf16 v[76:79], v[84:87], v[52:55], v[76:79]
	ds_read_b128 v[84:87], v96 offset:8640
	s_waitcnt lgkmcnt(0)
	v_mfma_f32_16x16x32_bf16 v[80:83], v[84:87], v[28:31], v[80:83]
	v_mfma_f32_16x16x32_bf16 v[76:79], v[84:87], v[48:51], v[76:79]
	ds_read_b128 v[84:87], v96 offset:8704
	s_waitcnt lgkmcnt(0)
	v_mfma_f32_16x16x32_bf16 v[80:83], v[84:87], v[20:23], v[80:83]
	v_mfma_f32_16x16x32_bf16 v[76:79], v[84:87], v[40:43], v[76:79]
	ds_read_b128 v[84:87], v96 offset:8768
	s_waitcnt lgkmcnt(0)
	v_mfma_f32_16x16x32_bf16 v[80:83], v[84:87], v[12:15], v[80:83]
	v_mfma_f32_16x16x32_bf16 v[76:79], v[84:87], v[32:35], v[76:79]
	ds_read_b128 v[84:87], v96 offset:8832
	s_waitcnt lgkmcnt(0)
	v_mfma_f32_16x16x32_bf16 v[80:83], v[84:87], v[8:11], v[80:83]
	v_mfma_f32_16x16x32_bf16 v[76:79], v[84:87], v[24:27], v[76:79]
	ds_read_b128 v[84:87], v96 offset:8896
	s_waitcnt lgkmcnt(0)
; #define LAS __attribute__((address_space(3)))
; DI unsigned f2bf(float f) { return pk2(f, f) & 0xffffu; }
; #define MFMA16(a, b, c) __builtin_amdgcn_mfma_f32_16x16x32_bf16((a), (b), (c), 0, 0, 0)
; DI void mm64_compute(const LAS unsigned char* A, int lda_b, const bf16x8 (&bfr)[2][8], int lane, f32x4 (&acc)[4][2]) {
;     ...
;     for (int rt = 0; rt < 4; ++rt)
;     {
;         bf16x8 af[8];
; #pragma unroll
;         for (int ks = 0; ks < 8; ++ks) af[ks] = ld8l(A + (16 * rt + fr) * lda_b + (32 * ks + 8 * fq) * 2);
; #pragma unroll
;         for (int ks = 0; ks < 8; ++ks) { acc[rt][0] = MFMA16(af[ks], bfr[0][ks], acc[rt][0]); acc[rt][1] = MFMA16(af[ks], bfr[1][ks], acc[rt][1]); }
;         __builtin_amdgcn_sched_barrier(0);
;     }
; DI void conv_unit(const Args& a, const Frame& F, int l, int unit) {
;     ...
; #pragma unroll
;     for (int ct = 0; ct < 2; ++ct) { const int n = 32 * F.wave + 16 * ct + fr;
; #pragma unroll
;         for (int rt = 0; rt < 4; ++rt)
; #pragma unroll
;             for (int j = 0; j < 4; ++j) ((LAS bf16*)(F.lds + CV_Y))[(16 * rt + 4 * fq + j) * 264 + n] = (bf16)f2bf(acc[rt][ct][j]); }
	v_mfma_f32_16x16x32_bf16 v[80:83], v[84:87], v[4:7], v[80:83]
	v_mfma_f32_16x16x32_bf16 v[76:79], v[84:87], v[16:19], v[76:79]
	ds_read_b128 v[84:87], v96 offset:16896
	ds_read_b128 v[92:95], v96 offset:16960
	s_waitcnt lgkmcnt(1)
	v_mfma_f32_16x16x32_bf16 v[88:91], v[84:87], v[60:63], 0
	v_mfma_f32_16x16x32_bf16 v[84:87], v[84:87], v[64:67], 0
	s_waitcnt lgkmcnt(0)
	v_mfma_f32_16x16x32_bf16 v[88:91], v[92:95], v[44:47], v[88:91]
	v_mfma_f32_16x16x32_bf16 v[84:87], v[92:95], v[56:59], v[84:87]
	ds_read_b128 v[92:95], v96 offset:17024
	s_waitcnt lgkmcnt(0)
	v_mfma_f32_16x16x32_bf16 v[88:91], v[92:95], v[36:39], v[88:91]
	v_mfma_f32_16x16x32_bf16 v[84:87], v[92:95], v[52:55], v[84:87]
	ds_read_b128 v[92:95], v96 offset:17088
	s_waitcnt lgkmcnt(0)
	v_mfma_f32_16x16x32_bf16 v[88:91], v[92:95], v[28:31], v[88:91]
	v_mfma_f32_16x16x32_bf16 v[84:87], v[92:95], v[48:51], v[84:87]
	ds_read_b128 v[92:95], v96 offset:17152
	s_waitcnt lgkmcnt(0)
	v_mfma_f32_16x16x32_bf16 v[88:91], v[92:95], v[20:23], v[88:91]
	v_mfma_f32_16x16x32_bf16 v[84:87], v[92:95], v[40:43], v[84:87]
	ds_read_b128 v[92:95], v96 offset:17216
	s_waitcnt lgkmcnt(0)
	v_mfma_f32_16x16x32_bf16 v[88:91], v[92:95], v[12:15], v[88:91]
	v_mfma_f32_16x16x32_bf16 v[84:87], v[92:95], v[32:35], v[84:87]
	ds_read_b128 v[92:95], v96 offset:17280
	s_waitcnt lgkmcnt(0)
	v_mfma_f32_16x16x32_bf16 v[88:91], v[92:95], v[8:11], v[88:91]
	v_mfma_f32_16x16x32_bf16 v[84:87], v[92:95], v[24:27], v[84:87]
	ds_read_b128 v[92:95], v96 offset:17344
	s_waitcnt lgkmcnt(0)
	v_mfma_f32_16x16x32_bf16 v[88:91], v[92:95], v[4:7], v[88:91]
	v_mfma_f32_16x16x32_bf16 v[84:87], v[92:95], v[16:19], v[84:87]
	ds_read_b128 v[92:95], v96 offset:25344
	s_waitcnt lgkmcnt(0)
	v_mfma_f32_16x16x32_bf16 v[60:63], v[92:95], v[60:63], 0
	v_mfma_f32_16x16x32_bf16 v[64:67], v[92:95], v[64:67], 0
	ds_read_b128 v[92:95], v96 offset:25408
	s_waitcnt lgkmcnt(0)
	v_mfma_f32_16x16x32_bf16 v[44:47], v[92:95], v[44:47], v[60:63]
	s_nop 3
	ds_read_b128 v[60:63], v96 offset:25472
	v_mfma_f32_16x16x32_bf16 v[56:59], v[92:95], v[56:59], v[64:67]
	s_waitcnt lgkmcnt(0)
	v_mfma_f32_16x16x32_bf16 v[36:39], v[60:63], v[36:39], v[44:47]
	v_mfma_f32_16x16x32_bf16 v[44:47], v[60:63], v[52:55], v[56:59]
	ds_read_b128 v[52:55], v96 offset:25536
	s_waitcnt lgkmcnt(0)
	v_mfma_f32_16x16x32_bf16 v[28:31], v[52:55], v[28:31], v[36:39]
	v_mfma_f32_16x16x32_bf16 v[36:39], v[52:55], v[48:51], v[44:47]
	s_nop 3
	ds_read_b128 v[44:47], v96 offset:25600
	s_waitcnt lgkmcnt(0)
	v_mfma_f32_16x16x32_bf16 v[20:23], v[44:47], v[20:23], v[28:31]
	v_mfma_f32_16x16x32_bf16 v[28:31], v[44:47], v[40:43], v[36:39]
	s_nop 2
	ds_read_b128 v[36:39], v96 offset:25664
	s_waitcnt lgkmcnt(0)
	v_mfma_f32_16x16x32_bf16 v[12:15], v[36:39], v[12:15], v[20:23]
	v_mfma_f32_16x16x32_bf16 v[20:23], v[36:39], v[32:35], v[28:31]
	s_nop 2
	ds_read_b128 v[28:31], v96 offset:25728
	s_waitcnt lgkmcnt(0)
	v_mfma_f32_16x16x32_bf16 v[8:11], v[28:31], v[8:11], v[12:15]
	v_mfma_f32_16x16x32_bf16 v[12:15], v[28:31], v[24:27], v[20:23]
	s_nop 2
	ds_read_b128 v[20:23], v96 offset:25792
	s_waitcnt lgkmcnt(0)
	v_mfma_f32_16x16x32_bf16 v[4:7], v[20:23], v[4:7], v[8:11]
	v_mfma_f32_16x16x32_bf16 v[8:11], v[20:23], v[16:19], v[12:15]
	s_nop 2
	v_ashrrev_i32_e32 v13, 2, v108
	v_and_b32_e32 v14, 0xffffffc, v13
	s_movk_i32 s2, 0x210
	v_lshl_add_u32 v12, v161, 1, s23
	v_mul_lo_u32 v17, v14, s2
	v_add_u32_e32 v18, v12, v17
	v_cvt_pk_bf16_f32 v14, v73, s0
	v_cvt_pk_bf16_f32 v15, v72, s0
	ds_write_b16 v18, v14 offset:49680
	v_cvt_pk_bf16_f32 v14, v74, s0
	v_or_b32_e32 v13, 3, v13
	ds_write_b16 v18, v15 offset:49152
	ds_write_b16 v18, v14 offset:50208
	v_cvt_pk_bf16_f32 v19, v75, s0
	v_mad_u64_u32 v[14:15], s[0:1], v13, s2, v[12:13]
	ds_write_b16 v14, v19 offset:49152
	s_nop 0
	v_cvt_pk_bf16_f32 v13, v80, s0
	ds_write_b16 v18, v13 offset:57600
	v_cvt_pk_bf16_f32 v13, v81, s0
	ds_write_b16 v18, v13 offset:58128
	v_cvt_pk_bf16_f32 v13, v82, s0
	v_add_u32_e32 v16, 0xc000, v12
	ds_write_b16 v18, v13 offset:58656
	v_cvt_pk_bf16_f32 v13, v83, s0
	v_add_u32_e32 v15, 0x4200, v17
	ds_write_b16 v18, v13 offset:59184
	v_cvt_pk_bf16_f32 v13, v88, s0
	v_add_u32_e32 v19, v16, v15
	ds_write_b16 v19, v13
	v_add_u32_e32 v19, 0x4410, v17
	v_cvt_pk_bf16_f32 v13, v89, s0
	v_add_u32_e32 v20, v16, v19
	ds_write_b16 v20, v13
	v_add_u32_e32 v20, 0x4620, v17
	v_cvt_pk_bf16_f32 v13, v90, s0
	v_add_u32_e32 v21, v16, v20
	ds_write_b16 v21, v13
	v_add_u32_e32 v21, 0x4830, v17
	v_cvt_pk_bf16_f32 v13, v91, s0
	v_add_u32_e32 v22, v16, v21
	ds_write_b16 v22, v13
	v_add_u32_e32 v13, 0x6300, v17
	v_cvt_pk_bf16_f32 v4, v4, s0
	v_add_u32_e32 v22, v16, v13
	ds_write_b16 v22, v4
	v_cvt_pk_bf16_f32 v4, v5, s0
	v_add_u32_e32 v5, 0x6510, v17
	v_add_u32_e32 v22, v16, v5
	ds_write_b16 v22, v4
	v_cvt_pk_bf16_f32 v4, v6, s0
	v_add_u32_e32 v6, 0x6720, v17
	v_add_u32_e32 v22, v16, v6
	ds_write_b16 v22, v4
	v_cvt_pk_bf16_f32 v4, v7, s0
	v_add_u32_e32 v7, 0x6930, v17
	v_add_u32_e32 v16, v16, v7
	ds_write_b16 v16, v4
	v_add_u32_e32 v4, 0xc020, v12
	v_cvt_pk_bf16_f32 v12, v68, s0
	ds_write_b16 v18, v12 offset:49184
	v_cvt_pk_bf16_f32 v12, v69, s0
	ds_write_b16 v18, v12 offset:49712
	v_cvt_pk_bf16_f32 v12, v70, s0
	ds_write_b16 v18, v12 offset:50240
	v_cvt_pk_bf16_f32 v12, v71, s0
	ds_write_b16 v14, v12 offset:49184
	v_cvt_pk_bf16_f32 v12, v76, s0
	ds_write_b16 v18, v12 offset:57632
	v_cvt_pk_bf16_f32 v12, v77, s0
	ds_write_b16 v18, v12 offset:58160
	v_cvt_pk_bf16_f32 v12, v78, s0
	ds_write_b16 v18, v12 offset:58688
	v_cvt_pk_bf16_f32 v12, v79, s0
	ds_write_b16 v18, v12 offset:59216
	v_cvt_pk_bf16_f32 v12, v84, s0
	v_add_u32_e32 v14, v4, v15
	ds_write_b16 v14, v12
	v_cvt_pk_bf16_f32 v12, v85, s0
	v_add_u32_e32 v14, v4, v19
	ds_write_b16 v14, v12
	v_cvt_pk_bf16_f32 v12, v86, s0
	v_add_u32_e32 v14, v4, v20
	ds_write_b16 v14, v12
	v_cvt_pk_bf16_f32 v12, v87, s0
	v_add_u32_e32 v14, v4, v21
	ds_write_b16 v14, v12
	v_cvt_pk_bf16_f32 v8, v8, s0
	v_add_u32_e32 v12, v4, v13
	ds_write_b16 v12, v8
	v_cvt_pk_bf16_f32 v8, v9, s0
	v_add_u32_e32 v5, v4, v5
	ds_write_b16 v5, v8
	v_cvt_pk_bf16_f32 v5, v10, s0
	v_add_u32_e32 v6, v4, v6
	ds_write_b16 v6, v5
	v_cvt_pk_bf16_f32 v5, v11, s0
	v_add_u32_e32 v4, v4, v7
	v_ashrrev_i32_e32 v8, 5, v111
	ds_write_b16 v4, v5
	v_mul_lo_u32 v4, v8, s2
	v_add_u32_e32 v8, s24, v8
	v_ashrrev_i32_e32 v9, 31, v8
	v_lshlrev_b32_e32 v12, 1, v110
	v_lshlrev_b64 v[8:9], 11, v[8:9]
	v_add3_u32 v4, 0, v4, v12
	v_lshl_add_u64 v[8:9], s[74:75], 0, v[8:9]
	v_mov_b32_e32 v13, v2
	s_waitcnt lgkmcnt(0)
	s_barrier
; #define LAS __attribute__((address_space(3)))
; DI void conv_unit(const Args& a, const Frame& F, int l, int unit) {
;     ...
; #pragma unroll
;     for (int k = 0; k < 4; ++k) { const int e = tid + k * NTHR, t = e >> 5, c8 = (e & 31) * 8;
;         *(u32x4*)(MIX + (size_t)(row0 + t) * DM + 512 + c8) = *(const LAS u32x4*)((LAS bf16*)(F.lds + CV_Y) + t * 264 + c8); }
	ds_read_b128 v[4:7], v4 offset:49152
	v_lshl_add_u64 v[8:9], v[8:9], 0, v[12:13]
	s_mov_b32 s0, 0x1b300000
	v_add_co_u32_e32 v14, vcc, s0, v8
	v_add_u32_e32 v8, 0x200, v111
	v_ashrrev_i32_e32 v16, 5, v8
	v_mul_lo_u32 v8, v16, s2
	v_addc_co_u32_e32 v15, vcc, 0, v9, vcc
	v_add3_u32 v8, 0, v8, v12
	ds_read_b128 v[8:11], v8 offset:49152
	s_waitcnt lgkmcnt(1)
	global_store_dwordx4 v[14:15], v[4:7], off offset:1024
	s_nop 1
	v_add_u32_e32 v4, s24, v16
	v_ashrrev_i32_e32 v5, 31, v4
	v_lshlrev_b64 v[4:5], 11, v[4:5]
	v_lshl_add_u64 v[4:5], s[74:75], 0, v[4:5]
	v_lshl_add_u64 v[4:5], v[4:5], 0, v[12:13]
	v_add_co_u32_e32 v4, vcc, s0, v4
	s_nop 1
	v_addc_co_u32_e32 v5, vcc, 0, v5, vcc
	s_waitcnt lgkmcnt(0)
	global_store_dwordx4 v[4:5], v[8:11], off offset:1024
	v_add_u32_e32 v4, 0x400, v111
	s_nop 0
	v_ashrrev_i32_e32 v8, 5, v4
	v_mul_lo_u32 v4, v8, s2
	v_add_u32_e32 v8, s24, v8
	v_ashrrev_i32_e32 v9, 31, v8
	v_lshlrev_b64 v[8:9], 11, v[8:9]
	v_add3_u32 v4, 0, v4, v12
	v_lshl_add_u64 v[8:9], s[74:75], 0, v[8:9]
	ds_read_b128 v[4:7], v4 offset:49152
	v_lshl_add_u64 v[8:9], v[8:9], 0, v[12:13]
	v_add_co_u32_e32 v14, vcc, s0, v8
	v_add_u32_e32 v8, 0x600, v111
	v_ashrrev_i32_e32 v16, 5, v8
	v_mul_lo_u32 v8, v16, s2
	v_addc_co_u32_e32 v15, vcc, 0, v9, vcc
	v_add3_u32 v8, 0, v8, v12
	ds_read_b128 v[8:11], v8 offset:49152
	s_waitcnt lgkmcnt(1)
	global_store_dwordx4 v[14:15], v[4:7], off offset:1024
	s_nop 1
	v_add_u32_e32 v4, s24, v16
	v_ashrrev_i32_e32 v5, 31, v4
	v_lshlrev_b64 v[4:5], 11, v[4:5]
	v_lshl_add_u64 v[4:5], s[74:75], 0, v[4:5]
	v_lshl_add_u64 v[4:5], v[4:5], 0, v[12:13]
	v_add_co_u32_e32 v4, vcc, 0x1b300000, v4
	s_nop 1
	v_addc_co_u32_e32 v5, vcc, 0, v5, vcc
	s_waitcnt lgkmcnt(0)
	global_store_dwordx4 v[4:5], v[8:11], off offset:1024
	s_barrier
	s_and_saveexec_b64 s[0:1], s[36:37]
	s_cbranch_execz .LBB0_1494
	v_mov_b32_e32 v4, s79
	ds_write_b32 v4, v3
	s_branch .LBB0_1494

; #define LAS __attribute__((address_space(3)))
; DI unsigned pk2(float lo, float hi) { const f32x2 v = {lo, hi}; return __builtin_bit_cast(unsigned, __builtin_convertvector(v, hwbf16x2)); }
; template <int L>
; DI void gmlp_unit_t(const Args& a, const Frame& F, int l, int row0, float* gv_out) {
;     ...
;         for (int t0 = F.wave; t0 < L; t0 += 4 * NWAVES) {
;             u32x2 raw[4];
; #pragma unroll
;             for (int r = 0; r < 4; ++r) raw[r] = *(const u32x2*)(P + (size_t)(row0 + t0 + r * NWAVES) * INW + 1792 + 4 * lane);
;             f32x4 v[4]; float st[8];
; #pragma unroll
;             for (int r = 0; r < 4; ++r) { v[r] = (f32x4){bflo(raw[r].x), bfhi(raw[r].x), bflo(raw[r].y), bfhi(raw[r].y)};
;                 st[r] = (v[r][0] + v[r][1]) + (v[r][2] + v[r][3]); st[4 + r] = (v[r][0] * v[r][0] + v[r][1] * v[r][1]) + (v[r][2] * v[r][2] + v[r][3] * v[r][3]); }
;             wave_sum_n<8>(st);
; #pragma unroll
;             for (int r = 0; r < 4; ++r) { const int t = t0 + r * NWAVES;
;                 const float mu = st[r] * (1.f / 256.f); const float var = fmaxf(st[4 + r] * (1.f / 256.f) - mu * mu, 0.f); const float rstd = 1.f / sqrtf(var + EPS);
;                 const f32x4 o = (v[r] - mu) * rstd * lg + lb;
;                 if (gv_out) *(f32x4*)(gv_out + (size_t)t * 256 + 4 * lane) = o;
;                 u32x2 wv; wv.x = pk2(o[0], o[1]); wv.y = pk2(o[2], o[3]); *(LAS u32x2*)(VL + t * 544 + lane * 8) = wv; }
;         }
.LBB0_1539:
	s_add_i32 s40, s38, s39
	s_add_i32 s2, s40, 0x2020
	s_ashr_i32 s3, s2, 31
	s_lshl_b64 s[2:3], s[2:3], 12
	v_lshl_add_u64 v[36:37], v[132:133], 0, s[2:3]
	s_add_i32 s2, s40, 0x2028
	s_ashr_i32 s3, s2, 31
	global_load_dwordx2 v[36:37], v[36:37], off offset:3584
	s_lshl_b64 s[2:3], s[2:3], 12
	v_lshl_add_u64 v[38:39], v[132:133], 0, s[2:3]
	global_load_dwordx2 v[38:39], v[38:39], off offset:3584
	s_add_i32 s2, s40, 0x2030
	s_ashr_i32 s3, s2, 31
	s_lshl_b64 s[2:3], s[2:3], 12
	v_lshl_add_u64 v[40:41], v[132:133], 0, s[2:3]
	s_add_i32 s2, s40, 0x2038
	s_ashr_i32 s3, s2, 31
	s_lshl_b64 s[2:3], s[2:3], 12
	v_lshl_add_u64 v[42:43], v[132:133], 0, s[2:3]
	global_load_dwordx2 v[40:41], v[40:41], off offset:3584
	s_add_i32 s39, s39, 32
	global_load_dwordx2 v[46:47], v[42:43], off offset:3584
	s_waitcnt vmcnt(3)
	v_lshlrev_b32_e32 v73, 16, v36
	v_and_b32_e32 v75, 0xffff0000, v36
	v_lshlrev_b32_e32 v77, 16, v37
	v_and_b32_e32 v37, 0xffff0000, v37
	v_mul_f32_e32 v72, v73, v73
	v_mul_f32_e32 v74, v75, v75
	v_mul_f32_e32 v76, v77, v77
	v_mul_f32_e32 v36, v37, v37
	s_waitcnt vmcnt(2)
	v_lshlrev_b32_e32 v57, 16, v38
	v_and_b32_e32 v59, 0xffff0000, v38
	v_lshlrev_b32_e32 v61, 16, v39
	v_and_b32_e32 v63, 0xffff0000, v39
	v_pk_add_f32 v[38:39], v[72:73], v[74:75]
	v_pk_add_f32 v[78:79], v[76:77], v[36:37]
	v_mul_f32_e32 v56, v57, v57
	v_pk_add_f32 v[38:39], v[38:39], v[78:79]
	s_nop 1
	v_mov_b32_dpp v79, v39 quad_perm:[1,0,3,2] row_mask:0xf bank_mask:0xf
	v_mov_b32_dpp v78, v38 quad_perm:[1,0,3,2] row_mask:0xf bank_mask:0xf
	v_mul_f32_e32 v58, v59, v59
	v_mul_f32_e32 v60, v61, v61
	v_mul_f32_e32 v62, v63, v63
	s_waitcnt vmcnt(1)
	v_lshlrev_b32_e32 v49, 16, v40
	s_waitcnt lgkmcnt(0)
	v_pk_add_f32 v[38:39], v[38:39], v[78:79]
	s_nop 1
	v_mov_b32_dpp v79, v39 quad_perm:[2,3,0,1] row_mask:0xf bank_mask:0xf
	v_mov_b32_dpp v78, v38 quad_perm:[2,3,0,1] row_mask:0xf bank_mask:0xf
	v_and_b32_e32 v51, 0xffff0000, v40
	v_lshlrev_b32_e32 v53, 16, v41
	v_and_b32_e32 v55, 0xffff0000, v41
	v_mul_f32_e32 v48, v49, v49
	s_waitcnt lgkmcnt(0)
	v_pk_add_f32 v[38:39], v[38:39], v[78:79]
	s_nop 1
	v_mov_b32_dpp v79, v39 row_half_mirror row_mask:0xf bank_mask:0xf
	v_mov_b32_dpp v78, v38 row_half_mirror row_mask:0xf bank_mask:0xf
	v_mul_f32_e32 v50, v51, v51
	v_mul_f32_e32 v52, v53, v53
	v_mul_f32_e32 v54, v55, v55
	s_waitcnt vmcnt(0)
	v_lshlrev_b32_e32 v41, 16, v46
	s_waitcnt lgkmcnt(0)
	v_pk_add_f32 v[38:39], v[38:39], v[78:79]
	s_nop 1
	v_mov_b32_dpp v79, v39 row_ror:8 row_mask:0xf bank_mask:0xf
	v_mov_b32_dpp v78, v38 row_ror:8 row_mask:0xf bank_mask:0xf
	v_and_b32_e32 v43, 0xffff0000, v46
	v_lshlrev_b32_e32 v45, 16, v47
	v_and_b32_e32 v47, 0xffff0000, v47
	v_mul_f32_e32 v40, v41, v41
	s_waitcnt lgkmcnt(0)
	v_pk_add_f32 v[38:39], v[38:39], v[78:79]
	v_mov_b32_e32 v79, v39
	v_mov_b32_e32 v254, v39
	s_nop 1
	v_permlane16_swap_b32_e32 v79, v254
	s_nop 1
	v_mov_b32_dpp v79, v254 quad_perm:[0,1,2,3] row_mask:0x5 bank_mask:0xf
	v_mov_b32_e32 v78, v38
	v_mov_b32_e32 v255, v38
	s_nop 1
	v_permlane16_swap_b32_e32 v78, v255
	s_nop 1
	v_mov_b32_dpp v78, v255 quad_perm:[0,1,2,3] row_mask:0x5 bank_mask:0xf
	v_mul_f32_e32 v42, v43, v43
	v_mul_f32_e32 v44, v45, v45
	v_mul_f32_e32 v46, v47, v47
	s_waitcnt lgkmcnt(0)
	v_pk_add_f32 v[38:39], v[38:39], v[78:79]
	v_mov_b32_e32 v79, v39
	v_mov_b32_e32 v254, v39
	s_nop 1
	v_permlane32_swap_b32_e32 v79, v254
	s_nop 1
	v_mov_b32_dpp v79, v254 quad_perm:[0,1,2,3] row_mask:0x3 bank_mask:0xf
	v_mov_b32_e32 v78, v38
	v_mov_b32_e32 v255, v38
	s_nop 1
	v_permlane32_swap_b32_e32 v78, v255
	s_nop 1
	v_mov_b32_dpp v78, v255 quad_perm:[0,1,2,3] row_mask:0x3 bank_mask:0xf
	s_waitcnt lgkmcnt(0)
	v_pk_add_f32 v[38:39], v[38:39], v[78:79]
	s_nop 0
	v_pk_mul_f32 v[38:39], v[38:39], s[80:81] op_sel_hi:[1,0]
	s_nop 0
	v_fma_f32 v36, -v39, v39, v38
	v_max_f32_e32 v36, 0, v36
	v_add_f32_e32 v36, 0x358637bd, v36
	v_cmp_gt_f32_e32 vcc, s67, v36
	v_mul_f32_e32 v38, 0x4f800000, v36
	v_sub_f32_e32 v79, v37, v39
	v_cndmask_b32_e32 v36, v36, v38, vcc
	v_sqrt_f32_e32 v38, v36
	v_sub_f32_e32 v78, v77, v39
	v_sub_f32_e32 v75, v75, v39
	v_add_u32_e32 v71, -1, v38
	v_fma_f32 v72, -v71, v38, v36
	v_cmp_ge_f32_e64 s[2:3], 0, v72
	v_add_u32_e32 v72, 1, v38
	s_nop 0
	v_cndmask_b32_e64 v71, v38, v71, s[2:3]
	v_fma_f32 v38, -v72, v38, v36
	v_cmp_lt_f32_e64 s[2:3], 0, v38
	s_nop 1
	v_cndmask_b32_e64 v38, v71, v72, s[2:3]
	v_mul_f32_e32 v71, 0x37800000, v38
	v_cndmask_b32_e32 v38, v38, v71, vcc
	v_cmp_class_f32_e32 vcc, v36, v196
	s_nop 1
	v_cndmask_b32_e32 v36, v38, v36, vcc
	v_div_scale_f32 v38, s[2:3], v36, v36, 1.0
	v_rcp_f32_e32 v71, v38
	s_nop 0
	v_fma_f32 v72, -v38, v71, 1.0
	v_fmac_f32_e32 v71, v72, v71
	v_div_scale_f32 v72, vcc, 1.0, v36, 1.0
	v_mul_f32_e32 v74, v72, v71
	v_fma_f32 v76, -v38, v74, v72
	v_fmac_f32_e32 v74, v76, v71
	v_fma_f32 v38, -v38, v74, v72
	v_div_fmas_f32 v38, v38, v71, v74
	v_div_fixup_f32 v36, v38, v36, 1.0
	v_sub_f32_e32 v74, v73, v39
	v_pk_mul_f32 v[72:73], v[74:75], v[36:37] op_sel_hi:[1,0]
	v_pk_mul_f32 v[36:37], v[78:79], v[36:37] op_sel_hi:[1,0]
	s_nop 0
	v_pk_fma_f32 v[38:39], v[30:31], v[36:37], v[34:35]
	v_pk_fma_f32 v[36:37], v[28:29], v[72:73], v[32:33]
	v_lshl_add_u64 v[72:73], s[24:25], 0, v[136:137]
	global_store_dwordx4 v[72:73], v[36:39], off
	s_nop 1
	v_cvt_pk_bf16_f32 v36, v36, v37
	v_cvt_pk_bf16_f32 v37, v38, v39
	ds_write_b64 v70, v[36:37]
	v_pk_add_f32 v[36:37], v[56:57], v[58:59]
	v_pk_add_f32 v[38:39], v[60:61], v[62:63]
	s_nop 0
	v_pk_add_f32 v[36:37], v[36:37], v[38:39]
	s_nop 1
	v_mov_b32_dpp v39, v37 quad_perm:[1,0,3,2] row_mask:0xf bank_mask:0xf
	v_mov_b32_dpp v38, v36 quad_perm:[1,0,3,2] row_mask:0xf bank_mask:0xf
	s_waitcnt lgkmcnt(0)
; #define LAS __attribute__((address_space(3)))
; DI unsigned pk2(float lo, float hi) { const f32x2 v = {lo, hi}; return __builtin_bit_cast(unsigned, __builtin_convertvector(v, hwbf16x2)); }
; template <int L>
; DI void gmlp_unit_t(const Args& a, const Frame& F, int l, int row0, float* gv_out) {
;     ...
;             for (int r = 0; r < 4; ++r) { v[r] = (f32x4){bflo(raw[r].x), bfhi(raw[r].x), bflo(raw[r].y), bfhi(raw[r].y)};
;                 st[r] = (v[r][0] + v[r][1]) + (v[r][2] + v[r][3]); st[4 + r] = (v[r][0] * v[r][0] + v[r][1] * v[r][1]) + (v[r][2] * v[r][2] + v[r][3] * v[r][3]); }
;             wave_sum_n<8>(st);
; #pragma unroll
;             for (int r = 0; r < 4; ++r) { const int t = t0 + r * NWAVES;
;                 const float mu = st[r] * (1.f / 256.f); const float var = fmaxf(st[4 + r] * (1.f / 256.f) - mu * mu, 0.f); const float rstd = 1.f / sqrtf(var + EPS);
;                 const f32x4 o = (v[r] - mu) * rstd * lg + lb;
;                 if (gv_out) *(f32x4*)(gv_out + (size_t)t * 256 + 4 * lane) = o;
;                 u32x2 wv; wv.x = pk2(o[0], o[1]); wv.y = pk2(o[2], o[3]); *(LAS u32x2*)(VL + t * 544 + lane * 8) = wv; }
	v_pk_add_f32 v[36:37], v[36:37], v[38:39]
	s_nop 1
	v_mov_b32_dpp v39, v37 quad_perm:[2,3,0,1] row_mask:0xf bank_mask:0xf
	v_mov_b32_dpp v38, v36 quad_perm:[2,3,0,1] row_mask:0xf bank_mask:0xf
	s_waitcnt lgkmcnt(0)
	v_pk_add_f32 v[36:37], v[36:37], v[38:39]
	s_nop 1
	v_mov_b32_dpp v39, v37 row_half_mirror row_mask:0xf bank_mask:0xf
	v_mov_b32_dpp v38, v36 row_half_mirror row_mask:0xf bank_mask:0xf
	s_waitcnt lgkmcnt(0)
	v_pk_add_f32 v[36:37], v[36:37], v[38:39]
	s_nop 1
	v_mov_b32_dpp v39, v37 row_ror:8 row_mask:0xf bank_mask:0xf
	v_mov_b32_dpp v38, v36 row_ror:8 row_mask:0xf bank_mask:0xf
	s_waitcnt lgkmcnt(0)
	v_pk_add_f32 v[36:37], v[36:37], v[38:39]
	v_mov_b32_e32 v39, v37
	v_mov_b32_e32 v254, v37
	s_nop 1
	v_permlane16_swap_b32_e32 v39, v254
	s_nop 1
	v_mov_b32_dpp v39, v254 quad_perm:[0,1,2,3] row_mask:0x5 bank_mask:0xf
	v_mov_b32_e32 v38, v36
	v_mov_b32_e32 v255, v36
	s_nop 1
	v_permlane16_swap_b32_e32 v38, v255
	s_nop 1
	v_mov_b32_dpp v38, v255 quad_perm:[0,1,2,3] row_mask:0x5 bank_mask:0xf
	s_waitcnt lgkmcnt(0)
	v_pk_add_f32 v[36:37], v[36:37], v[38:39]
	v_mov_b32_e32 v39, v37
	v_mov_b32_e32 v254, v37
	s_nop 1
	v_permlane32_swap_b32_e32 v39, v254
	s_nop 1
	v_mov_b32_dpp v39, v254 quad_perm:[0,1,2,3] row_mask:0x3 bank_mask:0xf
	v_mov_b32_e32 v38, v36
	v_mov_b32_e32 v255, v36
	s_nop 1
	v_permlane32_swap_b32_e32 v38, v255
	s_nop 1
	v_mov_b32_dpp v38, v255 quad_perm:[0,1,2,3] row_mask:0x3 bank_mask:0xf
	s_waitcnt lgkmcnt(0)
	v_pk_add_f32 v[36:37], v[36:37], v[38:39]
	s_nop 0
	v_pk_mul_f32 v[36:37], v[36:37], s[80:81] op_sel_hi:[1,0]
	s_nop 0
	v_fma_f32 v36, -v37, v37, v36
	v_max_f32_e32 v36, 0, v36
	v_add_f32_e32 v36, 0x358637bd, v36
	v_cmp_gt_f32_e32 vcc, s67, v36
	v_mul_f32_e32 v38, 0x4f800000, v36
	v_sub_f32_e32 v59, v59, v37
	v_cndmask_b32_e32 v36, v36, v38, vcc
	v_sqrt_f32_e32 v38, v36
	s_nop 0
	v_add_u32_e32 v39, -1, v38
	v_fma_f32 v56, -v39, v38, v36
	v_cmp_ge_f32_e64 s[2:3], 0, v56
	v_add_u32_e32 v56, 1, v38
	s_nop 0
	v_cndmask_b32_e64 v39, v38, v39, s[2:3]
	v_fma_f32 v38, -v56, v38, v36
	v_cmp_lt_f32_e64 s[2:3], 0, v38
	s_nop 1
	v_cndmask_b32_e64 v38, v39, v56, s[2:3]
	v_mul_f32_e32 v39, 0x37800000, v38
	v_cndmask_b32_e32 v38, v38, v39, vcc
	v_cmp_class_f32_e32 vcc, v36, v196
	s_nop 1
	v_cndmask_b32_e32 v36, v38, v36, vcc
	v_div_scale_f32 v38, s[2:3], v36, v36, 1.0
	v_rcp_f32_e32 v39, v38
	s_nop 0
	v_fma_f32 v56, -v38, v39, 1.0
	v_fmac_f32_e32 v39, v56, v39
	v_div_scale_f32 v56, vcc, 1.0, v36, 1.0
	v_mul_f32_e32 v58, v56, v39
	v_fma_f32 v60, -v38, v58, v56
	v_fmac_f32_e32 v58, v60, v39
	v_fma_f32 v38, -v38, v58, v56
	v_div_fmas_f32 v38, v38, v39, v58
	v_div_fixup_f32 v36, v38, v36, 1.0
	v_sub_f32_e32 v39, v63, v37
	v_sub_f32_e32 v38, v61, v37
	v_sub_f32_e32 v58, v57, v37
	v_pk_mul_f32 v[56:57], v[58:59], v[36:37] op_sel_hi:[1,0]
	v_pk_mul_f32 v[36:37], v[38:39], v[36:37] op_sel_hi:[1,0]
	s_nop 0
	v_pk_fma_f32 v[38:39], v[30:31], v[36:37], v[34:35]
	v_pk_fma_f32 v[36:37], v[28:29], v[56:57], v[32:33]
	v_lshl_add_u64 v[56:57], s[22:23], 0, v[136:137]
	global_store_dwordx4 v[56:57], v[36:39], off
	s_nop 1
	v_cvt_pk_bf16_f32 v36, v36, v37
	v_cvt_pk_bf16_f32 v37, v38, v39
	ds_write_b64 v70, v[36:37] offset:4352
	v_pk_add_f32 v[36:37], v[48:49], v[50:51]
	v_pk_add_f32 v[38:39], v[52:53], v[54:55]
	s_nop 0
	v_pk_add_f32 v[36:37], v[36:37], v[38:39]
	s_nop 1
	v_mov_b32_dpp v39, v37 quad_perm:[1,0,3,2] row_mask:0xf bank_mask:0xf
	v_mov_b32_dpp v38, v36 quad_perm:[1,0,3,2] row_mask:0xf bank_mask:0xf
	s_waitcnt lgkmcnt(0)
	v_pk_add_f32 v[36:37], v[36:37], v[38:39]
	s_nop 1
	v_mov_b32_dpp v39, v37 quad_perm:[2,3,0,1] row_mask:0xf bank_mask:0xf
	v_mov_b32_dpp v38, v36 quad_perm:[2,3,0,1] row_mask:0xf bank_mask:0xf
	s_waitcnt lgkmcnt(0)
	v_pk_add_f32 v[36:37], v[36:37], v[38:39]
	s_nop 1
	v_mov_b32_dpp v39, v37 row_half_mirror row_mask:0xf bank_mask:0xf
	v_mov_b32_dpp v38, v36 row_half_mirror row_mask:0xf bank_mask:0xf
	s_waitcnt lgkmcnt(0)
	v_pk_add_f32 v[36:37], v[36:37], v[38:39]
	s_nop 1
	v_mov_b32_dpp v39, v37 row_ror:8 row_mask:0xf bank_mask:0xf
	v_mov_b32_dpp v38, v36 row_ror:8 row_mask:0xf bank_mask:0xf
	s_waitcnt lgkmcnt(0)
	v_pk_add_f32 v[36:37], v[36:37], v[38:39]
	v_mov_b32_e32 v39, v37
	v_mov_b32_e32 v254, v37
	s_nop 1
	v_permlane16_swap_b32_e32 v39, v254
	s_nop 1
	v_mov_b32_dpp v39, v254 quad_perm:[0,1,2,3] row_mask:0x5 bank_mask:0xf
	v_mov_b32_e32 v38, v36
	v_mov_b32_e32 v255, v36
	s_nop 1
	v_permlane16_swap_b32_e32 v38, v255
	s_nop 1
	v_mov_b32_dpp v38, v255 quad_perm:[0,1,2,3] row_mask:0x5 bank_mask:0xf
	s_waitcnt lgkmcnt(0)
	v_pk_add_f32 v[36:37], v[36:37], v[38:39]
	v_mov_b32_e32 v39, v37
	v_mov_b32_e32 v254, v37
	s_nop 1
	v_permlane32_swap_b32_e32 v39, v254
	s_nop 1
	v_mov_b32_dpp v39, v254 quad_perm:[0,1,2,3] row_mask:0x3 bank_mask:0xf
	v_mov_b32_e32 v38, v36
	v_mov_b32_e32 v255, v36
	s_nop 1
	v_permlane32_swap_b32_e32 v38, v255
	s_nop 1
	v_mov_b32_dpp v38, v255 quad_perm:[0,1,2,3] row_mask:0x3 bank_mask:0xf
	s_waitcnt lgkmcnt(0)
; #define LAS __attribute__((address_space(3)))
; DI unsigned pk2(float lo, float hi) { const f32x2 v = {lo, hi}; return __builtin_bit_cast(unsigned, __builtin_convertvector(v, hwbf16x2)); }
; template <int L>
; DI void gmlp_unit_t(const Args& a, const Frame& F, int l, int row0, float* gv_out) {
;     ...
;             for (int r = 0; r < 4; ++r) { v[r] = (f32x4){bflo(raw[r].x), bfhi(raw[r].x), bflo(raw[r].y), bfhi(raw[r].y)};
;                 st[r] = (v[r][0] + v[r][1]) + (v[r][2] + v[r][3]); st[4 + r] = (v[r][0] * v[r][0] + v[r][1] * v[r][1]) + (v[r][2] * v[r][2] + v[r][3] * v[r][3]); }
;             wave_sum_n<8>(st);
; #pragma unroll
;             for (int r = 0; r < 4; ++r) { const int t = t0 + r * NWAVES;
;                 const float mu = st[r] * (1.f / 256.f); const float var = fmaxf(st[4 + r] * (1.f / 256.f) - mu * mu, 0.f); const float rstd = 1.f / sqrtf(var + EPS);
;                 const f32x4 o = (v[r] - mu) * rstd * lg + lb;
;                 if (gv_out) *(f32x4*)(gv_out + (size_t)t * 256 + 4 * lane) = o;
;                 u32x2 wv; wv.x = pk2(o[0], o[1]); wv.y = pk2(o[2], o[3]); *(LAS u32x2*)(VL + t * 544 + lane * 8) = wv; }
	v_pk_add_f32 v[36:37], v[36:37], v[38:39]
	s_nop 0
	v_pk_mul_f32 v[36:37], v[36:37], s[80:81] op_sel_hi:[1,0]
	s_nop 0
	v_fma_f32 v36, -v37, v37, v36
	v_max_f32_e32 v36, 0, v36
	v_add_f32_e32 v36, 0x358637bd, v36
	v_cmp_gt_f32_e32 vcc, s67, v36
	v_mul_f32_e32 v38, 0x4f800000, v36
	v_sub_f32_e32 v51, v51, v37
	v_cndmask_b32_e32 v36, v36, v38, vcc
	v_sqrt_f32_e32 v38, v36
	s_nop 0
	v_add_u32_e32 v39, -1, v38
	v_fma_f32 v48, -v39, v38, v36
	v_cmp_ge_f32_e64 s[2:3], 0, v48
	v_add_u32_e32 v48, 1, v38
	s_nop 0
	v_cndmask_b32_e64 v39, v38, v39, s[2:3]
	v_fma_f32 v38, -v48, v38, v36
	v_cmp_lt_f32_e64 s[2:3], 0, v38
	s_nop 1
	v_cndmask_b32_e64 v38, v39, v48, s[2:3]
	v_mul_f32_e32 v39, 0x37800000, v38
	v_cndmask_b32_e32 v38, v38, v39, vcc
	v_cmp_class_f32_e32 vcc, v36, v196
	s_nop 1
	v_cndmask_b32_e32 v36, v38, v36, vcc
	v_div_scale_f32 v38, s[2:3], v36, v36, 1.0
	v_rcp_f32_e32 v39, v38
	s_nop 0
	v_fma_f32 v48, -v38, v39, 1.0
	v_fmac_f32_e32 v39, v48, v39
	v_div_scale_f32 v48, vcc, 1.0, v36, 1.0
	v_mul_f32_e32 v50, v48, v39
	v_fma_f32 v52, -v38, v50, v48
	v_fmac_f32_e32 v50, v52, v39
	v_fma_f32 v38, -v38, v50, v48
	v_div_fmas_f32 v38, v38, v39, v50
	v_div_fixup_f32 v36, v38, v36, 1.0
	v_sub_f32_e32 v39, v55, v37
	v_sub_f32_e32 v38, v53, v37
	v_sub_f32_e32 v50, v49, v37
	v_pk_mul_f32 v[48:49], v[50:51], v[36:37] op_sel_hi:[1,0]
	v_pk_mul_f32 v[36:37], v[38:39], v[36:37] op_sel_hi:[1,0]
	s_nop 0
	v_pk_fma_f32 v[38:39], v[30:31], v[36:37], v[34:35]
	v_pk_fma_f32 v[36:37], v[28:29], v[48:49], v[32:33]
	v_lshl_add_u64 v[48:49], s[20:21], 0, v[136:137]
	global_store_dwordx4 v[48:49], v[36:39], off
	s_nop 1
	v_cvt_pk_bf16_f32 v36, v36, v37
	v_cvt_pk_bf16_f32 v37, v38, v39
	ds_write_b64 v70, v[36:37] offset:8704
	v_pk_add_f32 v[36:37], v[40:41], v[42:43]
	v_pk_add_f32 v[38:39], v[44:45], v[46:47]
	s_nop 0
	v_pk_add_f32 v[36:37], v[36:37], v[38:39]
	s_nop 1
	v_mov_b32_dpp v39, v37 quad_perm:[1,0,3,2] row_mask:0xf bank_mask:0xf
	v_mov_b32_dpp v38, v36 quad_perm:[1,0,3,2] row_mask:0xf bank_mask:0xf
	s_waitcnt lgkmcnt(0)
	v_pk_add_f32 v[36:37], v[36:37], v[38:39]
	s_nop 1
	v_mov_b32_dpp v39, v37 quad_perm:[2,3,0,1] row_mask:0xf bank_mask:0xf
	v_mov_b32_dpp v38, v36 quad_perm:[2,3,0,1] row_mask:0xf bank_mask:0xf
	s_waitcnt lgkmcnt(0)
	v_pk_add_f32 v[36:37], v[36:37], v[38:39]
	s_nop 1
	v_mov_b32_dpp v39, v37 row_half_mirror row_mask:0xf bank_mask:0xf
	v_mov_b32_dpp v38, v36 row_half_mirror row_mask:0xf bank_mask:0xf
	s_waitcnt lgkmcnt(0)
	v_pk_add_f32 v[36:37], v[36:37], v[38:39]
	s_nop 1
	v_mov_b32_dpp v39, v37 row_ror:8 row_mask:0xf bank_mask:0xf
	v_mov_b32_dpp v38, v36 row_ror:8 row_mask:0xf bank_mask:0xf
	s_waitcnt lgkmcnt(0)
	v_pk_add_f32 v[36:37], v[36:37], v[38:39]
	v_mov_b32_e32 v39, v37
	v_mov_b32_e32 v254, v37
	s_nop 1
	v_permlane16_swap_b32_e32 v39, v254
	s_nop 1
	v_mov_b32_dpp v39, v254 quad_perm:[0,1,2,3] row_mask:0x5 bank_mask:0xf
	v_mov_b32_e32 v38, v36
	v_mov_b32_e32 v255, v36
	s_nop 1
	v_permlane16_swap_b32_e32 v38, v255
	s_nop 1
	v_mov_b32_dpp v38, v255 quad_perm:[0,1,2,3] row_mask:0x5 bank_mask:0xf
	s_waitcnt lgkmcnt(0)
	v_pk_add_f32 v[36:37], v[36:37], v[38:39]
	v_mov_b32_e32 v39, v37
	v_mov_b32_e32 v254, v37
	s_nop 1
	v_permlane32_swap_b32_e32 v39, v254
	s_nop 1
	v_mov_b32_dpp v39, v254 quad_perm:[0,1,2,3] row_mask:0x3 bank_mask:0xf
	v_mov_b32_e32 v38, v36
	v_mov_b32_e32 v255, v36
	s_nop 1
	v_permlane32_swap_b32_e32 v38, v255
	s_nop 1
	v_mov_b32_dpp v38, v255 quad_perm:[0,1,2,3] row_mask:0x3 bank_mask:0xf
	s_waitcnt lgkmcnt(0)
	v_pk_add_f32 v[36:37], v[36:37], v[38:39]
	s_nop 0
	v_pk_mul_f32 v[36:37], v[36:37], s[80:81] op_sel_hi:[1,0]
	s_nop 0
	v_fma_f32 v36, -v37, v37, v36
	v_max_f32_e32 v36, 0, v36
	v_add_f32_e32 v36, 0x358637bd, v36
	v_cmp_gt_f32_e32 vcc, s67, v36
	v_mul_f32_e32 v38, 0x4f800000, v36
	v_sub_f32_e32 v43, v43, v37
	v_cndmask_b32_e32 v36, v36, v38, vcc
	v_sqrt_f32_e32 v38, v36
	s_nop 0
	v_add_u32_e32 v39, -1, v38
	v_fma_f32 v40, -v39, v38, v36
	v_cmp_ge_f32_e64 s[2:3], 0, v40
	v_add_u32_e32 v40, 1, v38
	s_nop 0
	v_cndmask_b32_e64 v39, v38, v39, s[2:3]
	v_fma_f32 v38, -v40, v38, v36
	v_cmp_lt_f32_e64 s[2:3], 0, v38
	s_nop 1
	v_cndmask_b32_e64 v38, v39, v40, s[2:3]
	v_mul_f32_e32 v39, 0x37800000, v38
	v_cndmask_b32_e32 v38, v38, v39, vcc
	v_cmp_class_f32_e32 vcc, v36, v196
	s_nop 1
	v_cndmask_b32_e32 v36, v38, v36, vcc
	v_div_scale_f32 v38, s[2:3], v36, v36, 1.0
	v_rcp_f32_e32 v39, v38
	s_nop 0
	v_fma_f32 v40, -v38, v39, 1.0
	v_fmac_f32_e32 v39, v40, v39
	v_div_scale_f32 v40, vcc, 1.0, v36, 1.0
	v_mul_f32_e32 v42, v40, v39
	v_fma_f32 v44, -v38, v42, v40
	v_fmac_f32_e32 v42, v44, v39
	v_fma_f32 v38, -v38, v42, v40
	v_div_fmas_f32 v38, v38, v39, v42
	v_div_fixup_f32 v36, v38, v36, 1.0
	v_sub_f32_e32 v39, v47, v37
	v_sub_f32_e32 v38, v45, v37
	v_sub_f32_e32 v42, v41, v37
	v_pk_mul_f32 v[40:41], v[42:43], v[36:37] op_sel_hi:[1,0]
	v_pk_mul_f32 v[36:37], v[38:39], v[36:37] op_sel_hi:[1,0]
	s_nop 0
	v_pk_fma_f32 v[38:39], v[30:31], v[36:37], v[34:35]
	v_pk_fma_f32 v[36:37], v[28:29], v[40:41], v[32:33]
	v_lshl_add_u64 v[40:41], s[0:1], 0, v[136:137]
	s_add_u32 s0, s0, 0x8000
	s_addc_u32 s1, s1, 0
	s_add_u32 s20, s20, 0x8000
	s_addc_u32 s21, s21, 0
	s_add_u32 s22, s22, 0x8000
	s_addc_u32 s23, s23, 0
	s_add_u32 s24, s24, 0x8000
	global_store_dwordx4 v[40:41], v[36:39], off
	s_addc_u32 s25, s25, 0
	s_cmp_lt_i32 s39, 32
	v_cvt_pk_bf16_f32 v36, v36, v37
	v_cvt_pk_bf16_f32 v37, v38, v39
	ds_write_b64 v70, v[36:37] offset:13056
	v_add_u32_e32 v70, 0x4400, v70
	s_cbranch_scc1 .LBB0_1539

; #define LAS __attribute__((address_space(3)))
; DI unsigned pk2(float lo, float hi) { const f32x2 v = {lo, hi}; return __builtin_bit_cast(unsigned, __builtin_convertvector(v, hwbf16x2)); }
; template <int L>
; DI void gmlp_unit_t(const Args& a, const Frame& F, int l, int row0, float* gv_out) {
;     ...
;         for (int t0 = F.wave; t0 < L; t0 += 4 * NWAVES) {
;             u32x2 raw[4];
; #pragma unroll
;             for (int r = 0; r < 4; ++r) raw[r] = *(const u32x2*)(P + (size_t)(row0 + t0 + r * NWAVES) * INW + 1792 + 4 * lane);
;             f32x4 v[4]; float st[8];
; #pragma unroll
;             for (int r = 0; r < 4; ++r) { v[r] = (f32x4){bflo(raw[r].x), bfhi(raw[r].x), bflo(raw[r].y), bfhi(raw[r].y)};
;                 st[r] = (v[r][0] + v[r][1]) + (v[r][2] + v[r][3]); st[4 + r] = (v[r][0] * v[r][0] + v[r][1] * v[r][1]) + (v[r][2] * v[r][2] + v[r][3] * v[r][3]); }
;             wave_sum_n<8>(st);
; #pragma unroll
;             for (int r = 0; r < 4; ++r) { const int t = t0 + r * NWAVES;
;                 const float mu = st[r] * (1.f / 256.f); const float var = fmaxf(st[4 + r] * (1.f / 256.f) - mu * mu, 0.f); const float rstd = 1.f / sqrtf(var + EPS);
;                 const f32x4 o = (v[r] - mu) * rstd * lg + lb;
;                 if (gv_out) *(f32x4*)(gv_out + (size_t)t * 256 + 4 * lane) = o;
;                 u32x2 wv; wv.x = pk2(o[0], o[1]); wv.y = pk2(o[2], o[3]); *(LAS u32x2*)(VL + t * 544 + lane * 8) = wv; }
;         }
.LBB0_1548:
	global_load_dwordx2 v[162:163], v[142:143], off
	global_load_dwordx2 v[164:165], v[140:141], off
	global_load_dwordx2 v[166:167], v[86:87], off
	global_load_dwordx2 v[168:169], v[84:85], off
	s_add_i32 s1, s1, 32
	v_lshl_add_u64 v[84:85], v[84:85], 0, s[88:89]
	v_lshl_add_u64 v[86:87], v[86:87], 0, s[88:89]
	v_lshl_add_u64 v[140:141], v[140:141], 0, s[88:89]
	v_lshl_add_u64 v[142:143], v[142:143], 0, s[88:89]
	s_cmpk_lt_i32 s1, 0x60
	s_waitcnt vmcnt(3)
	v_lshlrev_b32_e32 v171, 16, v162
	v_and_b32_e32 v173, 0xffff0000, v162
	v_lshlrev_b32_e32 v175, 16, v163
	v_and_b32_e32 v163, 0xffff0000, v163
	v_mul_f32_e32 v170, v171, v171
	v_mul_f32_e32 v172, v173, v173
	v_mul_f32_e32 v174, v175, v175
	v_mul_f32_e32 v162, v163, v163
	v_pk_add_f32 v[194:195], v[170:171], v[172:173]
	v_pk_add_f32 v[202:203], v[174:175], v[162:163]
	s_waitcnt vmcnt(2)
	v_lshlrev_b32_e32 v177, 16, v164
	v_pk_add_f32 v[194:195], v[194:195], v[202:203]
	s_nop 1
	v_mov_b32_dpp v203, v195 quad_perm:[1,0,3,2] row_mask:0xf bank_mask:0xf
	v_mov_b32_dpp v202, v194 quad_perm:[1,0,3,2] row_mask:0xf bank_mask:0xf
	v_and_b32_e32 v179, 0xffff0000, v164
	v_lshlrev_b32_e32 v181, 16, v165
	v_and_b32_e32 v165, 0xffff0000, v165
	v_mul_f32_e32 v176, v177, v177
	s_waitcnt lgkmcnt(0)
	v_pk_add_f32 v[194:195], v[194:195], v[202:203]
	s_nop 1
	v_mov_b32_dpp v203, v195 quad_perm:[2,3,0,1] row_mask:0xf bank_mask:0xf
	v_mov_b32_dpp v202, v194 quad_perm:[2,3,0,1] row_mask:0xf bank_mask:0xf
	v_mul_f32_e32 v178, v179, v179
	v_mul_f32_e32 v180, v181, v181
	v_mul_f32_e32 v164, v165, v165
	s_waitcnt vmcnt(1)
	v_lshlrev_b32_e32 v183, 16, v166
	s_waitcnt lgkmcnt(0)
	v_pk_add_f32 v[194:195], v[194:195], v[202:203]
	s_nop 1
	v_mov_b32_dpp v203, v195 row_half_mirror row_mask:0xf bank_mask:0xf
	v_mov_b32_dpp v202, v194 row_half_mirror row_mask:0xf bank_mask:0xf
	v_and_b32_e32 v185, 0xffff0000, v166
	v_lshlrev_b32_e32 v187, 16, v167
	v_and_b32_e32 v167, 0xffff0000, v167
	v_mul_f32_e32 v182, v183, v183
	s_waitcnt lgkmcnt(0)
	v_pk_add_f32 v[194:195], v[194:195], v[202:203]
	s_nop 1
	v_mov_b32_dpp v203, v195 row_ror:8 row_mask:0xf bank_mask:0xf
	v_mov_b32_dpp v202, v194 row_ror:8 row_mask:0xf bank_mask:0xf
	v_mul_f32_e32 v184, v185, v185
	v_mul_f32_e32 v186, v187, v187
	v_mul_f32_e32 v166, v167, v167
	s_waitcnt vmcnt(0)
	v_lshlrev_b32_e32 v189, 16, v168
	s_waitcnt lgkmcnt(0)
	v_pk_add_f32 v[194:195], v[194:195], v[202:203]
	v_mov_b32_e32 v203, v195
	v_mov_b32_e32 v254, v195
	s_nop 1
	v_permlane16_swap_b32_e32 v203, v254
	s_nop 1
	v_mov_b32_dpp v203, v254 quad_perm:[0,1,2,3] row_mask:0x5 bank_mask:0xf
	v_mov_b32_e32 v202, v194
	v_mov_b32_e32 v255, v194
	s_nop 1
	v_permlane16_swap_b32_e32 v202, v255
	s_nop 1
	v_mov_b32_dpp v202, v255 quad_perm:[0,1,2,3] row_mask:0x5 bank_mask:0xf
	v_and_b32_e32 v191, 0xffff0000, v168
	v_lshlrev_b32_e32 v193, 16, v169
	v_and_b32_e32 v169, 0xffff0000, v169
	v_mul_f32_e32 v188, v189, v189
	s_waitcnt lgkmcnt(0)
	v_pk_add_f32 v[194:195], v[194:195], v[202:203]
	v_mov_b32_e32 v203, v195
	v_mov_b32_e32 v254, v195
	s_nop 1
	v_permlane32_swap_b32_e32 v203, v254
	s_nop 1
	v_mov_b32_dpp v203, v254 quad_perm:[0,1,2,3] row_mask:0x3 bank_mask:0xf
	v_mov_b32_e32 v202, v194
	v_mov_b32_e32 v255, v194
	s_nop 1
	v_permlane32_swap_b32_e32 v202, v255
	s_nop 1
	v_mov_b32_dpp v202, v255 quad_perm:[0,1,2,3] row_mask:0x3 bank_mask:0xf
	v_mul_f32_e32 v190, v191, v191
	v_mul_f32_e32 v192, v193, v193
	v_mul_f32_e32 v168, v169, v169
	s_waitcnt lgkmcnt(0)
	v_pk_add_f32 v[194:195], v[194:195], v[202:203]
	s_nop 0
	v_pk_mul_f32 v[194:195], v[194:195], s[80:81] op_sel_hi:[1,0]
	s_nop 0
	v_fma_f32 v159, -v195, v195, v194
	v_max_f32_e32 v159, 0, v159
	v_add_f32_e32 v159, 0x358637bd, v159
	v_cmp_gt_f32_e32 vcc, s67, v159
	v_mul_f32_e32 v161, 0x4f800000, v159
	v_sub_f32_e32 v172, v171, v195
	v_cndmask_b32_e32 v159, v159, v161, vcc
	v_sqrt_f32_e32 v161, v159
	v_sub_f32_e32 v163, v163, v195
	v_sub_f32_e32 v173, v173, v195
	v_add_u32_e32 v162, -1, v161
	v_fma_f32 v170, -v162, v161, v159
	v_cmp_ge_f32_e64 s[2:3], 0, v170
	v_add_u32_e32 v170, 1, v161
	s_nop 0
	v_cndmask_b32_e64 v162, v161, v162, s[2:3]
	v_fma_f32 v161, -v170, v161, v159
	v_cmp_lt_f32_e64 s[2:3], 0, v161
	s_nop 1
	v_cndmask_b32_e64 v161, v162, v170, s[2:3]
	v_mul_f32_e32 v162, 0x37800000, v161
	v_cndmask_b32_e32 v161, v161, v162, vcc
	v_cmp_class_f32_e32 vcc, v159, v196
	v_sub_f32_e32 v162, v175, v195
	s_nop 0
	v_cndmask_b32_e32 v159, v161, v159, vcc
	v_div_scale_f32 v161, s[2:3], v159, v159, 1.0
	v_rcp_f32_e32 v170, v161
	s_nop 0
	v_fma_f32 v171, -v161, v170, 1.0
	v_fmac_f32_e32 v170, v171, v170
	v_div_scale_f32 v171, vcc, 1.0, v159, 1.0
	v_mul_f32_e32 v174, v171, v170
	v_fma_f32 v175, -v161, v174, v171
	v_fmac_f32_e32 v174, v175, v170
	v_fma_f32 v161, -v161, v174, v171
	v_div_fmas_f32 v161, v161, v170, v174
	v_div_fixup_f32 v170, v161, v159, 1.0
	v_pk_mul_f32 v[172:173], v[172:173], v[170:171] op_sel_hi:[1,0]
	v_pk_mul_f32 v[162:163], v[162:163], v[170:171] op_sel_hi:[1,0]
	v_pk_fma_f32 v[170:171], v[76:77], v[172:173], v[80:81]
	v_pk_fma_f32 v[162:163], v[78:79], v[162:163], v[82:83]
	v_cvt_pk_bf16_f32 v170, v170, v171
	v_cvt_pk_bf16_f32 v171, v162, v163
	ds_write_b64 v158, v[170:171]
	v_pk_add_f32 v[162:163], v[176:177], v[178:179]
	v_pk_add_f32 v[170:171], v[180:181], v[164:165]
	s_nop 0
	v_pk_add_f32 v[162:163], v[162:163], v[170:171]
	s_nop 1
	v_mov_b32_dpp v171, v163 quad_perm:[1,0,3,2] row_mask:0xf bank_mask:0xf
	v_mov_b32_dpp v170, v162 quad_perm:[1,0,3,2] row_mask:0xf bank_mask:0xf
	s_waitcnt lgkmcnt(0)
	v_pk_add_f32 v[162:163], v[162:163], v[170:171]
	s_nop 1
	v_mov_b32_dpp v171, v163 quad_perm:[2,3,0,1] row_mask:0xf bank_mask:0xf
	v_mov_b32_dpp v170, v162 quad_perm:[2,3,0,1] row_mask:0xf bank_mask:0xf
	s_waitcnt lgkmcnt(0)
; #define LAS __attribute__((address_space(3)))
; DI unsigned pk2(float lo, float hi) { const f32x2 v = {lo, hi}; return __builtin_bit_cast(unsigned, __builtin_convertvector(v, hwbf16x2)); }
; template <int L>
; DI void gmlp_unit_t(const Args& a, const Frame& F, int l, int row0, float* gv_out) {
;     ...
;             for (int r = 0; r < 4; ++r) { v[r] = (f32x4){bflo(raw[r].x), bfhi(raw[r].x), bflo(raw[r].y), bfhi(raw[r].y)};
;                 st[r] = (v[r][0] + v[r][1]) + (v[r][2] + v[r][3]); st[4 + r] = (v[r][0] * v[r][0] + v[r][1] * v[r][1]) + (v[r][2] * v[r][2] + v[r][3] * v[r][3]); }
;             wave_sum_n<8>(st);
; #pragma unroll
;             for (int r = 0; r < 4; ++r) { const int t = t0 + r * NWAVES;
;                 const float mu = st[r] * (1.f / 256.f); const float var = fmaxf(st[4 + r] * (1.f / 256.f) - mu * mu, 0.f); const float rstd = 1.f / sqrtf(var + EPS);
;                 const f32x4 o = (v[r] - mu) * rstd * lg + lb;
;                 if (gv_out) *(f32x4*)(gv_out + (size_t)t * 256 + 4 * lane) = o;
;                 u32x2 wv; wv.x = pk2(o[0], o[1]); wv.y = pk2(o[2], o[3]); *(LAS u32x2*)(VL + t * 544 + lane * 8) = wv; }
	v_pk_add_f32 v[162:163], v[162:163], v[170:171]
	s_nop 1
	v_mov_b32_dpp v171, v163 row_half_mirror row_mask:0xf bank_mask:0xf
	v_mov_b32_dpp v170, v162 row_half_mirror row_mask:0xf bank_mask:0xf
	s_waitcnt lgkmcnt(0)
	v_pk_add_f32 v[162:163], v[162:163], v[170:171]
	s_nop 1
	v_mov_b32_dpp v171, v163 row_ror:8 row_mask:0xf bank_mask:0xf
	v_mov_b32_dpp v170, v162 row_ror:8 row_mask:0xf bank_mask:0xf
	s_waitcnt lgkmcnt(0)
	v_pk_add_f32 v[162:163], v[162:163], v[170:171]
	v_mov_b32_e32 v171, v163
	v_mov_b32_e32 v254, v163
	s_nop 1
	v_permlane16_swap_b32_e32 v171, v254
	s_nop 1
	v_mov_b32_dpp v171, v254 quad_perm:[0,1,2,3] row_mask:0x5 bank_mask:0xf
	v_mov_b32_e32 v170, v162
	v_mov_b32_e32 v255, v162
	s_nop 1
	v_permlane16_swap_b32_e32 v170, v255
	s_nop 1
	v_mov_b32_dpp v170, v255 quad_perm:[0,1,2,3] row_mask:0x5 bank_mask:0xf
	s_waitcnt lgkmcnt(0)
	v_pk_add_f32 v[162:163], v[162:163], v[170:171]
	v_mov_b32_e32 v171, v163
	v_mov_b32_e32 v254, v163
	s_nop 1
	v_permlane32_swap_b32_e32 v171, v254
	s_nop 1
	v_mov_b32_dpp v171, v254 quad_perm:[0,1,2,3] row_mask:0x3 bank_mask:0xf
	v_mov_b32_e32 v170, v162
	v_mov_b32_e32 v255, v162
	s_nop 1
	v_permlane32_swap_b32_e32 v170, v255
	s_nop 1
	v_mov_b32_dpp v170, v255 quad_perm:[0,1,2,3] row_mask:0x3 bank_mask:0xf
	s_waitcnt lgkmcnt(0)
	v_pk_add_f32 v[162:163], v[162:163], v[170:171]
	s_nop 0
	v_pk_mul_f32 v[162:163], v[162:163], s[80:81] op_sel_hi:[1,0]
	s_nop 0
	v_fma_f32 v159, -v163, v163, v162
	v_max_f32_e32 v159, 0, v159
	v_add_f32_e32 v159, 0x358637bd, v159
	v_cmp_gt_f32_e32 vcc, s67, v159
	v_mul_f32_e32 v161, 0x4f800000, v159
	v_sub_f32_e32 v165, v165, v163
	v_cndmask_b32_e32 v159, v159, v161, vcc
	v_sqrt_f32_e32 v161, v159
	v_sub_f32_e32 v171, v179, v163
	v_sub_f32_e32 v170, v177, v163
	v_add_u32_e32 v162, -1, v161
	v_fma_f32 v164, -v162, v161, v159
	v_cmp_ge_f32_e64 s[2:3], 0, v164
	v_add_u32_e32 v164, 1, v161
	s_nop 0
	v_cndmask_b32_e64 v162, v161, v162, s[2:3]
	v_fma_f32 v161, -v164, v161, v159
	v_cmp_lt_f32_e64 s[2:3], 0, v161
	s_nop 1
	v_cndmask_b32_e64 v161, v162, v164, s[2:3]
	v_mul_f32_e32 v162, 0x37800000, v161
	v_cndmask_b32_e32 v161, v161, v162, vcc
	v_cmp_class_f32_e32 vcc, v159, v196
	v_sub_f32_e32 v164, v181, v163
	s_nop 0
	v_cndmask_b32_e32 v159, v161, v159, vcc
	v_div_scale_f32 v161, s[2:3], v159, v159, 1.0
	v_rcp_f32_e32 v162, v161
	s_nop 0
	v_fma_f32 v163, -v161, v162, 1.0
	v_fmac_f32_e32 v162, v163, v162
	v_div_scale_f32 v163, vcc, 1.0, v159, 1.0
	v_mul_f32_e32 v172, v163, v162
	v_fma_f32 v173, -v161, v172, v163
	v_fmac_f32_e32 v172, v173, v162
	v_fma_f32 v161, -v161, v172, v163
	v_div_fmas_f32 v161, v161, v162, v172
	v_div_fixup_f32 v162, v161, v159, 1.0
	v_pk_mul_f32 v[170:171], v[170:171], v[162:163] op_sel_hi:[1,0]
	v_pk_mul_f32 v[162:163], v[164:165], v[162:163] op_sel_hi:[1,0]
	v_pk_fma_f32 v[164:165], v[76:77], v[170:171], v[80:81]
	v_pk_fma_f32 v[162:163], v[78:79], v[162:163], v[82:83]
	v_cvt_pk_bf16_f32 v164, v164, v165
	v_cvt_pk_bf16_f32 v165, v162, v163
	ds_write_b64 v158, v[164:165] offset:4352
	v_pk_add_f32 v[162:163], v[182:183], v[184:185]
	v_pk_add_f32 v[164:165], v[186:187], v[166:167]
	s_nop 0
	v_pk_add_f32 v[162:163], v[162:163], v[164:165]
	s_nop 1
	v_mov_b32_dpp v165, v163 quad_perm:[1,0,3,2] row_mask:0xf bank_mask:0xf
	v_mov_b32_dpp v164, v162 quad_perm:[1,0,3,2] row_mask:0xf bank_mask:0xf
	s_waitcnt lgkmcnt(0)
	v_pk_add_f32 v[162:163], v[162:163], v[164:165]
	s_nop 1
	v_mov_b32_dpp v165, v163 quad_perm:[2,3,0,1] row_mask:0xf bank_mask:0xf
	v_mov_b32_dpp v164, v162 quad_perm:[2,3,0,1] row_mask:0xf bank_mask:0xf
	s_waitcnt lgkmcnt(0)
	v_pk_add_f32 v[162:163], v[162:163], v[164:165]
	s_nop 1
	v_mov_b32_dpp v165, v163 row_half_mirror row_mask:0xf bank_mask:0xf
	v_mov_b32_dpp v164, v162 row_half_mirror row_mask:0xf bank_mask:0xf
	s_waitcnt lgkmcnt(0)
	v_pk_add_f32 v[162:163], v[162:163], v[164:165]
	s_nop 1
	v_mov_b32_dpp v165, v163 row_ror:8 row_mask:0xf bank_mask:0xf
	v_mov_b32_dpp v164, v162 row_ror:8 row_mask:0xf bank_mask:0xf
	s_waitcnt lgkmcnt(0)
	v_pk_add_f32 v[162:163], v[162:163], v[164:165]
	v_mov_b32_e32 v165, v163
	v_mov_b32_e32 v254, v163
	s_nop 1
	v_permlane16_swap_b32_e32 v165, v254
	s_nop 1
	v_mov_b32_dpp v165, v254 quad_perm:[0,1,2,3] row_mask:0x5 bank_mask:0xf
	v_mov_b32_e32 v164, v162
	v_mov_b32_e32 v255, v162
	s_nop 1
	v_permlane16_swap_b32_e32 v164, v255
	s_nop 1
	v_mov_b32_dpp v164, v255 quad_perm:[0,1,2,3] row_mask:0x5 bank_mask:0xf
	s_waitcnt lgkmcnt(0)
	v_pk_add_f32 v[162:163], v[162:163], v[164:165]
	v_mov_b32_e32 v165, v163
	v_mov_b32_e32 v254, v163
	s_nop 1
	v_permlane32_swap_b32_e32 v165, v254
	s_nop 1
	v_mov_b32_dpp v165, v254 quad_perm:[0,1,2,3] row_mask:0x3 bank_mask:0xf
	v_mov_b32_e32 v164, v162
	v_mov_b32_e32 v255, v162
	s_nop 1
	v_permlane32_swap_b32_e32 v164, v255
	s_nop 1
	v_mov_b32_dpp v164, v255 quad_perm:[0,1,2,3] row_mask:0x3 bank_mask:0xf
	s_waitcnt lgkmcnt(0)
; #define LAS __attribute__((address_space(3)))
; DI unsigned pk2(float lo, float hi) { const f32x2 v = {lo, hi}; return __builtin_bit_cast(unsigned, __builtin_convertvector(v, hwbf16x2)); }
; template <int L>
; DI void gmlp_unit_t(const Args& a, const Frame& F, int l, int row0, float* gv_out) {
;     ...
;             for (int r = 0; r < 4; ++r) { v[r] = (f32x4){bflo(raw[r].x), bfhi(raw[r].x), bflo(raw[r].y), bfhi(raw[r].y)};
;                 st[r] = (v[r][0] + v[r][1]) + (v[r][2] + v[r][3]); st[4 + r] = (v[r][0] * v[r][0] + v[r][1] * v[r][1]) + (v[r][2] * v[r][2] + v[r][3] * v[r][3]); }
;             wave_sum_n<8>(st);
; #pragma unroll
;             for (int r = 0; r < 4; ++r) { const int t = t0 + r * NWAVES;
;                 const float mu = st[r] * (1.f / 256.f); const float var = fmaxf(st[4 + r] * (1.f / 256.f) - mu * mu, 0.f); const float rstd = 1.f / sqrtf(var + EPS);
;                 const f32x4 o = (v[r] - mu) * rstd * lg + lb;
;                 if (gv_out) *(f32x4*)(gv_out + (size_t)t * 256 + 4 * lane) = o;
;                 u32x2 wv; wv.x = pk2(o[0], o[1]); wv.y = pk2(o[2], o[3]); *(LAS u32x2*)(VL + t * 544 + lane * 8) = wv; }
	v_pk_add_f32 v[162:163], v[162:163], v[164:165]
	s_nop 0
	v_pk_mul_f32 v[162:163], v[162:163], s[80:81] op_sel_hi:[1,0]
	s_nop 0
	v_fma_f32 v159, -v163, v163, v162
	v_max_f32_e32 v159, 0, v159
	v_add_f32_e32 v159, 0x358637bd, v159
	v_cmp_gt_f32_e32 vcc, s67, v159
	v_mul_f32_e32 v161, 0x4f800000, v159
	v_sub_f32_e32 v165, v167, v163
	v_cndmask_b32_e32 v159, v159, v161, vcc
	v_sqrt_f32_e32 v161, v159
	v_sub_f32_e32 v167, v185, v163
	v_sub_f32_e32 v166, v183, v163
	v_add_u32_e32 v162, -1, v161
	v_fma_f32 v164, -v162, v161, v159
	v_cmp_ge_f32_e64 s[2:3], 0, v164
	v_add_u32_e32 v164, 1, v161
	s_nop 0
	v_cndmask_b32_e64 v162, v161, v162, s[2:3]
	v_fma_f32 v161, -v164, v161, v159
	v_cmp_lt_f32_e64 s[2:3], 0, v161
	s_nop 1
	v_cndmask_b32_e64 v161, v162, v164, s[2:3]
	v_mul_f32_e32 v162, 0x37800000, v161
	v_cndmask_b32_e32 v161, v161, v162, vcc
	v_cmp_class_f32_e32 vcc, v159, v196
	v_sub_f32_e32 v164, v187, v163
	s_nop 0
	v_cndmask_b32_e32 v159, v161, v159, vcc
	v_div_scale_f32 v161, s[2:3], v159, v159, 1.0
	v_rcp_f32_e32 v162, v161
	s_nop 0
	v_fma_f32 v163, -v161, v162, 1.0
	v_fmac_f32_e32 v162, v163, v162
	v_div_scale_f32 v163, vcc, 1.0, v159, 1.0
	v_mul_f32_e32 v170, v163, v162
	v_fma_f32 v171, -v161, v170, v163
	v_fmac_f32_e32 v170, v171, v162
	v_fma_f32 v161, -v161, v170, v163
	v_div_fmas_f32 v161, v161, v162, v170
	v_div_fixup_f32 v162, v161, v159, 1.0
	v_pk_mul_f32 v[166:167], v[166:167], v[162:163] op_sel_hi:[1,0]
	v_pk_mul_f32 v[162:163], v[164:165], v[162:163] op_sel_hi:[1,0]
	v_pk_fma_f32 v[164:165], v[76:77], v[166:167], v[80:81]
	v_pk_fma_f32 v[162:163], v[78:79], v[162:163], v[82:83]
	v_cvt_pk_bf16_f32 v164, v164, v165
	v_cvt_pk_bf16_f32 v165, v162, v163
	ds_write_b64 v158, v[164:165] offset:8704
	v_pk_add_f32 v[162:163], v[188:189], v[190:191]
	v_pk_add_f32 v[164:165], v[192:193], v[168:169]
	s_nop 0
	v_pk_add_f32 v[162:163], v[162:163], v[164:165]
	s_nop 1
	v_mov_b32_dpp v165, v163 quad_perm:[1,0,3,2] row_mask:0xf bank_mask:0xf
	v_mov_b32_dpp v164, v162 quad_perm:[1,0,3,2] row_mask:0xf bank_mask:0xf
	s_waitcnt lgkmcnt(0)
	v_pk_add_f32 v[162:163], v[162:163], v[164:165]
	s_nop 1
	v_mov_b32_dpp v165, v163 quad_perm:[2,3,0,1] row_mask:0xf bank_mask:0xf
	v_mov_b32_dpp v164, v162 quad_perm:[2,3,0,1] row_mask:0xf bank_mask:0xf
	s_waitcnt lgkmcnt(0)
	v_pk_add_f32 v[162:163], v[162:163], v[164:165]
	s_nop 1
	v_mov_b32_dpp v165, v163 row_half_mirror row_mask:0xf bank_mask:0xf
	v_mov_b32_dpp v164, v162 row_half_mirror row_mask:0xf bank_mask:0xf
	s_waitcnt lgkmcnt(0)
	v_pk_add_f32 v[162:163], v[162:163], v[164:165]
	s_nop 1
	v_mov_b32_dpp v165, v163 row_ror:8 row_mask:0xf bank_mask:0xf
	v_mov_b32_dpp v164, v162 row_ror:8 row_mask:0xf bank_mask:0xf
	s_waitcnt lgkmcnt(0)
	v_pk_add_f32 v[162:163], v[162:163], v[164:165]
	v_mov_b32_e32 v165, v163
	v_mov_b32_e32 v254, v163
	s_nop 1
	v_permlane16_swap_b32_e32 v165, v254
	s_nop 1
	v_mov_b32_dpp v165, v254 quad_perm:[0,1,2,3] row_mask:0x5 bank_mask:0xf
	v_mov_b32_e32 v164, v162
	v_mov_b32_e32 v255, v162
	s_nop 1
	v_permlane16_swap_b32_e32 v164, v255
	s_nop 1
	v_mov_b32_dpp v164, v255 quad_perm:[0,1,2,3] row_mask:0x5 bank_mask:0xf
	s_waitcnt lgkmcnt(0)
	v_pk_add_f32 v[162:163], v[162:163], v[164:165]
	v_mov_b32_e32 v165, v163
	v_mov_b32_e32 v254, v163
	s_nop 1
	v_permlane32_swap_b32_e32 v165, v254
	s_nop 1
	v_mov_b32_dpp v165, v254 quad_perm:[0,1,2,3] row_mask:0x3 bank_mask:0xf
	v_mov_b32_e32 v164, v162
	v_mov_b32_e32 v255, v162
	s_nop 1
	v_permlane32_swap_b32_e32 v164, v255
	s_nop 1
	v_mov_b32_dpp v164, v255 quad_perm:[0,1,2,3] row_mask:0x3 bank_mask:0xf
	s_waitcnt lgkmcnt(0)
	v_pk_add_f32 v[162:163], v[162:163], v[164:165]
	s_nop 0
	v_pk_mul_f32 v[162:163], v[162:163], s[80:81] op_sel_hi:[1,0]
	s_nop 0
	v_fma_f32 v159, -v163, v163, v162
	v_max_f32_e32 v159, 0, v159
	v_add_f32_e32 v159, 0x358637bd, v159
	v_cmp_gt_f32_e32 vcc, s67, v159
	v_mul_f32_e32 v161, 0x4f800000, v159
	v_sub_f32_e32 v165, v169, v163
	v_cndmask_b32_e32 v159, v159, v161, vcc
	v_sqrt_f32_e32 v161, v159
	v_sub_f32_e32 v167, v191, v163
	v_sub_f32_e32 v166, v189, v163
	v_add_u32_e32 v162, -1, v161
	v_fma_f32 v164, -v162, v161, v159
	v_cmp_ge_f32_e64 s[2:3], 0, v164
	v_add_u32_e32 v164, 1, v161
	s_nop 0
	v_cndmask_b32_e64 v162, v161, v162, s[2:3]
	v_fma_f32 v161, -v164, v161, v159
	v_cmp_lt_f32_e64 s[2:3], 0, v161
	s_nop 1
	v_cndmask_b32_e64 v161, v162, v164, s[2:3]
	v_mul_f32_e32 v162, 0x37800000, v161
	v_cndmask_b32_e32 v161, v161, v162, vcc
	v_cmp_class_f32_e32 vcc, v159, v196
	v_sub_f32_e32 v164, v193, v163
	s_nop 0
	v_cndmask_b32_e32 v159, v161, v159, vcc
	v_div_scale_f32 v161, s[2:3], v159, v159, 1.0
	v_rcp_f32_e32 v162, v161
	s_nop 0
	v_fma_f32 v163, -v161, v162, 1.0
	v_fmac_f32_e32 v162, v163, v162
	v_div_scale_f32 v163, vcc, 1.0, v159, 1.0
	v_mul_f32_e32 v168, v163, v162
	v_fma_f32 v169, -v161, v168, v163
	v_fmac_f32_e32 v168, v169, v162
	v_fma_f32 v161, -v161, v168, v163
	v_div_fmas_f32 v161, v161, v162, v168
	v_div_fixup_f32 v162, v161, v159, 1.0
	v_pk_mul_f32 v[166:167], v[166:167], v[162:163] op_sel_hi:[1,0]
	v_pk_mul_f32 v[162:163], v[164:165], v[162:163] op_sel_hi:[1,0]
	v_pk_fma_f32 v[164:165], v[76:77], v[166:167], v[80:81]
	v_pk_fma_f32 v[162:163], v[78:79], v[162:163], v[82:83]
	v_cvt_pk_bf16_f32 v164, v164, v165
	v_cvt_pk_bf16_f32 v165, v162, v163
	ds_write_b64 v158, v[164:165] offset:13056
	v_add_u32_e32 v158, 0x4400, v158
	s_cbranch_scc1 .LBB0_1548

; DI u32x4 pack8(f32x4 a, f32x4 b) { u32x4 w; w.x = pk2(a[0], a[1]); w.y = pk2(a[2], a[3]); w.z = pk2(b[0], b[1]); w.w = pk2(b[2], b[3]); return w; }
;     DI void operator()(const pg8::Acc& acc, const pg8::Unit& u, int wr, int wc, int fr, int fq) const {
;     ...
;             for (int ai = 0; ai < 2; ++ai) {
;                 bf16* XH = (bf16*)X;
;                 u32x4 xv[4][2];
; #pragma unroll
;                 for (int m = 0; m < 4; ++m)
; #pragma unroll
;                     for (int bj = 0; bj < 2; ++bj) xv[m][bj] = *(const u32x4*)(XH + (size_t)(row0 + ai * 128 + m * 16) * DM + col0 + bj * 128);
; #pragma unroll
;                 for (int m = 0; m < 4; ++m) { const int row = row0 + ai * 128 + m * 16; float ssq = 0.f;
; #pragma unroll
;                     for (int bj = 0; bj < 2; ++bj) { const u32x4 x = xv[m][bj];
;                         const f32x4 xa = (f32x4){bflo(x.x), bfhi(x.x), bflo(x.y), bfhi(x.y)} + acc[ai][bj][m][0] * scale, xb = (f32x4){bflo(x.z), bfhi(x.z), bflo(x.w), bfhi(x.w)} + acc[ai][bj][m][1] * scale;
;                         *(u32x4*)(XH + (size_t)row * DM + col0 + bj * 128) = pack8(xa, xb);
;                         ssq += ((xa[0] * xa[0] + xa[1] * xa[1]) + (xa[2] * xa[2] + xa[3] * xa[3])) + ((xb[0] * xb[0] + xb[1] * xb[1]) + (xb[2] * xb[2] + xb[3] * xb[3])); }
;                     ssq += __shfl_xor(ssq, 16); ssq += __shfl_xor(ssq, 32);
;                     if (fq == 0) SSP[(size_t)row * 16 + u.pn * 4 + wc] = ssq; }
.LBB0_1770:
	v_lshl_add_u64 v[176:177], v[132:133], 1, s[8:9]
	v_and_b32_e32 v133, 64, v198
	v_xor_b32_e32 v132, 16, v198
	v_add_u32_e32 v133, 64, v133
	v_cmp_lt_i32_e32 vcc, v132, v133
	v_or_b32_e32 v186, 16, v174
	v_ashrrev_i32_e32 v187, 31, v186
	v_cndmask_b32_e32 v132, v198, v132, vcc
	v_lshlrev_b32_e32 v195, 2, v132
	v_xor_b32_e32 v132, 32, v198
	v_cmp_lt_i32_e32 vcc, v132, v133
	v_or_b32_e32 v182, 32, v174
	v_ashrrev_i32_e32 v183, 31, v182
	v_cndmask_b32_e32 v132, v198, v132, vcc
	v_lshlrev_b32_e32 v194, 2, v132
	v_lshlrev_b64 v[132:133], 11, v[174:175]
	v_lshl_add_u64 v[190:191], v[176:177], 0, v[132:133]
	global_load_dwordx4 v[202:205], v[190:191], off
	global_load_dwordx4 v[156:159], v[190:191], off offset:256
	v_lshlrev_b64 v[132:133], 11, v[186:187]
	v_or_b32_e32 v178, 48, v174
	v_lshl_add_u64 v[188:189], v[176:177], 0, v[132:133]
	v_lshlrev_b64 v[132:133], 11, v[182:183]
	v_ashrrev_i32_e32 v179, 31, v178
	v_lshl_add_u64 v[184:185], v[176:177], 0, v[132:133]
	v_lshlrev_b64 v[132:133], 11, v[178:179]
	v_lshl_add_u64 v[180:181], v[176:177], 0, v[132:133]
	global_load_dwordx4 v[152:155], v[188:189], off
	global_load_dwordx4 v[148:151], v[188:189], off offset:256
	global_load_dwordx4 v[144:147], v[184:185], off
	global_load_dwordx4 v[140:143], v[184:185], off offset:256
	global_load_dwordx4 v[136:139], v[180:181], off
	global_load_dwordx4 v[132:135], v[180:181], off offset:256
	v_lshl_add_u64 v[240:241], s[88:89], 1, v[190:191]
	v_lshl_add_u64 v[242:243], s[88:89], 1, v[188:189]
	v_lshl_add_u64 v[244:245], s[88:89], 1, v[184:185]
	v_lshl_add_u64 v[246:247], s[88:89], 1, v[180:181]
	global_load_dwordx4 v[208:211], v[240:241], off
	global_load_dwordx4 v[212:215], v[240:241], off offset:256
	global_load_dwordx4 v[216:219], v[242:243], off
	global_load_dwordx4 v[220:223], v[242:243], off offset:256
	global_load_dwordx4 v[224:227], v[244:245], off
	global_load_dwordx4 v[228:231], v[244:245], off offset:256
	global_load_dwordx4 v[232:235], v[246:247], off
	global_load_dwordx4 v[236:239], v[246:247], off offset:256
	s_waitcnt vmcnt(0)
	v_lshlrev_b32_e32 v206, 16, v202
	v_and_b32_e32 v207, 0xffff0000, v202
	v_lshlrev_b32_e32 v202, 16, v203
	v_and_b32_e32 v203, 0xffff0000, v203
	v_pk_add_f32 v[130:131], v[130:131], v[202:203]
	v_lshlrev_b32_e32 v202, 16, v204
	v_and_b32_e32 v203, 0xffff0000, v204
	v_lshlrev_b32_e32 v204, 16, v205
	v_and_b32_e32 v205, 0xffff0000, v205
	v_pk_add_f32 v[128:129], v[128:129], v[206:207]
	v_pk_add_f32 v[204:205], v[126:127], v[204:205]
	v_pk_add_f32 v[202:203], v[124:125], v[202:203]
	v_cvt_pk_bf16_f32 v124, v128, v129
	v_cvt_pk_bf16_f32 v125, v130, v131
	v_cvt_pk_bf16_f32 v126, v202, v203
	v_cvt_pk_bf16_f32 v127, v204, v205
	global_store_dwordx4 v[190:191], v[124:127], off
	s_nop 1
	v_mul_f32_e32 v124, v129, v129
	v_mul_f32_e32 v125, v131, v131
	v_fmac_f32_e32 v124, v128, v128
	v_fmac_f32_e32 v125, v130, v130
	v_add_f32_e32 v124, v124, v125
	v_mul_f32_e32 v125, v203, v203
	v_mul_f32_e32 v126, v205, v205
	v_fmac_f32_e32 v125, v202, v202
	v_fmac_f32_e32 v126, v204, v204
	v_add_f32_e32 v125, v125, v126
	v_add_f32_e32 v128, v124, v125
	v_lshlrev_b32_e32 v124, 16, v156
	v_and_b32_e32 v125, 0xffff0000, v156
	v_lshlrev_b32_e32 v126, 16, v157
	v_and_b32_e32 v127, 0xffff0000, v157
	v_pk_add_f32 v[122:123], v[122:123], v[126:127]
	v_pk_add_f32 v[120:121], v[120:121], v[124:125]
	v_lshlrev_b32_e32 v124, 16, v158
	v_and_b32_e32 v125, 0xffff0000, v158
	v_lshlrev_b32_e32 v126, 16, v159
	v_and_b32_e32 v127, 0xffff0000, v159
	v_pk_add_f32 v[126:127], v[118:119], v[126:127]
	v_pk_add_f32 v[124:125], v[116:117], v[124:125]
	v_cvt_pk_bf16_f32 v116, v120, v121
	v_cvt_pk_bf16_f32 v117, v122, v123
	v_cvt_pk_bf16_f32 v118, v124, v125
	v_cvt_pk_bf16_f32 v119, v126, v127
	global_store_dwordx4 v[190:191], v[116:119], off offset:256
	s_nop 1
	v_mul_f32_e32 v116, v121, v121
	v_mul_f32_e32 v117, v123, v123
	v_fmac_f32_e32 v116, v120, v120
	v_fmac_f32_e32 v117, v122, v122
	v_add_f32_e32 v116, v116, v117
	v_mul_f32_e32 v117, v125, v125
	v_mul_f32_e32 v118, v127, v127
	v_fmac_f32_e32 v117, v124, v124
	v_fmac_f32_e32 v118, v126, v126
	v_add_f32_e32 v117, v117, v118
	v_add_f32_e32 v116, v116, v117
	v_add_f32_e32 v116, v128, v116
	v_mov_b32_e32 v117, v116
	v_mov_b32_e32 v254, v116
	s_nop 1
	v_permlane16_swap_b32_e32 v117, v254
	s_nop 1
	v_mov_b32_dpp v117, v254 quad_perm:[0,1,2,3] row_mask:0x5 bank_mask:0xf
	s_waitcnt lgkmcnt(0)
	v_add_f32_e32 v116, v116, v117
	v_mov_b32_e32 v117, v116
	v_mov_b32_e32 v255, v116
	s_nop 1
	v_permlane32_swap_b32_e32 v117, v255
	s_nop 1
	v_mov_b32_dpp v117, v255 quad_perm:[0,1,2,3] row_mask:0x3 bank_mask:0xf
	s_and_saveexec_b64 s[20:21], s[2:3]
	s_cbranch_execz .LBB0_1772
	s_waitcnt lgkmcnt(0)
	v_add_f32_e32 v118, v116, v117
	s_lshl_b32 s22, s39, 2
	v_lshlrev_b64 v[116:117], 6, v[174:175]
	s_ashr_i32 s23, s22, 31
	v_lshl_add_u64 v[116:117], s[10:11], 0, v[116:117]
	v_lshl_add_u64 v[116:117], s[22:23], 2, v[116:117]
	s_lshl_b32 s62, s45, 2
	v_lshl_add_u64 v[116:117], v[116:117], 0, s[62:63]
	global_store_dword v[116:117], v118, off
; DI u32x4 pack8(f32x4 a, f32x4 b) { u32x4 w; w.x = pk2(a[0], a[1]); w.y = pk2(a[2], a[3]); w.z = pk2(b[0], b[1]); w.w = pk2(b[2], b[3]); return w; }
;     DI void operator()(const pg8::Acc& acc, const pg8::Unit& u, int wr, int wc, int fr, int fq) const {
;     ...
;                 for (int m = 0; m < 4; ++m) { const int row = row0 + ai * 128 + m * 16; float ssq = 0.f;
; #pragma unroll
;                     for (int bj = 0; bj < 2; ++bj) { const u32x4 x = xv[m][bj];
;                         const f32x4 xa = (f32x4){bflo(x.x), bfhi(x.x), bflo(x.y), bfhi(x.y)} + acc[ai][bj][m][0] * scale, xb = (f32x4){bflo(x.z), bfhi(x.z), bflo(x.w), bfhi(x.w)} + acc[ai][bj][m][1] * scale;
;                         *(u32x4*)(XH + (size_t)row * DM + col0 + bj * 128) = pack8(xa, xb);
;                         ssq += ((xa[0] * xa[0] + xa[1] * xa[1]) + (xa[2] * xa[2] + xa[3] * xa[3])) + ((xb[0] * xb[0] + xb[1] * xb[1]) + (xb[2] * xb[2] + xb[3] * xb[3])); }
;                     ssq += __shfl_xor(ssq, 16); ssq += __shfl_xor(ssq, 32);
;                     if (fq == 0) SSP[(size_t)row * 16 + u.pn * 4 + wc] = ssq; }
.LBB0_1772:
	s_or_b64 exec, exec, s[20:21]
	v_lshlrev_b32_e32 v116, 16, v152
	s_waitcnt lgkmcnt(0)
	v_and_b32_e32 v117, 0xffff0000, v152
	v_lshlrev_b32_e32 v118, 16, v153
	v_and_b32_e32 v119, 0xffff0000, v153
	v_pk_add_f32 v[114:115], v[114:115], v[118:119]
	v_pk_add_f32 v[112:113], v[112:113], v[116:117]
	v_lshlrev_b32_e32 v116, 16, v154
	v_and_b32_e32 v117, 0xffff0000, v154
	v_lshlrev_b32_e32 v118, 16, v155
	v_and_b32_e32 v119, 0xffff0000, v155
	v_pk_add_f32 v[118:119], v[110:111], v[118:119]
	v_pk_add_f32 v[110:111], v[108:109], v[116:117]
	v_cvt_pk_bf16_f32 v108, v112, v113
	v_mul_f32_e32 v113, v113, v113
	v_fmac_f32_e32 v113, v112, v112
	v_mul_f32_e32 v112, v115, v115
	v_fmac_f32_e32 v112, v114, v114
	v_cvt_pk_bf16_f32 v109, v114, v115
	v_add_f32_e32 v112, v113, v112
	v_mul_f32_e32 v113, v111, v111
	v_mul_f32_e32 v114, v119, v119
	v_fmac_f32_e32 v113, v110, v110
	v_fmac_f32_e32 v114, v118, v118
	v_add_f32_e32 v113, v113, v114
	v_add_f32_e32 v116, v112, v113
	v_lshlrev_b32_e32 v112, 16, v148
	v_and_b32_e32 v113, 0xffff0000, v148
	v_lshlrev_b32_e32 v114, 16, v149
	v_and_b32_e32 v115, 0xffff0000, v149
	v_pk_add_f32 v[106:107], v[106:107], v[114:115]
	v_pk_add_f32 v[104:105], v[104:105], v[112:113]
	v_lshlrev_b32_e32 v112, 16, v150
	v_and_b32_e32 v113, 0xffff0000, v150
	v_lshlrev_b32_e32 v114, 16, v151
	v_and_b32_e32 v115, 0xffff0000, v151
	v_pk_add_f32 v[112:113], v[100:101], v[112:113]
	v_mul_f32_e32 v100, v105, v105
	v_mul_f32_e32 v101, v107, v107
	v_pk_add_f32 v[114:115], v[102:103], v[114:115]
	v_fmac_f32_e32 v100, v104, v104
	v_fmac_f32_e32 v101, v106, v106
	v_add_f32_e32 v100, v100, v101
	v_mul_f32_e32 v101, v113, v113
	v_mul_f32_e32 v102, v115, v115
	v_fmac_f32_e32 v101, v112, v112
	v_fmac_f32_e32 v102, v114, v114
	v_add_f32_e32 v101, v101, v102
	v_add_f32_e32 v100, v100, v101
	v_add_f32_e32 v100, v116, v100
	v_mov_b32_e32 v101, v100
	v_mov_b32_e32 v254, v100
	s_nop 1
	v_permlane16_swap_b32_e32 v101, v254
	s_nop 1
	v_mov_b32_dpp v101, v254 quad_perm:[0,1,2,3] row_mask:0x5 bank_mask:0xf
	v_cvt_pk_bf16_f32 v110, v110, v111
	v_cvt_pk_bf16_f32 v111, v118, v119
	v_cvt_pk_bf16_f32 v102, v104, v105
	v_cvt_pk_bf16_f32 v103, v106, v107
	s_waitcnt lgkmcnt(0)
	v_add_f32_e32 v100, v100, v101
	v_mov_b32_e32 v101, v100
	v_mov_b32_e32 v255, v100
	s_nop 1
	v_permlane32_swap_b32_e32 v101, v255
	s_nop 1
	v_mov_b32_dpp v101, v255 quad_perm:[0,1,2,3] row_mask:0x3 bank_mask:0xf
	v_cvt_pk_bf16_f32 v104, v112, v113
	v_cvt_pk_bf16_f32 v105, v114, v115
	global_store_dwordx4 v[188:189], v[108:111], off
	global_store_dwordx4 v[188:189], v[102:105], off offset:256
	s_and_saveexec_b64 s[20:21], s[2:3]
	s_cbranch_execz .LBB0_1774
	s_waitcnt lgkmcnt(0)
	v_add_f32_e32 v102, v100, v101
	s_lshl_b32 s22, s39, 2
	v_lshlrev_b64 v[100:101], 6, v[186:187]
	s_ashr_i32 s23, s22, 31
	v_lshl_add_u64 v[100:101], s[10:11], 0, v[100:101]
	v_lshl_add_u64 v[100:101], s[22:23], 2, v[100:101]
	s_lshl_b32 s62, s45, 2
	v_lshl_add_u64 v[100:101], v[100:101], 0, s[62:63]
	global_store_dword v[100:101], v102, off
.LBB0_1774:
	s_or_b64 exec, exec, s[20:21]
	v_lshlrev_b32_e32 v100, 16, v144
	s_waitcnt lgkmcnt(0)
	v_and_b32_e32 v101, 0xffff0000, v144
	v_lshlrev_b32_e32 v102, 16, v145
	v_and_b32_e32 v103, 0xffff0000, v145
	v_pk_add_f32 v[98:99], v[98:99], v[102:103]
	v_pk_add_f32 v[96:97], v[96:97], v[100:101]
	v_lshlrev_b32_e32 v100, 16, v146
	v_and_b32_e32 v101, 0xffff0000, v146
	v_lshlrev_b32_e32 v102, 16, v147
	v_and_b32_e32 v103, 0xffff0000, v147
	v_pk_add_f32 v[102:103], v[94:95], v[102:103]
	v_pk_add_f32 v[94:95], v[92:93], v[100:101]
	v_cvt_pk_bf16_f32 v92, v96, v97
	v_mul_f32_e32 v97, v97, v97
	v_fmac_f32_e32 v97, v96, v96
	v_mul_f32_e32 v96, v99, v99
	v_fmac_f32_e32 v96, v98, v98
	v_cvt_pk_bf16_f32 v93, v98, v99
	v_add_f32_e32 v96, v97, v96
	v_mul_f32_e32 v97, v95, v95
	v_mul_f32_e32 v98, v103, v103
	v_fmac_f32_e32 v97, v94, v94
	v_fmac_f32_e32 v98, v102, v102
	v_add_f32_e32 v97, v97, v98
	v_add_f32_e32 v100, v96, v97
	v_lshlrev_b32_e32 v96, 16, v140
	v_and_b32_e32 v97, 0xffff0000, v140
	v_lshlrev_b32_e32 v98, 16, v141
	v_and_b32_e32 v99, 0xffff0000, v141
	v_pk_add_f32 v[90:91], v[90:91], v[98:99]
	v_pk_add_f32 v[88:89], v[88:89], v[96:97]
	v_lshlrev_b32_e32 v96, 16, v142
	v_and_b32_e32 v97, 0xffff0000, v142
	v_lshlrev_b32_e32 v98, 16, v143
	v_and_b32_e32 v99, 0xffff0000, v143
	v_pk_add_f32 v[96:97], v[84:85], v[96:97]
	v_mul_f32_e32 v84, v89, v89
	v_mul_f32_e32 v85, v91, v91
	v_pk_add_f32 v[98:99], v[86:87], v[98:99]
	v_fmac_f32_e32 v84, v88, v88
	v_fmac_f32_e32 v85, v90, v90
	v_add_f32_e32 v84, v84, v85
	v_mul_f32_e32 v85, v97, v97
	v_mul_f32_e32 v86, v99, v99
	v_fmac_f32_e32 v85, v96, v96
	v_fmac_f32_e32 v86, v98, v98
	v_add_f32_e32 v85, v85, v86
	v_add_f32_e32 v84, v84, v85
	v_add_f32_e32 v84, v100, v84
	v_mov_b32_e32 v85, v84
	v_mov_b32_e32 v254, v84
	s_nop 1
	v_permlane16_swap_b32_e32 v85, v254
	s_nop 1
	v_mov_b32_dpp v85, v254 quad_perm:[0,1,2,3] row_mask:0x5 bank_mask:0xf
	v_cvt_pk_bf16_f32 v94, v94, v95
	v_cvt_pk_bf16_f32 v95, v102, v103
	v_cvt_pk_bf16_f32 v86, v88, v89
	v_cvt_pk_bf16_f32 v87, v90, v91
	s_waitcnt lgkmcnt(0)
	v_add_f32_e32 v84, v84, v85
	v_mov_b32_e32 v85, v84
	v_mov_b32_e32 v255, v84
	s_nop 1
	v_permlane32_swap_b32_e32 v85, v255
	s_nop 1
	v_mov_b32_dpp v85, v255 quad_perm:[0,1,2,3] row_mask:0x3 bank_mask:0xf
	v_cvt_pk_bf16_f32 v88, v96, v97
	v_cvt_pk_bf16_f32 v89, v98, v99
	global_store_dwordx4 v[184:185], v[92:95], off
	global_store_dwordx4 v[184:185], v[86:89], off offset:256
	s_and_saveexec_b64 s[20:21], s[2:3]
	s_cbranch_execz .LBB0_1776
	s_waitcnt lgkmcnt(0)
	v_add_f32_e32 v86, v84, v85
	s_lshl_b32 s22, s39, 2
	v_lshlrev_b64 v[84:85], 6, v[182:183]
	s_ashr_i32 s23, s22, 31
	v_lshl_add_u64 v[84:85], s[10:11], 0, v[84:85]
	v_lshl_add_u64 v[84:85], s[22:23], 2, v[84:85]
	s_lshl_b32 s62, s45, 2
	v_lshl_add_u64 v[84:85], v[84:85], 0, s[62:63]
	global_store_dword v[84:85], v86, off
; DI u32x4 pack8(f32x4 a, f32x4 b) { u32x4 w; w.x = pk2(a[0], a[1]); w.y = pk2(a[2], a[3]); w.z = pk2(b[0], b[1]); w.w = pk2(b[2], b[3]); return w; }
;     DI void operator()(const pg8::Acc& acc, const pg8::Unit& u, int wr, int wc, int fr, int fq) const {
;     ...
;                 for (int m = 0; m < 4; ++m) { const int row = row0 + ai * 128 + m * 16; float ssq = 0.f;
; #pragma unroll
;                     for (int bj = 0; bj < 2; ++bj) { const u32x4 x = xv[m][bj];
;                         const f32x4 xa = (f32x4){bflo(x.x), bfhi(x.x), bflo(x.y), bfhi(x.y)} + acc[ai][bj][m][0] * scale, xb = (f32x4){bflo(x.z), bfhi(x.z), bflo(x.w), bfhi(x.w)} + acc[ai][bj][m][1] * scale;
;                         *(u32x4*)(XH + (size_t)row * DM + col0 + bj * 128) = pack8(xa, xb);
;                         ssq += ((xa[0] * xa[0] + xa[1] * xa[1]) + (xa[2] * xa[2] + xa[3] * xa[3])) + ((xb[0] * xb[0] + xb[1] * xb[1]) + (xb[2] * xb[2] + xb[3] * xb[3])); }
;                     ssq += __shfl_xor(ssq, 16); ssq += __shfl_xor(ssq, 32);
;                     if (fq == 0) SSP[(size_t)row * 16 + u.pn * 4 + wc] = ssq; }
.LBB0_1776:
	s_or_b64 exec, exec, s[20:21]
	v_lshlrev_b32_e32 v84, 16, v136
	s_waitcnt lgkmcnt(0)
	v_and_b32_e32 v85, 0xffff0000, v136
	v_lshlrev_b32_e32 v86, 16, v137
	v_and_b32_e32 v87, 0xffff0000, v137
	v_pk_add_f32 v[82:83], v[82:83], v[86:87]
	v_pk_add_f32 v[80:81], v[80:81], v[84:85]
	v_lshlrev_b32_e32 v84, 16, v138
	v_and_b32_e32 v85, 0xffff0000, v138
	v_lshlrev_b32_e32 v86, 16, v139
	v_and_b32_e32 v87, 0xffff0000, v139
	v_pk_add_f32 v[86:87], v[78:79], v[86:87]
	v_pk_add_f32 v[78:79], v[76:77], v[84:85]
	v_cvt_pk_bf16_f32 v76, v80, v81
	v_mul_f32_e32 v81, v81, v81
	v_fmac_f32_e32 v81, v80, v80
	v_mul_f32_e32 v80, v83, v83
	v_fmac_f32_e32 v80, v82, v82
	v_cvt_pk_bf16_f32 v77, v82, v83
	v_add_f32_e32 v80, v81, v80
	v_mul_f32_e32 v81, v79, v79
	v_mul_f32_e32 v82, v87, v87
	v_fmac_f32_e32 v81, v78, v78
	v_fmac_f32_e32 v82, v86, v86
	v_add_f32_e32 v81, v81, v82
	v_add_f32_e32 v84, v80, v81
	v_lshlrev_b32_e32 v80, 16, v132
	v_and_b32_e32 v81, 0xffff0000, v132
	v_lshlrev_b32_e32 v82, 16, v133
	v_and_b32_e32 v83, 0xffff0000, v133
	v_pk_add_f32 v[74:75], v[74:75], v[82:83]
	v_pk_add_f32 v[72:73], v[72:73], v[80:81]
	v_lshlrev_b32_e32 v80, 16, v134
	v_and_b32_e32 v81, 0xffff0000, v134
	v_lshlrev_b32_e32 v82, 16, v135
	v_and_b32_e32 v83, 0xffff0000, v135
	v_pk_add_f32 v[80:81], v[68:69], v[80:81]
	v_mul_f32_e32 v68, v73, v73
	v_mul_f32_e32 v69, v75, v75
	v_pk_add_f32 v[82:83], v[70:71], v[82:83]
	v_fmac_f32_e32 v68, v72, v72
	v_fmac_f32_e32 v69, v74, v74
	v_add_f32_e32 v68, v68, v69
	v_mul_f32_e32 v69, v81, v81
	v_mul_f32_e32 v70, v83, v83
	v_fmac_f32_e32 v69, v80, v80
	v_fmac_f32_e32 v70, v82, v82
	v_add_f32_e32 v69, v69, v70
	v_add_f32_e32 v68, v68, v69
	v_add_f32_e32 v68, v84, v68
	v_mov_b32_e32 v69, v68
	v_mov_b32_e32 v254, v68
	s_nop 1
	v_permlane16_swap_b32_e32 v69, v254
	s_nop 1
	v_mov_b32_dpp v69, v254 quad_perm:[0,1,2,3] row_mask:0x5 bank_mask:0xf
	v_cvt_pk_bf16_f32 v78, v78, v79
	v_cvt_pk_bf16_f32 v79, v86, v87
	v_cvt_pk_bf16_f32 v70, v72, v73
	v_cvt_pk_bf16_f32 v71, v74, v75
	s_waitcnt lgkmcnt(0)
	v_add_f32_e32 v68, v68, v69
	v_mov_b32_e32 v69, v68
	v_mov_b32_e32 v255, v68
	s_nop 1
	v_permlane32_swap_b32_e32 v69, v255
	s_nop 1
	v_mov_b32_dpp v69, v255 quad_perm:[0,1,2,3] row_mask:0x3 bank_mask:0xf
	v_cvt_pk_bf16_f32 v72, v80, v81
	v_cvt_pk_bf16_f32 v73, v82, v83
	global_store_dwordx4 v[180:181], v[76:79], off
	global_store_dwordx4 v[180:181], v[70:73], off offset:256
	s_and_saveexec_b64 s[20:21], s[2:3]
	s_cbranch_execz .LBB0_1778
	s_waitcnt lgkmcnt(0)
	v_add_f32_e32 v70, v68, v69
	s_lshl_b32 s22, s39, 2
	v_lshlrev_b64 v[68:69], 6, v[178:179]
	s_ashr_i32 s23, s22, 31
	v_lshl_add_u64 v[68:69], s[10:11], 0, v[68:69]
	v_lshl_add_u64 v[68:69], s[22:23], 2, v[68:69]
	s_lshl_b32 s62, s45, 2
	v_lshl_add_u64 v[68:69], v[68:69], 0, s[62:63]
	global_store_dword v[68:69], v70, off
.LBB0_1778:
	s_or_b64 exec, exec, s[20:21]
	v_add_u32_e32 v108, 0x80, v174
	v_ashrrev_i32_e32 v109, 31, v108
	s_waitcnt lgkmcnt(0)
	v_lshlrev_b64 v[68:69], 11, v[108:109]
	v_lshl_add_u64 v[110:111], v[176:177], 0, v[68:69]
	s_nop 1
	v_mov_b64_e32 v[112:113], v[208:209]
	v_mov_b64_e32 v[114:115], v[210:211]
	v_mov_b64_e32 v[92:93], v[212:213]
	v_mov_b64_e32 v[94:95], v[214:215]
	v_add_u32_e32 v104, 0x90, v174
	v_ashrrev_i32_e32 v105, 31, v104
	v_add_u32_e32 v100, 0xa0, v174
	v_lshlrev_b64 v[68:69], 11, v[104:105]
	v_ashrrev_i32_e32 v101, 31, v100
	v_add_u32_e32 v96, 0xb0, v174
	v_lshl_add_u64 v[106:107], v[176:177], 0, v[68:69]
	v_lshlrev_b64 v[68:69], 11, v[100:101]
	v_ashrrev_i32_e32 v97, 31, v96
	v_lshl_add_u64 v[102:103], v[176:177], 0, v[68:69]
	v_lshlrev_b64 v[68:69], 11, v[96:97]
	v_lshl_add_u64 v[98:99], v[176:177], 0, v[68:69]
	v_mov_b64_e32 v[88:89], v[216:217]
	v_mov_b64_e32 v[90:91], v[218:219]
	v_mov_b64_e32 v[84:85], v[220:221]
	v_mov_b64_e32 v[86:87], v[222:223]
	v_mov_b64_e32 v[80:81], v[224:225]
	v_mov_b64_e32 v[82:83], v[226:227]
	v_mov_b64_e32 v[76:77], v[228:229]
	v_mov_b64_e32 v[78:79], v[230:231]
	v_mov_b64_e32 v[72:73], v[232:233]
	v_mov_b64_e32 v[74:75], v[234:235]
	v_mov_b64_e32 v[68:69], v[236:237]
	v_mov_b64_e32 v[70:71], v[238:239]
	v_lshlrev_b32_e32 v116, 16, v112
	v_and_b32_e32 v117, 0xffff0000, v112
	v_lshlrev_b32_e32 v112, 16, v113
	v_and_b32_e32 v113, 0xffff0000, v113
	v_pk_add_f32 v[66:67], v[66:67], v[112:113]
	v_lshlrev_b32_e32 v112, 16, v114
	v_and_b32_e32 v113, 0xffff0000, v114
	v_lshlrev_b32_e32 v114, 16, v115
	v_and_b32_e32 v115, 0xffff0000, v115
	v_pk_add_f32 v[64:65], v[64:65], v[116:117]
	v_pk_add_f32 v[114:115], v[62:63], v[114:115]
	v_pk_add_f32 v[112:113], v[60:61], v[112:113]
	v_cvt_pk_bf16_f32 v60, v64, v65
	v_cvt_pk_bf16_f32 v61, v66, v67
	v_cvt_pk_bf16_f32 v62, v112, v113
	v_cvt_pk_bf16_f32 v63, v114, v115
	global_store_dwordx4 v[110:111], v[60:63], off
	s_nop 1
	v_mul_f32_e32 v60, v65, v65
	v_mul_f32_e32 v61, v67, v67
	v_fmac_f32_e32 v60, v64, v64
	v_fmac_f32_e32 v61, v66, v66
	v_add_f32_e32 v60, v60, v61
	v_mul_f32_e32 v61, v113, v113
	v_mul_f32_e32 v62, v115, v115
	v_fmac_f32_e32 v61, v112, v112
	v_fmac_f32_e32 v62, v114, v114
	v_add_f32_e32 v61, v61, v62
	v_add_f32_e32 v64, v60, v61
	v_lshlrev_b32_e32 v60, 16, v92
	v_and_b32_e32 v61, 0xffff0000, v92
	v_lshlrev_b32_e32 v62, 16, v93
	v_and_b32_e32 v63, 0xffff0000, v93
	v_pk_add_f32 v[58:59], v[58:59], v[62:63]
	v_pk_add_f32 v[56:57], v[56:57], v[60:61]
	v_lshlrev_b32_e32 v60, 16, v94
	v_and_b32_e32 v61, 0xffff0000, v94
	v_lshlrev_b32_e32 v62, 16, v95
	v_and_b32_e32 v63, 0xffff0000, v95
	v_pk_add_f32 v[62:63], v[54:55], v[62:63]
	v_pk_add_f32 v[60:61], v[52:53], v[60:61]
	v_cvt_pk_bf16_f32 v52, v56, v57
	v_cvt_pk_bf16_f32 v53, v58, v59
	v_cvt_pk_bf16_f32 v54, v60, v61
	v_cvt_pk_bf16_f32 v55, v62, v63
	global_store_dwordx4 v[110:111], v[52:55], off offset:256
	s_nop 1
	v_mul_f32_e32 v52, v57, v57
	v_mul_f32_e32 v53, v59, v59
	v_fmac_f32_e32 v52, v56, v56
	v_fmac_f32_e32 v53, v58, v58
	v_add_f32_e32 v52, v52, v53
	v_mul_f32_e32 v53, v61, v61
	v_mul_f32_e32 v54, v63, v63
	v_fmac_f32_e32 v53, v60, v60
	v_fmac_f32_e32 v54, v62, v62
	v_add_f32_e32 v53, v53, v54
	v_add_f32_e32 v52, v52, v53
	v_add_f32_e32 v52, v64, v52
	v_mov_b32_e32 v53, v52
	v_mov_b32_e32 v254, v52
	s_nop 1
	v_permlane16_swap_b32_e32 v53, v254
	s_nop 1
	v_mov_b32_dpp v53, v254 quad_perm:[0,1,2,3] row_mask:0x5 bank_mask:0xf
	s_waitcnt lgkmcnt(0)
	v_add_f32_e32 v52, v52, v53
	v_mov_b32_e32 v53, v52
	v_mov_b32_e32 v255, v52
	s_nop 1
	v_permlane32_swap_b32_e32 v53, v255
	s_nop 1
	v_mov_b32_dpp v53, v255 quad_perm:[0,1,2,3] row_mask:0x3 bank_mask:0xf
	s_and_saveexec_b64 s[20:21], s[2:3]
	s_cbranch_execz .LBB0_1780
	s_waitcnt lgkmcnt(0)
	v_add_f32_e32 v54, v52, v53
	s_lshl_b32 s22, s39, 2
	v_lshlrev_b64 v[52:53], 6, v[108:109]
	s_ashr_i32 s23, s22, 31
	v_lshl_add_u64 v[52:53], s[10:11], 0, v[52:53]
	v_lshl_add_u64 v[52:53], s[22:23], 2, v[52:53]
	s_lshl_b32 s62, s45, 2
	v_lshl_add_u64 v[52:53], v[52:53], 0, s[62:63]
	global_store_dword v[52:53], v54, off
; DI u32x4 pack8(f32x4 a, f32x4 b) { u32x4 w; w.x = pk2(a[0], a[1]); w.y = pk2(a[2], a[3]); w.z = pk2(b[0], b[1]); w.w = pk2(b[2], b[3]); return w; }
;     DI void operator()(const pg8::Acc& acc, const pg8::Unit& u, int wr, int wc, int fr, int fq) const {
;     ...
;                 for (int m = 0; m < 4; ++m) { const int row = row0 + ai * 128 + m * 16; float ssq = 0.f;
; #pragma unroll
;                     for (int bj = 0; bj < 2; ++bj) { const u32x4 x = xv[m][bj];
;                         const f32x4 xa = (f32x4){bflo(x.x), bfhi(x.x), bflo(x.y), bfhi(x.y)} + acc[ai][bj][m][0] * scale, xb = (f32x4){bflo(x.z), bfhi(x.z), bflo(x.w), bfhi(x.w)} + acc[ai][bj][m][1] * scale;
;                         *(u32x4*)(XH + (size_t)row * DM + col0 + bj * 128) = pack8(xa, xb);
;                         ssq += ((xa[0] * xa[0] + xa[1] * xa[1]) + (xa[2] * xa[2] + xa[3] * xa[3])) + ((xb[0] * xb[0] + xb[1] * xb[1]) + (xb[2] * xb[2] + xb[3] * xb[3])); }
;                     ssq += __shfl_xor(ssq, 16); ssq += __shfl_xor(ssq, 32);
;                     if (fq == 0) SSP[(size_t)row * 16 + u.pn * 4 + wc] = ssq; }
.LBB0_1780:
	s_or_b64 exec, exec, s[20:21]
	v_lshlrev_b32_e32 v52, 16, v88
	s_waitcnt lgkmcnt(0)
	v_and_b32_e32 v53, 0xffff0000, v88
	v_lshlrev_b32_e32 v54, 16, v89
	v_and_b32_e32 v55, 0xffff0000, v89
	v_pk_add_f32 v[50:51], v[50:51], v[54:55]
	v_pk_add_f32 v[48:49], v[48:49], v[52:53]
	v_lshlrev_b32_e32 v52, 16, v90
	v_and_b32_e32 v53, 0xffff0000, v90
	v_lshlrev_b32_e32 v54, 16, v91
	v_and_b32_e32 v55, 0xffff0000, v91
	v_pk_add_f32 v[54:55], v[46:47], v[54:55]
	v_pk_add_f32 v[46:47], v[44:45], v[52:53]
	v_cvt_pk_bf16_f32 v44, v48, v49
	v_mul_f32_e32 v49, v49, v49
	v_fmac_f32_e32 v49, v48, v48
	v_mul_f32_e32 v48, v51, v51
	v_fmac_f32_e32 v48, v50, v50
	v_cvt_pk_bf16_f32 v45, v50, v51
	v_add_f32_e32 v48, v49, v48
	v_mul_f32_e32 v49, v47, v47
	v_mul_f32_e32 v50, v55, v55
	v_fmac_f32_e32 v49, v46, v46
	v_fmac_f32_e32 v50, v54, v54
	v_add_f32_e32 v49, v49, v50
	v_add_f32_e32 v52, v48, v49
	v_lshlrev_b32_e32 v48, 16, v84
	v_and_b32_e32 v49, 0xffff0000, v84
	v_lshlrev_b32_e32 v50, 16, v85
	v_and_b32_e32 v51, 0xffff0000, v85
	v_pk_add_f32 v[42:43], v[42:43], v[50:51]
	v_pk_add_f32 v[40:41], v[40:41], v[48:49]
	v_lshlrev_b32_e32 v48, 16, v86
	v_and_b32_e32 v49, 0xffff0000, v86
	v_lshlrev_b32_e32 v50, 16, v87
	v_and_b32_e32 v51, 0xffff0000, v87
	v_pk_add_f32 v[48:49], v[36:37], v[48:49]
	v_mul_f32_e32 v36, v41, v41
	v_mul_f32_e32 v37, v43, v43
	v_pk_add_f32 v[50:51], v[38:39], v[50:51]
	v_fmac_f32_e32 v36, v40, v40
	v_fmac_f32_e32 v37, v42, v42
	v_add_f32_e32 v36, v36, v37
	v_mul_f32_e32 v37, v49, v49
	v_mul_f32_e32 v38, v51, v51
	v_fmac_f32_e32 v37, v48, v48
	v_fmac_f32_e32 v38, v50, v50
	v_add_f32_e32 v37, v37, v38
	v_add_f32_e32 v36, v36, v37
	v_add_f32_e32 v36, v52, v36
	v_mov_b32_e32 v37, v36
	v_mov_b32_e32 v254, v36
	s_nop 1
	v_permlane16_swap_b32_e32 v37, v254
	s_nop 1
	v_mov_b32_dpp v37, v254 quad_perm:[0,1,2,3] row_mask:0x5 bank_mask:0xf
	v_cvt_pk_bf16_f32 v46, v46, v47
	v_cvt_pk_bf16_f32 v47, v54, v55
	v_cvt_pk_bf16_f32 v38, v40, v41
	v_cvt_pk_bf16_f32 v39, v42, v43
	s_waitcnt lgkmcnt(0)
	v_add_f32_e32 v36, v36, v37
	v_mov_b32_e32 v37, v36
	v_mov_b32_e32 v255, v36
	s_nop 1
	v_permlane32_swap_b32_e32 v37, v255
	s_nop 1
	v_mov_b32_dpp v37, v255 quad_perm:[0,1,2,3] row_mask:0x3 bank_mask:0xf
	v_cvt_pk_bf16_f32 v40, v48, v49
	v_cvt_pk_bf16_f32 v41, v50, v51
	global_store_dwordx4 v[106:107], v[44:47], off
	global_store_dwordx4 v[106:107], v[38:41], off offset:256
	s_and_saveexec_b64 s[20:21], s[2:3]
	s_cbranch_execz .LBB0_1782
	s_waitcnt lgkmcnt(0)
	v_add_f32_e32 v38, v36, v37
	s_lshl_b32 s22, s39, 2
	v_lshlrev_b64 v[36:37], 6, v[104:105]
	s_ashr_i32 s23, s22, 31
	v_lshl_add_u64 v[36:37], s[10:11], 0, v[36:37]
	v_lshl_add_u64 v[36:37], s[22:23], 2, v[36:37]
	s_lshl_b32 s62, s45, 2
	v_lshl_add_u64 v[36:37], v[36:37], 0, s[62:63]
	global_store_dword v[36:37], v38, off
; DI u32x4 pack8(f32x4 a, f32x4 b) { u32x4 w; w.x = pk2(a[0], a[1]); w.y = pk2(a[2], a[3]); w.z = pk2(b[0], b[1]); w.w = pk2(b[2], b[3]); return w; }
;     DI void operator()(const pg8::Acc& acc, const pg8::Unit& u, int wr, int wc, int fr, int fq) const {
;     ...
;                 for (int m = 0; m < 4; ++m) { const int row = row0 + ai * 128 + m * 16; float ssq = 0.f;
; #pragma unroll
;                     for (int bj = 0; bj < 2; ++bj) { const u32x4 x = xv[m][bj];
;                         const f32x4 xa = (f32x4){bflo(x.x), bfhi(x.x), bflo(x.y), bfhi(x.y)} + acc[ai][bj][m][0] * scale, xb = (f32x4){bflo(x.z), bfhi(x.z), bflo(x.w), bfhi(x.w)} + acc[ai][bj][m][1] * scale;
;                         *(u32x4*)(XH + (size_t)row * DM + col0 + bj * 128) = pack8(xa, xb);
;                         ssq += ((xa[0] * xa[0] + xa[1] * xa[1]) + (xa[2] * xa[2] + xa[3] * xa[3])) + ((xb[0] * xb[0] + xb[1] * xb[1]) + (xb[2] * xb[2] + xb[3] * xb[3])); }
;                     ssq += __shfl_xor(ssq, 16); ssq += __shfl_xor(ssq, 32);
;                     if (fq == 0) SSP[(size_t)row * 16 + u.pn * 4 + wc] = ssq; }
.LBB0_1782:
	s_or_b64 exec, exec, s[20:21]
	v_lshlrev_b32_e32 v36, 16, v80
	s_waitcnt lgkmcnt(0)
	v_and_b32_e32 v37, 0xffff0000, v80
	v_lshlrev_b32_e32 v38, 16, v81
	v_and_b32_e32 v39, 0xffff0000, v81
	v_pk_add_f32 v[34:35], v[34:35], v[38:39]
	v_pk_add_f32 v[32:33], v[32:33], v[36:37]
	v_lshlrev_b32_e32 v36, 16, v82
	v_and_b32_e32 v37, 0xffff0000, v82
	v_lshlrev_b32_e32 v38, 16, v83
	v_and_b32_e32 v39, 0xffff0000, v83
	v_pk_add_f32 v[38:39], v[30:31], v[38:39]
	v_pk_add_f32 v[30:31], v[28:29], v[36:37]
	v_cvt_pk_bf16_f32 v28, v32, v33
	v_mul_f32_e32 v33, v33, v33
	v_fmac_f32_e32 v33, v32, v32
	v_mul_f32_e32 v32, v35, v35
	v_fmac_f32_e32 v32, v34, v34
	v_cvt_pk_bf16_f32 v29, v34, v35
	v_add_f32_e32 v32, v33, v32
	v_mul_f32_e32 v33, v31, v31
	v_mul_f32_e32 v34, v39, v39
	v_fmac_f32_e32 v33, v30, v30
	v_fmac_f32_e32 v34, v38, v38
	v_add_f32_e32 v33, v33, v34
	v_add_f32_e32 v36, v32, v33
	v_lshlrev_b32_e32 v32, 16, v76
	v_and_b32_e32 v33, 0xffff0000, v76
	v_lshlrev_b32_e32 v34, 16, v77
	v_and_b32_e32 v35, 0xffff0000, v77
	v_pk_add_f32 v[26:27], v[26:27], v[34:35]
	v_pk_add_f32 v[24:25], v[24:25], v[32:33]
	v_lshlrev_b32_e32 v32, 16, v78
	v_and_b32_e32 v33, 0xffff0000, v78
	v_lshlrev_b32_e32 v34, 16, v79
	v_and_b32_e32 v35, 0xffff0000, v79
	v_pk_add_f32 v[32:33], v[20:21], v[32:33]
	v_mul_f32_e32 v20, v25, v25
	v_mul_f32_e32 v21, v27, v27
	v_pk_add_f32 v[34:35], v[22:23], v[34:35]
	v_fmac_f32_e32 v20, v24, v24
	v_fmac_f32_e32 v21, v26, v26
	v_add_f32_e32 v20, v20, v21
	v_mul_f32_e32 v21, v33, v33
	v_mul_f32_e32 v22, v35, v35
	v_fmac_f32_e32 v21, v32, v32
	v_fmac_f32_e32 v22, v34, v34
	v_add_f32_e32 v21, v21, v22
	v_add_f32_e32 v20, v20, v21
	v_add_f32_e32 v20, v36, v20
	v_mov_b32_e32 v21, v20
	v_mov_b32_e32 v254, v20
	s_nop 1
	v_permlane16_swap_b32_e32 v21, v254
	s_nop 1
	v_mov_b32_dpp v21, v254 quad_perm:[0,1,2,3] row_mask:0x5 bank_mask:0xf
	v_cvt_pk_bf16_f32 v30, v30, v31
	v_cvt_pk_bf16_f32 v31, v38, v39
	v_cvt_pk_bf16_f32 v22, v24, v25
	v_cvt_pk_bf16_f32 v23, v26, v27
	s_waitcnt lgkmcnt(0)
	v_add_f32_e32 v20, v20, v21
	v_mov_b32_e32 v21, v20
	v_mov_b32_e32 v255, v20
	s_nop 1
	v_permlane32_swap_b32_e32 v21, v255
	s_nop 1
	v_mov_b32_dpp v21, v255 quad_perm:[0,1,2,3] row_mask:0x3 bank_mask:0xf
	v_cvt_pk_bf16_f32 v24, v32, v33
	v_cvt_pk_bf16_f32 v25, v34, v35
	global_store_dwordx4 v[102:103], v[28:31], off
	global_store_dwordx4 v[102:103], v[22:25], off offset:256
	s_and_saveexec_b64 s[20:21], s[2:3]
	s_cbranch_execz .LBB0_1784
	s_waitcnt lgkmcnt(0)
	v_add_f32_e32 v22, v20, v21
	s_lshl_b32 s22, s39, 2
	v_lshlrev_b64 v[20:21], 6, v[100:101]
	s_ashr_i32 s23, s22, 31
	v_lshl_add_u64 v[20:21], s[10:11], 0, v[20:21]
	v_lshl_add_u64 v[20:21], s[22:23], 2, v[20:21]
	s_lshl_b32 s62, s45, 2
	v_lshl_add_u64 v[20:21], v[20:21], 0, s[62:63]
	global_store_dword v[20:21], v22, off
.LBB0_1784:
	s_or_b64 exec, exec, s[20:21]
	v_lshlrev_b32_e32 v20, 16, v72
	s_waitcnt lgkmcnt(0)
	v_and_b32_e32 v21, 0xffff0000, v72
	v_lshlrev_b32_e32 v22, 16, v73
	v_and_b32_e32 v23, 0xffff0000, v73
	v_pk_add_f32 v[18:19], v[18:19], v[22:23]
	v_pk_add_f32 v[16:17], v[16:17], v[20:21]
	v_lshlrev_b32_e32 v20, 16, v74
	v_and_b32_e32 v21, 0xffff0000, v74
	v_lshlrev_b32_e32 v22, 16, v75
	v_and_b32_e32 v23, 0xffff0000, v75
	v_pk_add_f32 v[22:23], v[14:15], v[22:23]
	v_pk_add_f32 v[14:15], v[12:13], v[20:21]
	v_cvt_pk_bf16_f32 v12, v16, v17
	v_mul_f32_e32 v17, v17, v17
	v_fmac_f32_e32 v17, v16, v16
	v_mul_f32_e32 v16, v19, v19
	v_fmac_f32_e32 v16, v18, v18
	v_cvt_pk_bf16_f32 v13, v18, v19
	v_add_f32_e32 v16, v17, v16
	v_mul_f32_e32 v17, v15, v15
	v_mul_f32_e32 v18, v23, v23
	v_fmac_f32_e32 v17, v14, v14
	v_fmac_f32_e32 v18, v22, v22
	v_add_f32_e32 v17, v17, v18
	v_add_f32_e32 v20, v16, v17
	v_lshlrev_b32_e32 v16, 16, v68
	v_and_b32_e32 v17, 0xffff0000, v68
	v_lshlrev_b32_e32 v18, 16, v69
	v_and_b32_e32 v19, 0xffff0000, v69
	v_pk_add_f32 v[10:11], v[10:11], v[18:19]
	v_pk_add_f32 v[8:9], v[8:9], v[16:17]
	v_lshlrev_b32_e32 v16, 16, v70
	v_and_b32_e32 v17, 0xffff0000, v70
	v_lshlrev_b32_e32 v18, 16, v71
	v_and_b32_e32 v19, 0xffff0000, v71
	v_pk_add_f32 v[16:17], v[4:5], v[16:17]
	v_mul_f32_e32 v4, v9, v9
	v_mul_f32_e32 v5, v11, v11
	v_pk_add_f32 v[18:19], v[6:7], v[18:19]
	v_fmac_f32_e32 v4, v8, v8
	v_fmac_f32_e32 v5, v10, v10
	v_add_f32_e32 v4, v4, v5
	v_mul_f32_e32 v5, v17, v17
	v_mul_f32_e32 v6, v19, v19
	v_fmac_f32_e32 v5, v16, v16
	v_fmac_f32_e32 v6, v18, v18
	v_add_f32_e32 v5, v5, v6
	v_add_f32_e32 v4, v4, v5
	v_add_f32_e32 v4, v20, v4
	v_mov_b32_e32 v5, v4
	v_mov_b32_e32 v254, v4
	s_nop 1
	v_permlane16_swap_b32_e32 v5, v254
	s_nop 1
	v_mov_b32_dpp v5, v254 quad_perm:[0,1,2,3] row_mask:0x5 bank_mask:0xf
	v_cvt_pk_bf16_f32 v14, v14, v15
	v_cvt_pk_bf16_f32 v15, v22, v23
	v_cvt_pk_bf16_f32 v6, v8, v9
	v_cvt_pk_bf16_f32 v7, v10, v11
	s_waitcnt lgkmcnt(0)
	v_add_f32_e32 v4, v4, v5
	v_mov_b32_e32 v5, v4
	v_mov_b32_e32 v255, v4
	s_nop 1
	v_permlane32_swap_b32_e32 v5, v255
	s_nop 1
	v_mov_b32_dpp v5, v255 quad_perm:[0,1,2,3] row_mask:0x3 bank_mask:0xf
	v_cvt_pk_bf16_f32 v8, v16, v17
	v_cvt_pk_bf16_f32 v9, v18, v19
	global_store_dwordx4 v[98:99], v[12:15], off
	global_store_dwordx4 v[98:99], v[6:9], off offset:256
	s_and_saveexec_b64 s[20:21], s[2:3]
	s_cbranch_execz .LBB0_1786
	s_waitcnt lgkmcnt(0)
	v_add_f32_e32 v6, v4, v5
	s_lshl_b32 s22, s39, 2
	v_lshlrev_b64 v[4:5], 6, v[96:97]
	s_ashr_i32 s23, s22, 31
	v_lshl_add_u64 v[4:5], s[10:11], 0, v[4:5]
	v_lshl_add_u64 v[4:5], s[22:23], 2, v[4:5]
	s_lshl_b32 s62, s45, 2
	v_lshl_add_u64 v[4:5], v[4:5], 0, s[62:63]
	global_store_dword v[4:5], v6, off
